# plus: static s_setprio 1 for waves 4-7 during attention units (reset at unit end)
# baseline (speedup 1.0000x reference)
; #define LAS __attribute__((address_space(3)))
; __device__ __forceinline__ void att_unit(LAS unsigned char* lds, const bf16* P, const bf16* AKV, const bf16* IKC, bf16* ACAT, const float* aqg, const float* ssq_ak, const float* ssq_ik, int b, int qg, int tid) {
;     ...
;     const int lane = tid & 63, w = __builtin_amdgcn_readfirstlane(tid >> 6), fr = lane & 15, fq = lane >> 4;
;     LAS unsigned char* IK = lds;
;     LAS unsigned char* Vst = lds + w * 9216;
;     LAS int* list0 = (LAS int*)(lds + 73728 + w * 6144);
;     const int L = 64 * ((qg >> 2) + 1);
;     const bf16* AKVb = AKV + (size_t)(b * SEQ) * 256;
;     const bf16* IKb = IKC + (size_t)(b * SEQ) * 128;
;     const GAS f32x4* sak = (const GAS f32x4*)ssq_ak + b * SEQ;
;     const size_t tok0 = (size_t)(b * SEQ + 16 * qg + 2 * w);
;     int cnt;
;     if (L <= 256) {
;         cnt = L;
; #pragma unroll
;         for (int r = 0; r < 4; ++r) { const int i = 64 * r + lane; const int kx = i < L ? i : 0; const f32x4 q4 = sak[kx]; const float rk = rsqrtf(((q4.x + q4.y) + (q4.z + q4.w)) * (1.f / 128.f) + EPS);
;             list0[i] = kx; ((LAS float*)list0)[256 + i] = rk; list0[512 + i] = kx; ((LAS float*)list0)[768 + i] = rk;
;             const int tp = ((i >> 5) * 4 + (i & 3)) * 8 + ((i >> 2) & 7); ((LAS unsigned*)list0)[1024 + tp] = (unsigned)kx * 512u; ((LAS unsigned*)list0)[1280 + tp] = (unsigned)kx * 512u; }
;     } else {
;         cnt = 256;
;         typedef float f32x2 __attribute__((ext_vector_type(2)));
;         const GAS f32x2* sik = (const GAS f32x2*)ssq_ik + b * SEQ;
;         bf16x8 Qi[2][2]; float wv[2][4];
; #pragma unroll
;         for (int q = 0; q < 2; ++q) {
; #pragma unroll
;             for (int kk = 0; kk < 2; ++kk) Qi[q][kk] = *(const GAS bf16x8*)(P + (tok0 + q) * NP + C_IQ + fr * 64 + 32 * kk + 8 * fq);
;             const u32x2 ww = *(const GAS u32x2*)(IKC + (tok0 + q) * 128 + 64 + 4 * fq); wv[q][0] = bflo(ww.x); wv[q][1] = bfhi(ww.x); wv[q][2] = bflo(ww.y); wv[q][3] = bfhi(ww.y);
;         }
;         unsigned uk[2][32];
;         const int ntile = (L + 255) >> 8;
;         const int skey = tid >> 3, spart = tid & 7;
;         const bf16* sb = IKb + (size_t)skey * 128 + spart * 8;
;         u32x4 ikr[4]; f32x2 rik[4];
; #pragma unroll
;         for (int i = 0; i < 4; ++i) { ikr[i] = *(const GAS u32x4*)(sb + (size_t)(64 * i) * 128); rik[i] = sik[64 * i + lane]; }
; #pragma unroll
.LBB0_593:
	v_readlane_b32 s0, v254, 13
	v_readlane_b32 s70, v254, 19
	v_readlane_b32 s2, v254, 9
	v_readlane_b32 s76, v254, 11
	v_readlane_b32 s8, v254, 5
	v_readlane_b32 s6, v254, 7
	v_readlane_b32 s4, v254, 3
	v_readlane_b32 s1, v254, 14
	v_readlane_b32 s71, v254, 20
	v_readlane_b32 s3, v254, 10
	v_readlane_b32 s77, v254, 12
	s_waitcnt vmcnt(0)
	v_mov_b32_e32 v18, v220
	v_readlane_b32 s9, v254, 6
	v_readlane_b32 s7, v254, 8
	v_readlane_b32 s5, v254, 4
	s_mov_b32 s11, 0x8c00
	v_writelane_b32 v254, s8, 43
	v_mov_b64_e32 v[154:155], s[4:5]
	v_readfirstlane_b32 s4, v18
	s_ashr_i32 s74, s4, 6
	s_cmp_lt_u32 s74, 4
	s_cbranch_scc1 .Latt_prio_skip
	s_setprio 1
.Latt_prio_skip:
	v_writelane_b32 v254, s9, 44
	s_mul_i32 s4, s74, 0x1800
	s_lshl_b32 s5, s26, 4
	s_add_i32 s33, s4, 0
	s_and_b32 s4, s5, 0xffffffc0
	v_readlane_b32 s9, v254, 38
	s_add_i32 s33, s33, 0x12000
	s_add_i32 s81, s4, 64
	s_lshl_b32 s8, s9, 4
	s_add_u32 s72, s6, s8
	s_addc_u32 s73, s7, 0
	s_lshl_b32 s6, s74, 1
	s_add_i32 s6, s6, s9
	s_add_i32 s5, s6, s5
	s_ashr_i32 s6, s5, 31
	v_and_b32_e32 v124, 63, v18
	v_and_b32_e32 v125, 15, v18
	v_bfe_u32 v126, v18, 4, 2
	v_writelane_b32 v254, s5, 45
	s_cmpk_gt_i32 s81, 0x100
	s_movk_i32 s10, 0x4000
	v_mov_b32_e32 v6, s81
	v_mov_b32_e32 v156, s5
	v_writelane_b32 v254, s6, 46
	v_mov_b32_e32 v157, s6
	s_cselect_b64 s[6:7], -1, 0
	v_lshlrev_b32_e32 v50, 7, v125
	v_lshlrev_b32_e32 v52, 3, v124
	v_lshlrev_b32_e32 v2, 3, v126
	v_and_b32_e32 v51, 48, v18
	s_and_saveexec_b64 s[8:9], s[6:7]
	s_xor_b64 s[82:83], exec, s[8:9]
	s_cbranch_execz .LBB0_1007
	v_mov_b64_e32 v[20:21], s[2:3]
	v_readlane_b32 s2, v254, 41
	v_mov_b64_e32 v[2:3], s[0:1]
	v_readlane_b32 s3, v254, 42
	v_mov_b32_e32 v51, v1
	v_lshlrev_b32_e32 v4, 4, v126
	v_lshl_add_u64 v[22:23], v[2:3], 0, s[2:3]
	v_readlane_b32 s2, v254, 45
	v_mov_b32_e32 v5, v1
	v_lshlrev_b64 v[24:25], 8, v[156:157]
	v_mov_b32_e32 v2, s2
	v_mad_i64_i32 v[2:3], s[2:3], v2, s11, v[154:155]
	v_lshl_add_u64 v[2:3], v[2:3], 0, v[50:51]
	v_lshl_add_u64 v[2:3], v[2:3], 0, v[4:5]
	s_mov_b64 s[2:3], 0x6200
	v_add_co_u32_e32 v6, vcc, 0x6000, v2
	v_lshl_add_u64 v[4:5], v[2:3], 0, s[2:3]
	s_nop 0
	v_addc_co_u32_e32 v7, vcc, 0, v3, vcc
	global_load_dwordx4 v[14:17], v[6:7], off offset:512
	global_load_dwordx4 v[10:13], v[4:5], off offset:64
	v_lshl_add_u64 v[4:5], s[0:1], 0, v[24:25]
	v_or_b32_e32 v24, 0x100, v24
	s_mov_b64 s[2:3], 0xee00
	v_lshl_add_u64 v[24:25], s[0:1], 0, v[24:25]
	v_readlane_b32 s0, v253, 34
	v_lshlrev_b32_e32 v0, 3, v126
	v_lshl_add_u64 v[6:7], v[2:3], 0, s[2:3]
	v_add_co_u32_e32 v2, vcc, 0xe000, v2
	v_readlane_b32 s1, v253, 35
	v_readlane_b32 s0, v254, 38
	v_ashrrev_i32_e32 v32, 3, v18
	v_lshl_add_u64 v[4:5], v[4:5], 0, v[0:1]
	v_addc_co_u32_e32 v3, vcc, 0, v3, vcc
	v_lshl_add_u64 v[24:25], v[24:25], 0, v[0:1]
	s_mov_b32 s3, s1
	s_lshl_b32 s2, s0, 3
	v_ashrrev_i32_e32 v33, 31, v32
	global_load_dwordx2 v[40:41], v[4:5], off offset:128
	s_nop 0
	global_load_dwordx4 v[2:5], v[2:3], off offset:3584
	s_nop 0
	global_load_dwordx4 v[6:9], v[6:7], off offset:64
	v_lshlrev_b32_e32 v19, 4, v18
	global_load_dwordx2 v[38:39], v[24:25], off offset:128
	v_lshl_add_u64 v[24:25], v[20:21], 0, s[2:3]
	v_lshlrev_b64 v[20:21], 8, v[32:33]
	v_lshl_add_u64 v[20:21], v[22:23], 0, v[20:21]
	v_and_b32_e32 v54, 0x70, v19
	v_mov_b32_e32 v55, v1
	v_lshl_add_u64 v[66:67], v[20:21], 0, v[54:55]
	v_mov_b32_e32 v53, v1
	v_writelane_b32 v253, s0, 34
	v_lshl_add_u64 v[88:89], v[24:25], 0, v[52:53]
	v_add_co_u32_e32 v24, vcc, s10, v66
	v_writelane_b32 v253, s1, 35
	s_nop 0
	v_addc_co_u32_e32 v25, vcc, 0, v67, vcc
	s_mov_b32 s0, 0x8000
	v_add_co_u32_e32 v28, vcc, s0, v66
	s_mov_b32 s0, 0xc000
	s_nop 0
	v_addc_co_u32_e32 v29, vcc, 0, v67, vcc
	v_add_co_u32_e32 v36, vcc, s0, v66
	global_load_dwordx4 v[20:23], v[66:67], off
	s_nop 0
	v_addc_co_u32_e32 v37, vcc, 0, v67, vcc
	global_load_dwordx2 v[42:43], v[88:89], off
	s_nop 0
	global_load_dwordx4 v[24:27], v[24:25], off
	s_nop 0
	global_load_dwordx2 v[44:45], v[88:89], off offset:512
	s_nop 0
	global_load_dwordx4 v[28:31], v[28:29], off
	s_nop 0
	global_load_dwordx2 v[34:35], v[88:89], off offset:1024
	global_load_dwordx4 v[46:49], v[36:37], off
	s_nop 0
	global_load_dwordx2 v[36:37], v[88:89], off offset:1536
	s_movk_i32 s0, 0x90
	v_mul_lo_u32 v32, v32, s0
	v_and_b32_e32 v51, 48, v18
	v_and_b32_e32 v18, 16, v18
	s_mov_b32 s0, 0x10000
	v_add_u32_e32 v19, 0, v54
	v_cmp_eq_u32_e64 s[6:7], 0, v18
	v_add_co_u32_e32 v18, vcc, s0, v66
	v_add_u32_e32 v129, v19, v32
	s_nop 0
	v_addc_co_u32_e32 v19, vcc, 0, v67, vcc
	s_mov_b32 s0, 0x14000
	s_mov_b32 s2, 0x3c800000
	v_mov_b32_e32 v132, s4
	s_mov_b32 s18, 0x800000
	s_waitcnt vmcnt(7)
	ds_write_b128 v129, v[20:23]
	s_waitcnt vmcnt(5)
	ds_write_b128 v129, v[24:27] offset:9216
	s_waitcnt vmcnt(3)
	ds_write_b128 v129, v[28:31] offset:18432
	s_waitcnt vmcnt(1)
	ds_write_b128 v129, v[46:49] offset:27648
	v_add_co_u32_e32 v22, vcc, s0, v66
	s_mov_b32 s0, 0x18000
	s_nop 0
	v_addc_co_u32_e32 v23, vcc, 0, v67, vcc
	v_add_co_u32_e32 v26, vcc, s0, v66
	s_mov_b32 s0, 0x1c000
	s_nop 0
	v_addc_co_u32_e32 v27, vcc, 0, v67, vcc
	v_add_co_u32_e32 v30, vcc, s0, v66
	v_mul_u32_u24_e32 v48, 0x90, v125
	s_nop 0
	v_addc_co_u32_e32 v31, vcc, 0, v67, vcc
	v_add3_u32 v131, 0, v51, v48
	s_waitcnt lgkmcnt(0)
	s_barrier
; #define LAS __attribute__((address_space(3)))
; #define GAS __attribute__((address_space(1)))
; __device__ __forceinline__ f32x4 mfma16(bf16x8 a, bf16x8 b, f32x4 c) { return __builtin_amdgcn_mfma_f32_16x16x32_bf16(a, b, c, 0, 0, 0); }
; __device__ __forceinline__ void att_unit(LAS unsigned char* lds, const bf16* P, const bf16* AKV, const bf16* IKC, bf16* ACAT, const float* aqg, const float* ssq_ak, const float* ssq_ik, int b, int qg, int tid) {
;     ...
;         for (int tile = 0; tile < 8; ++tile) {
;             if (tile < ntile) {
;                 LAS unsigned char* IKc = IK + (tile & 1) * 36864;
;                 f32x2 rc[4];
; #pragma unroll
;                 for (int i = 0; i < 4; ++i) rc[i] = rik[i];
;                 if (tile + 1 < ntile) {
; #pragma unroll
;                     for (int i = 0; i < 4; ++i) { ikr[i] = *(const GAS u32x4*)(sb + (size_t)(256 * (tile + 1) + 64 * i) * 128); rik[i] = sik[256 * (tile + 1) + 64 * i + lane]; }
;                 }
; #pragma unroll
;                 for (int r4 = 0; r4 < 4; ++r4) {
;                     float pt[2][4];
; #pragma unroll
;                     for (int q4 = 0; q4 < 4; ++q4) {
;                         const LAS unsigned char* kp = IKc + (64 * r4 + 16 * q4 + fr) * 144 + fq * 16;
;                         const bf16x8 K0 = *(const LAS bf16x8*)kp, K1 = *(const LAS bf16x8*)(kp + 64);
; #pragma unroll
;                         for (int q = 0; q < 2; ++q) {
;                             f32x4 a = (f32x4){0.f, 0.f, 0.f, 0.f};
;                             a = mfma16(Qi[q][0], K0, a); a = mfma16(Qi[q][1], K1, a);
;                             pt[q][q4] = fmaxf(a[0], 0.f) * wv[q][0] + fmaxf(a[1], 0.f) * wv[q][1] + fmaxf(a[2], 0.f) * wv[q][2] + fmaxf(a[3], 0.f) * wv[q][3];
;                         }
;                     }
	global_load_dwordx4 v[18:21], v[18:19], off
	s_nop 0
	global_load_dwordx2 v[46:47], v[88:89], off offset:2048
	s_nop 0
	global_load_dwordx4 v[22:25], v[22:23], off
	s_nop 0
	global_load_dwordx2 v[104:105], v[88:89], off offset:2560
	s_nop 0
	global_load_dwordx4 v[26:29], v[26:27], off
	s_nop 0
	global_load_dwordx2 v[100:101], v[88:89], off offset:3072
	s_nop 0
	global_load_dwordx4 v[30:33], v[30:31], off
	s_nop 0
	global_load_dwordx2 v[94:95], v[88:89], off offset:3584
	ds_read_b128 v[54:57], v131
	ds_read_b128 v[60:63], v131 offset:64
	s_waitcnt lgkmcnt(1)
	v_mfma_f32_16x16x32_bf16 v[68:71], v[14:17], v[54:57], 0
	s_mov_b32 s0, 0x358637bd
	v_mfma_f32_16x16x32_bf16 v[54:57], v[2:5], v[54:57], 0
	s_waitcnt lgkmcnt(0)
	v_mfma_f32_16x16x32_bf16 v[68:71], v[10:13], v[60:63], v[68:71]
	v_mfma_f32_16x16x32_bf16 v[54:57], v[6:9], v[60:63], v[54:57]
	ds_read_b128 v[60:63], v131 offset:2304
	ds_read_b128 v[72:75], v131 offset:2368
	s_nop 4
	v_max_f32_e32 v64, 0, v68
	v_max_f32_e32 v65, 0, v69
	v_max_f32_e32 v59, 0, v70
	v_max_f32_e32 v58, 0, v71
	s_waitcnt lgkmcnt(1)
	v_mfma_f32_16x16x32_bf16 v[68:71], v[14:17], v[60:63], 0
	v_max_f32_e32 v54, 0, v54
	s_waitcnt lgkmcnt(0)
	v_mfma_f32_16x16x32_bf16 v[76:79], v[10:13], v[72:75], v[68:71]
	v_max_f32_e32 v55, 0, v55
	v_mfma_f32_16x16x32_bf16 v[60:63], v[2:5], v[60:63], 0
	v_max_f32_e32 v49, 0, v56
	s_nop 2
	s_nop 1
	v_max_f32_e32 v70, 0, v76
	v_max_f32_e32 v71, 0, v77
	v_max_f32_e32 v69, 0, v78
	v_max_f32_e32 v68, 0, v79
	ds_read_b128 v[78:81], v131 offset:4608
	ds_read_b128 v[82:85], v131 offset:4672
	v_mfma_f32_16x16x32_bf16 v[60:63], v[6:9], v[72:75], v[60:63]
	v_max_f32_e32 v48, 0, v57
	s_waitcnt lgkmcnt(1)
	v_mfma_f32_16x16x32_bf16 v[72:75], v[14:17], v[78:81], 0
	s_waitcnt lgkmcnt(0)
	v_mfma_f32_16x16x32_bf16 v[72:75], v[10:13], v[82:85], v[72:75]
	s_nop 0
	s_nop 1
	v_max_f32_e32 v60, 0, v60
	v_mfma_f32_16x16x32_bf16 v[78:81], v[2:5], v[78:81], 0
	v_max_f32_e32 v61, 0, v61
	v_max_f32_e32 v57, 0, v62
	v_max_f32_e32 v56, 0, v63
	v_mfma_f32_16x16x32_bf16 v[80:83], v[6:9], v[82:85], v[78:81]
	v_max_f32_e32 v76, 0, v72
	v_max_f32_e32 v77, 0, v73
	v_max_f32_e32 v73, 0, v74
	v_max_f32_e32 v72, 0, v75
	s_nop 0
	s_nop 2
	v_max_f32_e32 v80, 0, v80
	v_max_f32_e32 v81, 0, v81
	v_max_f32_e32 v63, 0, v82
	v_max_f32_e32 v62, 0, v83
	ds_read_b128 v[82:85], v131 offset:6912
	ds_read_b128 v[96:99], v131 offset:6976
	s_waitcnt lgkmcnt(1)
	v_mfma_f32_16x16x32_bf16 v[90:93], v[14:17], v[82:85], 0
	v_mov_b32_e32 v75, v42
	v_mov_b32_e32 v42, v45
	s_waitcnt lgkmcnt(0)
	v_mfma_f32_16x16x32_bf16 v[90:93], v[10:13], v[96:99], v[90:93]
	v_mfma_f32_16x16x32_bf16 v[82:85], v[2:5], v[82:85], 0
	v_mfma_f32_16x16x32_bf16 v[84:87], v[6:9], v[96:99], v[82:85]
	s_nop 5
	v_max_f32_e32 v78, 0, v90
	ds_read_b128 v[96:99], v131 offset:9216
	ds_read_b128 v[106:109], v131 offset:9280
	v_max_f32_e32 v79, 0, v91
	v_max_f32_e32 v91, 0, v92
	v_max_f32_e32 v90, 0, v93
	v_max_f32_e32 v84, 0, v84
	s_waitcnt lgkmcnt(1)
	v_mfma_f32_16x16x32_bf16 v[110:113], v[14:17], v[96:99], 0
	v_max_f32_e32 v85, 0, v85
	v_max_f32_e32 v83, 0, v86
	v_mfma_f32_16x16x32_bf16 v[96:99], v[2:5], v[96:99], 0
	v_max_f32_e32 v82, 0, v87
	v_mbcnt_hi_u32_b32 v53, -1, v221
	v_and_b32_e32 v74, 64, v53
	s_waitcnt lgkmcnt(0)
	v_mfma_f32_16x16x32_bf16 v[110:113], v[10:13], v[106:109], v[110:113]
	v_xor_b32_e32 v127, 16, v53
	v_add_u32_e32 v128, 64, v74
	v_cmp_lt_i32_e32 vcc, v127, v128
	v_mfma_f32_16x16x32_bf16 v[96:99], v[6:9], v[106:109], v[96:99]
	ds_read_b128 v[106:109], v131 offset:11520
	ds_read_b128 v[114:117], v131 offset:11584
	v_cndmask_b32_e32 v74, v53, v127, vcc
	v_lshlrev_b32_e32 v130, 2, v74
	s_waitcnt lgkmcnt(1)
	v_mfma_f32_16x16x32_bf16 v[118:121], v[14:17], v[106:109], 0
	v_max_f32_e32 v110, 0, v110
	v_max_f32_e32 v111, 0, v111
	v_max_f32_e32 v103, 0, v112
	v_mfma_f32_16x16x32_bf16 v[106:109], v[2:5], v[106:109], 0
	v_max_f32_e32 v102, 0, v113
	v_max_f32_e32 v96, 0, v96
	s_waitcnt lgkmcnt(0)
	v_mfma_f32_16x16x32_bf16 v[118:121], v[10:13], v[114:117], v[118:121]
	v_max_f32_e32 v97, 0, v97
	v_max_f32_e32 v87, 0, v98
	v_mfma_f32_16x16x32_bf16 v[106:109], v[6:9], v[114:117], v[106:109]
	ds_read_b128 v[114:117], v131 offset:13824
	ds_read_b128 v[134:137], v131 offset:13888
	v_max_f32_e32 v86, 0, v99
	s_nop 1
	v_max_f32_e32 v118, 0, v118
	v_max_f32_e32 v119, 0, v119
	v_max_f32_e32 v113, 0, v120
	v_max_f32_e32 v112, 0, v121
	s_waitcnt lgkmcnt(1)
	v_mfma_f32_16x16x32_bf16 v[120:123], v[14:17], v[114:117], 0
	v_max_f32_e32 v106, 0, v106
	v_mfma_f32_16x16x32_bf16 v[114:117], v[2:5], v[114:117], 0
	v_max_f32_e32 v107, 0, v107
	s_waitcnt lgkmcnt(0)
	v_mfma_f32_16x16x32_bf16 v[120:123], v[10:13], v[134:137], v[120:123]
	v_max_f32_e32 v99, 0, v108
	v_max_f32_e32 v98, 0, v109
	v_mfma_f32_16x16x32_bf16 v[114:117], v[6:9], v[134:137], v[114:117]
	ds_read_b128 v[134:137], v131 offset:16128
	ds_read_b128 v[138:141], v131 offset:16192
	s_nop 1
	s_nop 0
	v_max_f32_e32 v146, 0, v120
	s_waitcnt lgkmcnt(1)
	v_mfma_f32_16x16x32_bf16 v[142:145], v[14:17], v[134:137], 0
	v_max_f32_e32 v147, 0, v121
	v_max_f32_e32 v121, 0, v122
	v_max_f32_e32 v120, 0, v123
	s_waitcnt lgkmcnt(0)
	v_mfma_f32_16x16x32_bf16 v[142:145], v[10:13], v[138:141], v[142:145]
	v_max_f32_e32 v114, 0, v114
	v_max_f32_e32 v115, 0, v115
	v_mfma_f32_16x16x32_bf16 v[134:137], v[2:5], v[134:137], 0
	v_max_f32_e32 v109, 0, v116
	v_max_f32_e32 v108, 0, v117
	v_mfma_f32_16x16x32_bf16 v[134:137], v[6:9], v[138:141], v[134:137]
	s_nop 1
	v_max_f32_e32 v148, 0, v142
	v_max_f32_e32 v149, 0, v143
	v_max_f32_e32 v151, 0, v144
	v_max_f32_e32 v150, 0, v145
	s_nop 0
	s_nop 0
	v_max_f32_e32 v122, 0, v134
	v_max_f32_e32 v123, 0, v135
	v_max_f32_e32 v117, 0, v136
	v_max_f32_e32 v116, 0, v137
	ds_read_b128 v[134:137], v131 offset:18432
	ds_read_b128 v[138:141], v131 offset:18496
	s_waitcnt lgkmcnt(1)
; #define LAS __attribute__((address_space(3)))
; __device__ __forceinline__ f32x4 mfma16(bf16x8 a, bf16x8 b, f32x4 c) { return __builtin_amdgcn_mfma_f32_16x16x32_bf16(a, b, c, 0, 0, 0); }
; __device__ __forceinline__ void att_unit(LAS unsigned char* lds, const bf16* P, const bf16* AKV, const bf16* IKC, bf16* ACAT, const float* aqg, const float* ssq_ak, const float* ssq_ik, int b, int qg, int tid) {
;     ...
;                     for (int q4 = 0; q4 < 4; ++q4) {
;                         const LAS unsigned char* kp = IKc + (64 * r4 + 16 * q4 + fr) * 144 + fq * 16;
;                         const bf16x8 K0 = *(const LAS bf16x8*)kp, K1 = *(const LAS bf16x8*)(kp + 64);
; #pragma unroll
;                         for (int q = 0; q < 2; ++q) {
;                             f32x4 a = (f32x4){0.f, 0.f, 0.f, 0.f};
;                             a = mfma16(Qi[q][0], K0, a); a = mfma16(Qi[q][1], K1, a);
;                             pt[q][q4] = fmaxf(a[0], 0.f) * wv[q][0] + fmaxf(a[1], 0.f) * wv[q][1] + fmaxf(a[2], 0.f) * wv[q][2] + fmaxf(a[3], 0.f) * wv[q][3];
;                         }
;                     }
;                     const int rr = 4 * tile + r4;
;                     const float rscale = rsqrtf((rc[r4].x + rc[r4].y) * (1.f / 64.f) + EPS);
;                     const bool live = 64 * rr + lane < L;
; #pragma unroll
;                     for (int q = 0; q < 2; ++q) {
;                         float hx; const float A = half_sum32(pt[q][0], pt[q][2], hx), B = half_sum32(pt[q][1], pt[q][3], hx);
;                         const bool odd = fq & 1;
;                         const float send = odd ? A : B, keep = odd ? B : A;
;                         const float sc = live ? (keep + __shfl_xor(send, 16)) * rscale : -INFINITY;
;                         const unsigned bts = __float_as_uint(sc);
;                         uk[q][rr] = bts ^ ((unsigned)((int)bts >> 31) | 0x80000000u);
	v_mfma_f32_16x16x32_bf16 v[142:145], v[14:17], v[134:137], 0
	v_mov_b32_e32 v74, v44
	v_pk_add_f32 v[44:45], v[74:75], v[42:43]
	v_and_b32_e32 v75, 0xffff0000, v40
	s_waitcnt lgkmcnt(0)
	v_mfma_f32_16x16x32_bf16 v[142:145], v[10:13], v[138:141], v[142:145]
	v_lshlrev_b32_e32 v74, 16, v40
	v_mul_f32_e32 v40, v65, v75
	v_pk_fma_f32 v[64:65], v[64:65], v[74:75], v[40:41] op_sel_hi:[1,1,0]
	v_mul_f32_e32 v40, v71, v75
	v_pk_fma_f32 v[70:71], v[70:71], v[74:75], v[40:41] op_sel_hi:[1,1,0]
	v_mul_f32_e32 v40, v77, v75
	v_mov_b64_e32 v[42:43], s[0:1]
	v_pk_fma_f32 v[76:77], v[76:77], v[74:75], v[40:41] op_sel_hi:[1,1,0]
	v_mul_f32_e32 v40, v79, v75
	v_pk_fma_f32 v[92:93], v[44:45], s[2:3], v[42:43] op_sel_hi:[1,0,0]
	v_max_f32_e32 v44, 0, v142
	v_max_f32_e32 v45, 0, v143
	v_pk_fma_f32 v[142:143], v[78:79], v[74:75], v[40:41] op_sel_hi:[1,1,0]
	v_mul_f32_e32 v40, v111, v75
	v_pk_fma_f32 v[110:111], v[110:111], v[74:75], v[40:41] op_sel_hi:[1,1,0]
	v_mul_f32_e32 v40, v119, v75
	v_pk_fma_f32 v[118:119], v[118:119], v[74:75], v[40:41] op_sel_hi:[1,1,0]
	v_mul_f32_e32 v40, v147, v75
	v_pk_fma_f32 v[146:147], v[146:147], v[74:75], v[40:41] op_sel_hi:[1,1,0]
	v_mul_f32_e32 v40, v149, v75
	v_pk_fma_f32 v[148:149], v[148:149], v[74:75], v[40:41] op_sel_hi:[1,1,0]
	v_mul_f32_e32 v40, v45, v75
	v_pk_fma_f32 v[44:45], v[44:45], v[74:75], v[40:41] op_sel_hi:[1,1,0]
	v_max_f32_e32 v153, 0, v144
	v_lshlrev_b32_e32 v79, 16, v41
	v_max_f32_e32 v152, 0, v145
	v_mul_f32_e32 v40, v59, v79
	v_and_b32_e32 v78, 0xffff0000, v41
	v_pk_add_f32 v[40:41], v[40:41], v[64:65] op_sel_hi:[0,1]
	v_pk_fma_f32 v[40:41], v[58:59], v[78:79], v[40:41]
	v_mul_f32_e32 v58, v69, v79
	v_pk_add_f32 v[58:59], v[58:59], v[70:71] op_sel_hi:[0,1]
	v_pk_fma_f32 v[58:59], v[68:69], v[78:79], v[58:59]
	v_mul_f32_e32 v64, v73, v79
	v_mul_f32_e32 v68, v91, v79
	v_pk_add_f32 v[64:65], v[64:65], v[76:77] op_sel_hi:[0,1]
	v_pk_add_f32 v[68:69], v[68:69], v[142:143] op_sel_hi:[0,1]
	v_pk_fma_f32 v[64:65], v[72:73], v[78:79], v[64:65]
	v_pk_fma_f32 v[68:69], v[90:91], v[78:79], v[68:69]
	v_mul_f32_e32 v70, v103, v79
	v_mul_f32_e32 v72, v113, v79
	v_mul_f32_e32 v76, v121, v79
	v_mul_f32_e32 v90, v151, v79
	v_pk_add_f32 v[70:71], v[70:71], v[110:111] op_sel_hi:[0,1]
	v_pk_add_f32 v[72:73], v[72:73], v[118:119] op_sel_hi:[0,1]
	v_pk_add_f32 v[76:77], v[76:77], v[146:147] op_sel_hi:[0,1]
	v_pk_add_f32 v[90:91], v[90:91], v[148:149] op_sel_hi:[0,1]
	v_permlane32_swap_b32_e32 v40, v64
	v_permlane32_swap_b32_e32 v58, v68
	v_pk_fma_f32 v[70:71], v[102:103], v[78:79], v[70:71]
	v_pk_fma_f32 v[72:73], v[112:113], v[78:79], v[72:73]
	v_pk_fma_f32 v[76:77], v[120:121], v[78:79], v[76:77]
	v_pk_fma_f32 v[90:91], v[150:151], v[78:79], v[90:91]
	v_mfma_f32_16x16x32_bf16 v[110:113], v[2:5], v[134:137], 0
	v_permlane32_swap_b32_e32 v70, v76
	v_permlane32_swap_b32_e32 v72, v90
	v_mov_b32_e32 v73, v58
	v_mov_b32_e32 v91, v68
	v_mov_b32_e32 v71, v40
	v_mov_b32_e32 v77, v64
	v_pk_add_f32 v[68:69], v[72:73], v[90:91]
	v_pk_add_f32 v[70:71], v[70:71], v[76:77]
	v_and_b32_e32 v77, 0xffff0000, v38
	v_cndmask_b32_e64 v40, v71, v69, s[6:7]
	v_lshlrev_b32_e32 v76, 16, v38
	v_mul_f32_e32 v38, v55, v77
	ds_bpermute_b32 v73, v130, v40
	v_cndmask_b32_e64 v40, v70, v68, s[6:7]
	v_mfma_f32_16x16x32_bf16 v[110:113], v[6:9], v[138:141], v[110:113]
	v_fma_f32 v54, v54, v76, v38
	v_fma_f32 v55, v55, v77, v38
	v_mul_f32_e32 v38, v61, v77
	ds_bpermute_b32 v72, v130, v40
	v_mul_f32_e32 v40, v153, v79
	v_pk_fma_f32 v[58:59], v[60:61], v[76:77], v[38:39] op_sel_hi:[1,1,0]
	v_mul_f32_e32 v38, v81, v77
	v_pk_add_f32 v[40:41], v[40:41], v[44:45] op_sel_hi:[0,1]
	v_pk_fma_f32 v[60:61], v[80:81], v[76:77], v[38:39] op_sel_hi:[1,1,0]
	v_mul_f32_e32 v38, v85, v77
	v_pk_fma_f32 v[40:41], v[152:153], v[78:79], v[40:41]
	v_pk_fma_f32 v[64:65], v[84:85], v[76:77], v[38:39] op_sel_hi:[1,1,0]
	v_mul_f32_e32 v38, v97, v77
	v_pk_fma_f32 v[84:85], v[96:97], v[76:77], v[38:39] op_sel_hi:[1,1,0]
	v_mul_f32_e32 v38, v107, v77
	v_max_f32_e32 v44, 0, v110
	v_pk_fma_f32 v[90:91], v[106:107], v[76:77], v[38:39] op_sel_hi:[1,1,0]
	v_mul_f32_e32 v38, v115, v77
	v_max_f32_e32 v45, 0, v111
	v_pk_fma_f32 v[96:97], v[114:115], v[76:77], v[38:39] op_sel_hi:[1,1,0]
	v_mul_f32_e32 v38, v123, v77
	v_pk_fma_f32 v[102:103], v[122:123], v[76:77], v[38:39] op_sel_hi:[1,1,0]
	v_mul_f32_e32 v38, v45, v77
	v_pk_fma_f32 v[44:45], v[44:45], v[76:77], v[38:39] op_sel_hi:[1,1,0]
	v_max_f32_e32 v107, 0, v112
	v_lshlrev_b32_e32 v81, 16, v39
	v_max_f32_e32 v106, 0, v113
	v_mul_f32_e32 v38, v49, v81
	v_and_b32_e32 v80, 0xffff0000, v39
	v_pk_add_f32 v[38:39], v[38:39], v[54:55] op_sel_hi:[0,1]
	v_pk_fma_f32 v[38:39], v[48:49], v[80:81], v[38:39]
	v_mul_f32_e32 v48, v57, v81
	v_mul_f32_e32 v54, v63, v81
	v_pk_add_f32 v[48:49], v[48:49], v[58:59] op_sel_hi:[0,1]
	v_pk_add_f32 v[54:55], v[54:55], v[60:61] op_sel_hi:[0,1]
	v_pk_fma_f32 v[48:49], v[56:57], v[80:81], v[48:49]
	v_pk_fma_f32 v[56:57], v[62:63], v[80:81], v[54:55]
	v_mul_f32_e32 v54, v83, v81
	v_pk_add_f32 v[54:55], v[54:55], v[64:65] op_sel_hi:[0,1]
	v_mul_f32_e32 v58, v87, v81
	v_mul_f32_e32 v60, v99, v81
	v_mul_f32_e32 v62, v109, v81
	v_mul_f32_e32 v64, v117, v81
	v_pk_fma_f32 v[54:55], v[82:83], v[80:81], v[54:55]
	v_pk_add_f32 v[58:59], v[58:59], v[84:85] op_sel_hi:[0,1]
	v_pk_add_f32 v[60:61], v[60:61], v[90:91] op_sel_hi:[0,1]
	v_pk_add_f32 v[62:63], v[62:63], v[96:97] op_sel_hi:[0,1]
	v_pk_add_f32 v[64:65], v[64:65], v[102:103] op_sel_hi:[0,1]
	v_permlane32_swap_b32_e32 v38, v56
	v_permlane32_swap_b32_e32 v48, v54
	v_pk_fma_f32 v[58:59], v[86:87], v[80:81], v[58:59]
	v_pk_fma_f32 v[60:61], v[98:99], v[80:81], v[60:61]
	v_pk_fma_f32 v[62:63], v[108:109], v[80:81], v[62:63]
	v_pk_fma_f32 v[64:65], v[116:117], v[80:81], v[64:65]
	s_nop 0
	v_permlane32_swap_b32_e32 v58, v62
	v_permlane32_swap_b32_e32 v60, v64
	v_mov_b32_e32 v61, v48
	v_mov_b32_e32 v65, v54
	v_mov_b32_e32 v59, v38
	v_mov_b32_e32 v63, v56
	v_pk_add_f32 v[54:55], v[60:61], v[64:65]
	v_pk_add_f32 v[58:59], v[58:59], v[62:63]
	ds_read_b128 v[60:63], v131 offset:20736
	ds_read_b128 v[82:85], v131 offset:20800
	s_waitcnt lgkmcnt(1)
; #define LAS __attribute__((address_space(3)))
; __device__ __forceinline__ f32x4 mfma16(bf16x8 a, bf16x8 b, f32x4 c) { return __builtin_amdgcn_mfma_f32_16x16x32_bf16(a, b, c, 0, 0, 0); }
; __device__ __forceinline__ void att_unit(LAS unsigned char* lds, const bf16* P, const bf16* AKV, const bf16* IKC, bf16* ACAT, const float* aqg, const float* ssq_ak, const float* ssq_ik, int b, int qg, int tid) {
;     ...
;                     for (int q4 = 0; q4 < 4; ++q4) {
;                         const LAS unsigned char* kp = IKc + (64 * r4 + 16 * q4 + fr) * 144 + fq * 16;
;                         const bf16x8 K0 = *(const LAS bf16x8*)kp, K1 = *(const LAS bf16x8*)(kp + 64);
; #pragma unroll
;                         for (int q = 0; q < 2; ++q) {
;                             f32x4 a = (f32x4){0.f, 0.f, 0.f, 0.f};
;                             a = mfma16(Qi[q][0], K0, a); a = mfma16(Qi[q][1], K1, a);
;                             pt[q][q4] = fmaxf(a[0], 0.f) * wv[q][0] + fmaxf(a[1], 0.f) * wv[q][1] + fmaxf(a[2], 0.f) * wv[q][2] + fmaxf(a[3], 0.f) * wv[q][3];
;                         }
;                     }
;                     const int rr = 4 * tile + r4;
;                     const float rscale = rsqrtf((rc[r4].x + rc[r4].y) * (1.f / 64.f) + EPS);
;                     const bool live = 64 * rr + lane < L;
; #pragma unroll
;                     for (int q = 0; q < 2; ++q) {
;                         float hx; const float A = half_sum32(pt[q][0], pt[q][2], hx), B = half_sum32(pt[q][1], pt[q][3], hx);
;                         const bool odd = fq & 1;
;                         const float send = odd ? A : B, keep = odd ? B : A;
;                         const float sc = live ? (keep + __shfl_xor(send, 16)) * rscale : -INFINITY;
;                         const unsigned bts = __float_as_uint(sc);
;                         uk[q][rr] = bts ^ ((unsigned)((int)bts >> 31) | 0x80000000u);
	v_mfma_f32_16x16x32_bf16 v[96:99], v[14:17], v[60:63], 0
	v_cndmask_b32_e64 v38, v59, v55, s[6:7]
	ds_bpermute_b32 v57, v130, v38
	v_cndmask_b32_e64 v38, v58, v54, s[6:7]
	s_waitcnt lgkmcnt(1)
	v_mfma_f32_16x16x32_bf16 v[96:99], v[10:13], v[82:85], v[96:99]
	ds_bpermute_b32 v56, v130, v38
	v_mul_f32_e32 v38, v107, v81
	v_pk_add_f32 v[38:39], v[38:39], v[44:45] op_sel_hi:[0,1]
	v_mfma_f32_16x16x32_bf16 v[60:63], v[2:5], v[60:63], 0
	v_fma_f32 v38, v106, v80, v38
	v_fma_f32 v39, v107, v81, v39
	s_mov_b32 s0, 0x800000
	s_nop 0
	v_max_f32_e32 v44, 0, v96
	v_max_f32_e32 v45, 0, v97
	v_mfma_f32_16x16x32_bf16 v[60:63], v[6:9], v[82:85], v[60:63]
	v_mul_f32_e32 v48, v45, v75
	v_pk_fma_f32 v[44:45], v[44:45], v[74:75], v[48:49] op_sel_hi:[1,1,0]
	v_max_f32_e32 v49, 0, v98
	v_mul_f32_e32 v64, v49, v79
	v_max_f32_e32 v48, 0, v99
	v_pk_add_f32 v[44:45], v[64:65], v[44:45] op_sel_hi:[0,1]
	v_pk_fma_f32 v[44:45], v[48:49], v[78:79], v[44:45]
	s_nop 0
	v_max_f32_e32 v48, 0, v60
	v_max_f32_e32 v49, 0, v61
	v_mul_f32_e32 v60, v49, v77
	v_pk_fma_f32 v[48:49], v[48:49], v[76:77], v[60:61] op_sel_hi:[1,1,0]
	v_max_f32_e32 v61, 0, v62
	v_mul_f32_e32 v62, v61, v81
	v_max_f32_e32 v60, 0, v63
	v_pk_add_f32 v[48:49], v[62:63], v[48:49] op_sel_hi:[0,1]
	v_pk_fma_f32 v[48:49], v[60:61], v[80:81], v[48:49]
	ds_read_b128 v[60:63], v131 offset:23040
	ds_read_b128 v[96:99], v131 offset:23104
	s_waitcnt lgkmcnt(1)
	v_mfma_f32_16x16x32_bf16 v[82:85], v[14:17], v[60:63], 0
	v_cmp_gt_f32_e64 s[8:9], s0, v92
	v_cmp_gt_f32_e64 s[10:11], s0, v93
	v_mfma_f32_16x16x32_bf16 v[60:63], v[2:5], v[60:63], 0
	s_waitcnt lgkmcnt(0)
	v_mfma_f32_16x16x32_bf16 v[82:85], v[10:13], v[96:99], v[82:85]
	v_mfma_f32_16x16x32_bf16 v[60:63], v[6:9], v[96:99], v[60:63]
	ds_read_b128 v[96:99], v131 offset:25344
	ds_read_b128 v[106:109], v131 offset:25408
	s_nop 4
	v_max_f32_e32 v64, 0, v82
	v_max_f32_e32 v65, 0, v83
	v_mul_f32_e32 v82, v65, v75
	s_waitcnt lgkmcnt(1)
	v_mfma_f32_16x16x32_bf16 v[110:113], v[14:17], v[96:99], 0
	v_fma_f32 v64, v64, v74, v82
	v_fma_f32 v65, v65, v75, v82
	v_max_f32_e32 v83, 0, v84
	v_max_f32_e32 v82, 0, v85
	v_mul_f32_e32 v84, v83, v79
	v_max_f32_e32 v60, 0, v60
	v_pk_add_f32 v[64:65], v[84:85], v[64:65] op_sel_hi:[0,1]
	v_max_f32_e32 v61, 0, v61
	s_waitcnt lgkmcnt(0)
	v_mfma_f32_16x16x32_bf16 v[110:113], v[10:13], v[106:109], v[110:113]
	v_fma_f32 v84, v82, v78, v64
	v_fma_f32 v85, v83, v79, v65
	v_mul_f32_e32 v64, v61, v77
	v_pk_fma_f32 v[60:61], v[60:61], v[76:77], v[64:65] op_sel_hi:[1,1,0]
	v_max_f32_e32 v65, 0, v62
	v_mfma_f32_16x16x32_bf16 v[96:99], v[2:5], v[96:99], 0
	v_mul_f32_e32 v62, v65, v81
	v_max_f32_e32 v64, 0, v63
	v_pk_add_f32 v[60:61], v[62:63], v[60:61] op_sel_hi:[0,1]
	v_pk_fma_f32 v[62:63], v[64:65], v[80:81], v[60:61]
	v_max_f32_e32 v60, 0, v110
	v_max_f32_e32 v61, 0, v111
	v_mfma_f32_16x16x32_bf16 v[96:99], v[6:9], v[106:109], v[96:99]
	v_mul_f32_e32 v64, v61, v75
	v_pk_fma_f32 v[60:61], v[60:61], v[74:75], v[64:65] op_sel_hi:[1,1,0]
	v_max_f32_e32 v65, 0, v112
	v_mul_f32_e32 v82, v65, v79
	v_max_f32_e32 v64, 0, v113
	v_pk_add_f32 v[60:61], v[82:83], v[60:61] op_sel_hi:[0,1]
	v_pk_fma_f32 v[82:83], v[64:65], v[78:79], v[60:61]
	s_nop 0
	v_max_f32_e32 v60, 0, v96
	v_max_f32_e32 v61, 0, v97
	v_mul_f32_e32 v64, v61, v77
	v_pk_fma_f32 v[60:61], v[60:61], v[76:77], v[64:65] op_sel_hi:[1,1,0]
	v_max_f32_e32 v65, 0, v98
	v_max_f32_e32 v64, 0, v99
	ds_read_b128 v[96:99], v131 offset:27648
	ds_read_b128 v[106:109], v131 offset:27712
	s_waitcnt lgkmcnt(1)
	v_mfma_f32_16x16x32_bf16 v[110:113], v[14:17], v[96:99], 0
	v_mul_f32_e32 v86, v65, v81
	v_pk_add_f32 v[60:61], v[86:87], v[60:61] op_sel_hi:[0,1]
	s_waitcnt lgkmcnt(0)
	v_mfma_f32_16x16x32_bf16 v[110:113], v[10:13], v[106:109], v[110:113]
	v_fma_f32 v60, v64, v80, v60
	v_fma_f32 v61, v65, v81, v61
	v_permlane32_swap_b32_e32 v38, v62
	v_mfma_f32_16x16x32_bf16 v[96:99], v[2:5], v[96:99], 0
	v_permlane32_swap_b32_e32 v48, v60
	s_nop 2
	v_max_f32_e32 v64, 0, v110
	v_max_f32_e32 v65, 0, v111
	v_mfma_f32_16x16x32_bf16 v[96:99], v[6:9], v[106:109], v[96:99]
	v_mul_f32_e32 v86, v65, v75
	v_pk_fma_f32 v[64:65], v[64:65], v[74:75], v[86:87] op_sel_hi:[1,1,0]
	v_max_f32_e32 v87, 0, v112
	v_mul_f32_e32 v90, v87, v79
	v_max_f32_e32 v86, 0, v113
	v_pk_add_f32 v[64:65], v[90:91], v[64:65] op_sel_hi:[0,1]
	v_pk_fma_f32 v[86:87], v[86:87], v[78:79], v[64:65]
	s_nop 0
	v_max_f32_e32 v64, 0, v96
	v_max_f32_e32 v65, 0, v97
	v_mul_f32_e32 v90, v65, v77
	v_pk_fma_f32 v[64:65], v[64:65], v[76:77], v[90:91] op_sel_hi:[1,1,0]
	v_max_f32_e32 v91, 0, v98
	v_mul_f32_e32 v96, v91, v81
	v_max_f32_e32 v90, 0, v99
	v_pk_add_f32 v[64:65], v[96:97], v[64:65] op_sel_hi:[0,1]
	ds_read_b128 v[96:99], v131 offset:29952
	ds_read_b128 v[106:109], v131 offset:30016
	s_waitcnt lgkmcnt(1)
	v_mfma_f32_16x16x32_bf16 v[110:113], v[14:17], v[96:99], 0
	v_pk_fma_f32 v[64:65], v[90:91], v[80:81], v[64:65]
	v_permlane32_swap_b32_e32 v40, v84
	s_waitcnt lgkmcnt(0)
	v_mfma_f32_16x16x32_bf16 v[110:113], v[10:13], v[106:109], v[110:113]
	v_mov_b32_e32 v65, v38
	v_permlane32_swap_b32_e32 v44, v82
	v_mfma_f32_16x16x32_bf16 v[96:99], v[2:5], v[96:99], 0
	v_mov_b32_e32 v87, v40
	s_nop 3
	v_max_f32_e32 v90, 0, v110
	v_max_f32_e32 v91, 0, v111
	v_mul_f32_e32 v102, v91, v75
	v_pk_fma_f32 v[90:91], v[90:91], v[74:75], v[102:103] op_sel_hi:[1,1,0]
	v_max_f32_e32 v103, 0, v112
	v_mul_f32_e32 v110, v103, v79
	v_max_f32_e32 v102, 0, v113
	v_pk_add_f32 v[90:91], v[110:111], v[90:91] op_sel_hi:[0,1]
	v_mfma_f32_16x16x32_bf16 v[96:99], v[6:9], v[106:109], v[96:99]
	ds_read_b128 v[106:109], v131 offset:32256
	ds_read_b128 v[110:113], v131 offset:32320
	v_pk_fma_f32 v[90:91], v[102:103], v[78:79], v[90:91]
	s_waitcnt lgkmcnt(1)
; #define LAS __attribute__((address_space(3)))
; __device__ __forceinline__ void att_unit(LAS unsigned char* lds, const bf16* P, const bf16* AKV, const bf16* IKC, bf16* ACAT, const float* aqg, const float* ssq_ak, const float* ssq_ik, int b, int qg, int tid) {
;     ...
;                             pt[q][q4] = fmaxf(a[0], 0.f) * wv[q][0] + fmaxf(a[1], 0.f) * wv[q][1] + fmaxf(a[2], 0.f) * wv[q][2] + fmaxf(a[3], 0.f) * wv[q][3];
;                         }
;                     }
;                     const int rr = 4 * tile + r4;
;                     const float rscale = rsqrtf((rc[r4].x + rc[r4].y) * (1.f / 64.f) + EPS);
;                     const bool live = 64 * rr + lane < L;
; #pragma unroll
;                     for (int q = 0; q < 2; ++q) {
;                         float hx; const float A = half_sum32(pt[q][0], pt[q][2], hx), B = half_sum32(pt[q][1], pt[q][3], hx);
;                         const bool odd = fq & 1;
;                         const float send = odd ? A : B, keep = odd ? B : A;
;                         const float sc = live ? (keep + __shfl_xor(send, 16)) * rscale : -INFINITY;
;                         const unsigned bts = __float_as_uint(sc);
;                         uk[q][rr] = bts ^ ((unsigned)((int)bts >> 31) | 0x80000000u);
;                     }
;                 }
;                 if (tile + 1 < ntile) {
; #pragma unroll
;                     for (int i = 0; i < 4; ++i) *(LAS u32x4*)(IK + ((tile + 1) & 1) * 36864 + (skey + 64 * i) * 144 + spart * 16) = ikr[i];
;                 }
;                 __syncthreads();
	v_mfma_f32_16x16x32_bf16 v[114:117], v[14:17], v[106:109], 0
	s_nop 1
	s_nop 0
	v_max_f32_e32 v96, 0, v96
	s_waitcnt lgkmcnt(0)
	v_mfma_f32_16x16x32_bf16 v[114:117], v[10:13], v[110:113], v[114:117]
	v_max_f32_e32 v97, 0, v97
	v_mul_f32_e32 v102, v97, v77
	v_mfma_f32_16x16x32_bf16 v[106:109], v[2:5], v[106:109], 0
	v_fma_f32 v96, v96, v76, v102
	v_fma_f32 v97, v97, v77, v102
	v_max_f32_e32 v103, 0, v98
	v_max_f32_e32 v102, 0, v99
	v_mul_f32_e32 v98, v103, v81
	v_pk_add_f32 v[96:97], v[98:99], v[96:97] op_sel_hi:[0,1]
	v_max_f32_e32 v98, 0, v114
	v_max_f32_e32 v99, 0, v115
	v_mfma_f32_16x16x32_bf16 v[106:109], v[6:9], v[110:113], v[106:109]
	v_fma_f32 v96, v102, v80, v96
	v_fma_f32 v97, v103, v81, v97
	v_mul_f32_e32 v102, v99, v75
	v_pk_fma_f32 v[98:99], v[98:99], v[74:75], v[102:103] op_sel_hi:[1,1,0]
	v_max_f32_e32 v103, 0, v116
	v_mul_f32_e32 v114, v103, v79
	v_max_f32_e32 v102, 0, v117
	v_pk_add_f32 v[98:99], v[114:115], v[98:99] op_sel_hi:[0,1]
	v_pk_fma_f32 v[98:99], v[102:103], v[78:79], v[98:99]
	v_max_f32_e32 v102, 0, v106
	v_max_f32_e32 v103, 0, v107
	v_mul_f32_e32 v106, v103, v77
	v_pk_fma_f32 v[102:103], v[102:103], v[76:77], v[106:107] op_sel_hi:[1,1,0]
	v_max_f32_e32 v107, 0, v108
	v_mul_f32_e32 v108, v107, v81
	v_max_f32_e32 v106, 0, v109
	v_pk_add_f32 v[102:103], v[108:109], v[102:103] op_sel_hi:[0,1]
	v_pk_fma_f32 v[102:103], v[106:107], v[80:81], v[102:103]
	ds_read_b128 v[106:109], v131 offset:34560
	ds_read_b128 v[110:113], v131 offset:34624
	s_waitcnt lgkmcnt(1)
	v_mfma_f32_16x16x32_bf16 v[114:117], v[14:17], v[106:109], 0
	v_permlane32_swap_b32_e32 v64, v102
	v_mov_b32_e32 v97, v48
	s_waitcnt lgkmcnt(0)
	v_mfma_f32_16x16x32_bf16 v[114:117], v[10:13], v[110:113], v[114:117]
	v_mov_b32_e32 v103, v62
	v_pk_add_f32 v[64:65], v[64:65], v[102:103]
	v_permlane32_swap_b32_e32 v86, v98
	v_mfma_f32_16x16x32_bf16 v[106:109], v[2:5], v[106:109], 0
	s_nop 3
	v_max_f32_e32 v114, 0, v114
	v_mfma_f32_16x16x32_bf16 v[106:109], v[6:9], v[110:113], v[106:109]
	v_max_f32_e32 v115, 0, v115
	v_mul_f32_e32 v118, v115, v75
	v_pk_fma_f32 v[114:115], v[114:115], v[74:75], v[118:119] op_sel_hi:[1,1,0]
	v_max_f32_e32 v119, 0, v116
	v_max_f32_e32 v118, 0, v117
	s_nop 0
	s_nop 1
	v_max_f32_e32 v106, 0, v106
	v_max_f32_e32 v107, 0, v107
	v_mul_f32_e32 v110, v107, v77
	v_pk_fma_f32 v[106:107], v[106:107], v[76:77], v[110:111] op_sel_hi:[1,1,0]
	v_max_f32_e32 v111, 0, v108
	v_mul_f32_e32 v108, v111, v81
	v_max_f32_e32 v110, 0, v109
	v_pk_add_f32 v[106:107], v[108:109], v[106:107] op_sel_hi:[0,1]
	v_mul_f32_e32 v116, v119, v79
	v_pk_fma_f32 v[108:109], v[110:111], v[80:81], v[106:107]
	v_pk_add_f32 v[114:115], v[116:117], v[114:115] op_sel_hi:[0,1]
	s_nop 0
	v_permlane32_swap_b32_e32 v96, v108
	s_waitcnt vmcnt(8)
	v_mov_b32_e32 v106, v36
	v_mov_b32_e32 v107, v34
	v_mov_b32_e32 v34, v37
	v_mov_b32_e32 v109, v60
	v_pk_fma_f32 v[114:115], v[118:119], v[78:79], v[114:115]
	v_pk_add_f32 v[34:35], v[106:107], v[34:35]
	v_pk_add_f32 v[60:61], v[96:97], v[108:109]
	v_permlane32_swap_b32_e32 v90, v114
	v_pk_fma_f32 v[106:107], v[34:35], s[2:3], v[42:43] op_sel_hi:[1,0,0]
	v_cndmask_b32_e64 v34, v65, v61, s[6:7]
	v_mov_b32_e32 v91, v44
	v_mov_b32_e32 v115, v82
	v_mov_b32_e32 v99, v84
	ds_bpermute_b32 v63, v130, v34
	v_cndmask_b32_e64 v34, v64, v60, s[6:7]
	v_pk_add_f32 v[82:83], v[90:91], v[114:115]
	v_pk_add_f32 v[86:87], v[86:87], v[98:99]
	ds_bpermute_b32 v62, v130, v34
	v_cndmask_b32_e64 v34, v87, v83, s[6:7]
	ds_bpermute_b32 v85, v130, v34
	v_cndmask_b32_e64 v34, v86, v82, s[6:7]
	ds_bpermute_b32 v84, v130, v34
	v_cmp_gt_f32_e64 s[12:13], s0, v106
	v_cmp_gt_f32_e64 s[14:15], s0, v107
	s_movk_i32 s0, 0x1c0
	v_cmp_lt_u32_e64 s[0:1], s0, v132
	s_waitcnt vmcnt(0)
	v_mov_b64_e32 v[90:91], v[94:95]
	v_mov_b64_e32 v[96:97], v[100:101]
	v_mov_b64_e32 v[98:99], v[104:105]
	v_mov_b64_e32 v[102:103], v[46:47]
	ds_write_b128 v129, v[18:21] offset:36864
	ds_write_b128 v129, v[22:25] offset:46080
	ds_write_b128 v129, v[26:29] offset:55296
	ds_write_b128 v129, v[30:33] offset:64512
	s_waitcnt lgkmcnt(0)
	s_barrier
	s_and_saveexec_b64 s[2:3], s[0:1]
	s_cbranch_execz .LBB0_596
	v_add_co_u32_e32 v18, vcc, 0x20000, v66
	s_nop 1
	v_addc_co_u32_e32 v19, vcc, 0, v67, vcc
	v_add_co_u32_e32 v34, vcc, 0x1000, v88
	global_load_dwordx4 v[18:21], v[18:19], off
	s_nop 0
	v_addc_co_u32_e32 v35, vcc, 0, v89, vcc
	v_add_co_u32_e32 v22, vcc, 0x24000, v66
	s_nop 1
	v_addc_co_u32_e32 v23, vcc, 0, v67, vcc
	v_add_co_u32_e32 v26, vcc, 0x28000, v66
	s_nop 1
	v_addc_co_u32_e32 v27, vcc, 0, v67, vcc
	v_add_co_u32_e32 v30, vcc, 0x2c000, v66
	global_load_dwordx4 v[22:25], v[22:23], off
	s_nop 0
	global_load_dwordx4 v[26:29], v[26:27], off
	v_addc_co_u32_e32 v31, vcc, 0, v67, vcc
	global_load_dwordx4 v[30:33], v[30:31], off
	s_nop 0
	global_load_dwordx2 v[102:103], v[34:35], off
	global_load_dwordx2 v[98:99], v[34:35], off offset:512
	global_load_dwordx2 v[96:97], v[34:35], off offset:1024
	global_load_dwordx2 v[90:91], v[34:35], off offset:1536

; #define LAS __attribute__((address_space(3)))
; #define GAS __attribute__((address_space(1)))
; __device__ __forceinline__ float bflo(unsigned w) { return __uint_as_float(w << 16); }
; __device__ __forceinline__ float bfhi(unsigned w) { return __uint_as_float(w & 0xffff0000u); }
; __device__ __forceinline__ unsigned pk2(float lo, float hi) { unsigned r; asm("v_cvt_pk_bf16_f32 %0, %1, %2" : "=v"(r) : "v"(lo), "v"(hi)); return r; }
; __device__ __forceinline__ void att_core(LAS unsigned char* Vst, const LAS float* listr, const LAS unsigned* listT, const bf16* P, const bf16* AKVb, bf16* ACAT, const float* aqg, size_t tok, int cnt, int lane) {
;     ...
;     const GAS unsigned char* kbase = (const GAS unsigned char*)AKVb + fr * 16;
;     const LAS unsigned* lt = listT + fq * 8;
;     u32x4 kb[3][8];
; #pragma unroll
;     for (int s2 = 0; s2 < 3; ++s2) {
;         const u32x4 o0 = *(const LAS u32x4*)(lt + s2 * 32), o1 = *(const LAS u32x4*)(lt + s2 * 32 + 4);
; #pragma unroll
;         for (int i = 0; i < 8; ++i) kb[s2][i] = *(const GAS u32x4*)(kbase + (i < 4 ? o0[i & 3] : o1[i & 3]));
;     }
;     bf16x8 Qf[4];
;     {
;         u32x4 raw[4]; float ss = 0.f;
; #pragma unroll
;         for (int kk = 0; kk < 4; ++kk) { raw[kk] = *(const GAS u32x4*)(P + tok * NP + C_AQ + fr * 128 + 32 * kk + 8 * fq);
; #pragma unroll
;             for (int e = 0; e < 4; ++e) { const float lo = bflo(raw[kk][e]), hi = bfhi(raw[kk][e]); ss += lo * lo + hi * hi; } }
;         ss += __shfl_xor(ss, 16); ss += __shfl_xor(ss, 32);
;         const float rq = rsqrtf(ss * (1.f / 128.f) + EPS) * (0.08838834764831845f * LOG2E);
; #pragma unroll
;         for (int kk = 0; kk < 4; ++kk) { const f32x4 g0 = *(const GAS f32x4*)(aqg + 32 * kk + 8 * fq), g1 = *(const GAS f32x4*)(aqg + 32 * kk + 8 * fq + 4); u32x4 o;
;             o.x = pk2(bflo(raw[kk].x) * rq * g0.x, bfhi(raw[kk].x) * rq * g0.y); o.y = pk2(bflo(raw[kk].y) * rq * g0.z, bfhi(raw[kk].y) * rq * g0.w);
;             o.z = pk2(bflo(raw[kk].z) * rq * g1.x, bfhi(raw[kk].z) * rq * g1.y); o.w = pk2(bflo(raw[kk].w) * rq * g1.z, bfhi(raw[kk].w) * rq * g1.w);
;             Qf[kk] = __builtin_bit_cast(bf16x8, o); }
.LBB0_1010:
	v_lshl_add_u32 v167, s33, 10, v184
	ds_read_b128 v[2:5], v167 offset:4096
	ds_read_b128 v[6:9], v167 offset:4112
	v_cndmask_b32_e64 v0, 0, 1, s[42:43]
	v_cmp_ne_u32_e64 s[40:41], 1, v0
	v_mov_b32_e32 v0, s45
	v_or_b32_e32 v156, s33, v0
	s_waitcnt lgkmcnt(1)
	v_mov_b32_e32 v0, v2
	v_lshl_add_u64 v[10:11], v[160:161], 0, v[0:1]
	v_mov_b32_e32 v0, v3
	v_lshl_add_u64 v[2:3], v[160:161], 0, v[0:1]
	v_mov_b32_e32 v0, v4
	global_load_dwordx4 v[66:69], v[10:11], off
	global_load_dwordx4 v[70:73], v[2:3], off
	v_lshl_add_u64 v[2:3], v[160:161], 0, v[0:1]
	v_mov_b32_e32 v0, v5
	global_load_dwordx4 v[74:77], v[2:3], off
	v_lshl_add_u64 v[2:3], v[160:161], 0, v[0:1]
	s_waitcnt lgkmcnt(0)
	v_mov_b32_e32 v0, v6
	global_load_dwordx4 v[78:81], v[2:3], off
	v_lshl_add_u64 v[2:3], v[160:161], 0, v[0:1]
	v_mov_b32_e32 v0, v7
	global_load_dwordx4 v[82:85], v[2:3], off
	v_lshl_add_u64 v[2:3], v[160:161], 0, v[0:1]
	v_mov_b32_e32 v0, v8
	global_load_dwordx4 v[86:89], v[2:3], off
	v_lshl_add_u64 v[2:3], v[160:161], 0, v[0:1]
	v_mov_b32_e32 v0, v9
	global_load_dwordx4 v[90:93], v[2:3], off
	v_lshl_add_u64 v[2:3], v[160:161], 0, v[0:1]
	global_load_dwordx4 v[94:97], v[2:3], off
	ds_read_b128 v[2:5], v167 offset:4224
	ds_read_b128 v[6:9], v167 offset:4240
	v_mov_b32_e32 v98, s48
	v_mad_u64_u32 v[182:183], s[42:43], v156, s44, v[154:155]
	s_waitcnt lgkmcnt(1)
	v_mov_b32_e32 v0, v2
	v_lshl_add_u64 v[10:11], v[160:161], 0, v[0:1]
	v_mov_b32_e32 v0, v3
	v_lshl_add_u64 v[2:3], v[160:161], 0, v[0:1]
	v_mov_b32_e32 v0, v4
	global_load_dwordx4 v[34:37], v[10:11], off
	global_load_dwordx4 v[38:41], v[2:3], off
	v_lshl_add_u64 v[2:3], v[160:161], 0, v[0:1]
	v_mov_b32_e32 v0, v5
	v_mad_i32_i24 v183, v98, s44, v183
	v_mov_b32_e32 v165, v1
	global_load_dwordx4 v[42:45], v[2:3], off
	v_lshl_add_u64 v[2:3], v[160:161], 0, v[0:1]
	s_waitcnt lgkmcnt(0)
	v_mov_b32_e32 v0, v6
	v_lshl_add_u64 v[98:99], v[182:183], 0, v[164:165]
	global_load_dwordx4 v[46:49], v[2:3], off
	v_lshl_add_u64 v[2:3], v[160:161], 0, v[0:1]
	v_mov_b32_e32 v0, v7
	v_lshl_add_u64 v[100:101], v[158:159], 1, v[98:99]
	s_mov_b64 s[42:43], 0x4000
	global_load_dwordx4 v[50:53], v[2:3], off
	v_lshl_add_u64 v[2:3], v[160:161], 0, v[0:1]
	v_mov_b32_e32 v0, v8
	v_lshl_add_u64 v[98:99], v[100:101], 0, s[42:43]
	s_movk_i32 s42, 0x4000
	global_load_dwordx4 v[54:57], v[2:3], off
	v_lshl_add_u64 v[2:3], v[160:161], 0, v[0:1]
	v_mov_b32_e32 v0, v9
	v_add_co_u32_e32 v100, vcc, s42, v100
	global_load_dwordx4 v[58:61], v[2:3], off
	v_lshl_add_u64 v[2:3], v[160:161], 0, v[0:1]
	v_addc_co_u32_e32 v101, vcc, 0, v101, vcc
	global_load_dwordx4 v[62:65], v[2:3], off
	ds_read_b128 v[12:15], v167 offset:4352
	ds_read_b128 v[28:31], v167 offset:4368
	global_load_dwordx4 v[100:103], v[100:101], off
	v_lshl_add_u32 v165, s33, 11, v197
	global_load_dwordx4 v[104:107], v[98:99], off offset:64
	global_load_dwordx4 v[132:135], v[98:99], off offset:192
	s_waitcnt lgkmcnt(1)
	v_mov_b32_e32 v0, v12
	v_lshl_add_u64 v[2:3], v[160:161], 0, v[0:1]
	v_mov_b32_e32 v0, v13
	v_lshl_add_u64 v[6:7], v[160:161], 0, v[0:1]
	v_mov_b32_e32 v0, v14
	v_lshl_add_u64 v[10:11], v[160:161], 0, v[0:1]
	v_mov_b32_e32 v0, v15
	v_lshl_add_u64 v[14:15], v[160:161], 0, v[0:1]
	s_waitcnt lgkmcnt(0)
	v_mov_b32_e32 v0, v28
	v_lshl_add_u64 v[18:19], v[160:161], 0, v[0:1]
	v_mov_b32_e32 v0, v29
	v_lshl_add_u64 v[22:23], v[160:161], 0, v[0:1]
	v_mov_b32_e32 v0, v30
	v_lshl_add_u64 v[26:27], v[160:161], 0, v[0:1]
	v_mov_b32_e32 v0, v31
	v_lshl_add_u64 v[30:31], v[160:161], 0, v[0:1]
	global_load_dwordx4 v[2:5], v[2:3], off
	s_waitcnt vmcnt(3)
	v_lshlrev_b32_e32 v131, 16, v100
	v_and_b32_e32 v127, 0xffff0000, v100
	v_and_b32_e32 v100, 0xffff0000, v101
	v_mul_f32_e32 v0, v127, v127
	v_lshlrev_b32_e32 v128, 16, v101
	v_mul_f32_e32 v101, v100, v100
	v_fmac_f32_e32 v0, v131, v131
	v_fmac_f32_e32 v101, v128, v128
	v_add_f32_e32 v0, v0, v101
	v_and_b32_e32 v101, 0xffff0000, v102
	v_lshlrev_b32_e32 v129, 16, v102
	v_mul_f32_e32 v102, v101, v101
	v_fmac_f32_e32 v102, v129, v129
	v_and_b32_e32 v126, 0xffff0000, v103
	v_add_f32_e32 v0, v102, v0
	v_lshlrev_b32_e32 v130, 16, v103
	v_mul_f32_e32 v102, v126, v126
	v_fmac_f32_e32 v102, v130, v130
	v_add_f32_e32 v103, v102, v0
	s_waitcnt vmcnt(2)
	v_and_b32_e32 v0, 0xffff0000, v104
	v_lshlrev_b32_e32 v102, 16, v104
	v_mul_f32_e32 v104, v0, v0
	v_fmac_f32_e32 v104, v102, v102
	v_add_f32_e32 v104, v104, v103
	v_and_b32_e32 v103, 0xffff0000, v105
	v_lshlrev_b32_e32 v122, 16, v105
	v_mul_f32_e32 v105, v103, v103
	v_fmac_f32_e32 v105, v122, v122
	v_add_f32_e32 v105, v105, v104
	v_and_b32_e32 v104, 0xffff0000, v106
	v_lshlrev_b32_e32 v123, 16, v106
	v_mul_f32_e32 v106, v104, v104
	v_fmac_f32_e32 v106, v123, v123
	v_add_f32_e32 v106, v106, v105
	v_and_b32_e32 v105, 0xffff0000, v107
	v_lshlrev_b32_e32 v124, 16, v107
	v_mul_f32_e32 v107, v105, v105
	v_fmac_f32_e32 v107, v124, v124
	v_add_f32_e32 v114, v107, v106
	global_load_dwordx4 v[106:109], v[98:99], off offset:128
	s_waitcnt vmcnt(2)
	v_and_b32_e32 v119, 0xffff0000, v133
	v_and_b32_e32 v118, 0xffff0000, v132
	v_lshlrev_b32_e32 v121, 16, v133
	v_lshlrev_b32_e32 v120, 16, v132
	v_pk_mul_f32 v[98:99], v[118:119], v[118:119]
	global_load_dwordx4 v[6:9], v[6:7], off
	v_pk_fma_f32 v[98:99], v[120:121], v[120:121], v[98:99]
	global_load_dwordx4 v[10:13], v[10:11], off
	v_lshlrev_b32_e32 v117, 16, v135
	global_load_dwordx4 v[14:17], v[14:15], off
	s_waitcnt vmcnt(3)
; #define LAS __attribute__((address_space(3)))
; #define GAS __attribute__((address_space(1)))
; __device__ __forceinline__ float bflo(unsigned w) { return __uint_as_float(w << 16); }
; __device__ __forceinline__ float bfhi(unsigned w) { return __uint_as_float(w & 0xffff0000u); }
; __device__ __forceinline__ unsigned pk2(float lo, float hi) { unsigned r; asm("v_cvt_pk_bf16_f32 %0, %1, %2" : "=v"(r) : "v"(lo), "v"(hi)); return r; }
; __device__ __forceinline__ void att_core(LAS unsigned char* Vst, const LAS float* listr, const LAS unsigned* listT, const bf16* P, const bf16* AKVb, bf16* ACAT, const float* aqg, size_t tok, int cnt, int lane) {
;     ...
;         for (int kk = 0; kk < 4; ++kk) { raw[kk] = *(const GAS u32x4*)(P + tok * NP + C_AQ + fr * 128 + 32 * kk + 8 * fq);
; #pragma unroll
;             for (int e = 0; e < 4; ++e) { const float lo = bflo(raw[kk][e]), hi = bfhi(raw[kk][e]); ss += lo * lo + hi * hi; } }
;         ss += __shfl_xor(ss, 16); ss += __shfl_xor(ss, 32);
;         const float rq = rsqrtf(ss * (1.f / 128.f) + EPS) * (0.08838834764831845f * LOG2E);
; #pragma unroll
;         for (int kk = 0; kk < 4; ++kk) { const f32x4 g0 = *(const GAS f32x4*)(aqg + 32 * kk + 8 * fq), g1 = *(const GAS f32x4*)(aqg + 32 * kk + 8 * fq + 4); u32x4 o;
;             o.x = pk2(bflo(raw[kk].x) * rq * g0.x, bfhi(raw[kk].x) * rq * g0.y); o.y = pk2(bflo(raw[kk].y) * rq * g0.z, bfhi(raw[kk].y) * rq * g0.w);
;             o.z = pk2(bflo(raw[kk].z) * rq * g1.x, bfhi(raw[kk].z) * rq * g1.y); o.w = pk2(bflo(raw[kk].w) * rq * g1.z, bfhi(raw[kk].w) * rq * g1.w);
;             Qf[kk] = __builtin_bit_cast(bf16x8, o); }
;     }
;     f32x4 lg[16];
;     float mx = -INFINITY;
; #pragma unroll
;     for (int st = 0; st < 8; ++st) {
; #pragma unroll
;         for (int i = 0; i < 8; ++i) *(LAS u32x4*)(Vst + (4 * i + fq) * 272 + fr * 16) = kb[st % 3][i];
;         __builtin_amdgcn_fence(__ATOMIC_RELEASE, "wavefront"); __builtin_amdgcn_wave_barrier();
;         bf16x8 Kf[2][4];
; #pragma unroll
;         for (int gg = 0; gg < 2; ++gg)
; #pragma unroll
;             for (int kk = 0; kk < 4; ++kk) Kf[gg][kk] = *(const LAS bf16x8*)(Vst + (16 * gg + fr) * 272 + kk * 64 + fq * 16);
;         const f32x4 lr0 = *(const LAS f32x4*)(listr + 32 * st + 4 * fq), lr1 = *(const LAS f32x4*)(listr + 32 * st + 16 + 4 * fq);
	v_lshlrev_b32_e32 v113, 16, v107
	v_lshlrev_b32_e32 v112, 16, v106
	v_and_b32_e32 v107, 0xffff0000, v107
	v_and_b32_e32 v106, 0xffff0000, v106
	v_pk_mul_f32 v[110:111], v[106:107], v[106:107]
	global_load_dwordx4 v[18:21], v[18:19], off
	v_pk_fma_f32 v[110:111], v[112:113], v[112:113], v[110:111]
	global_load_dwordx4 v[22:25], v[22:23], off
	v_add_f32_e32 v110, v110, v114
	v_add_f32_e32 v116, v111, v110
	v_lshlrev_b32_e32 v111, 16, v109
	v_lshlrev_b32_e32 v110, 16, v108
	v_and_b32_e32 v109, 0xffff0000, v109
	v_and_b32_e32 v108, 0xffff0000, v108
	v_pk_mul_f32 v[114:115], v[108:109], v[108:109]
	global_load_dwordx4 v[26:29], v[26:27], off
	v_pk_fma_f32 v[114:115], v[110:111], v[110:111], v[114:115]
	global_load_dwordx4 v[30:33], v[30:31], off
	v_add_f32_e32 v114, v114, v116
	v_add_f32_e32 v114, v115, v114
	v_add_f32_e32 v98, v98, v114
	v_lshlrev_b32_e32 v116, 16, v134
	v_and_b32_e32 v115, 0xffff0000, v135
	v_and_b32_e32 v114, 0xffff0000, v134
	global_load_dwordx4 v[132:135], v[162:163], off offset:16
	global_load_dwordx4 v[136:139], v[162:163], off
	v_add_f32_e32 v125, v99, v98
	v_pk_mul_f32 v[98:99], v[114:115], v[114:115]
	s_nop 0
	v_pk_fma_f32 v[98:99], v[116:117], v[116:117], v[98:99]
	s_nop 0
	v_add_f32_e32 v98, v98, v125
	v_add_f32_e32 v98, v99, v98
	ds_bpermute_b32 v99, v185, v98
	s_waitcnt lgkmcnt(0)
	v_add_f32_e32 v98, v98, v99
	ds_bpermute_b32 v99, v194, v98
	s_waitcnt lgkmcnt(0)
	v_add_f32_e32 v98, v98, v99
	v_fmamk_f32 v98, v98, 0x3c000000, v222
	v_cmp_gt_f32_e32 vcc, s49, v98
	v_mul_f32_e32 v99, 0x4b800000, v98
	s_nop 0
	v_cndmask_b32_e32 v98, v98, v99, vcc
	v_rsq_f32_e32 v98, v98
	s_nop 0
	v_mul_f32_e32 v99, 0x45800000, v98
	v_cndmask_b32_e32 v98, v98, v99, vcc
	v_mul_f32_e32 v125, 0x3e0293ee, v98
	v_mul_f32_e32 v98, v125, v131
	v_mul_f32_e32 v99, v125, v127
	v_mul_f32_e32 v100, v125, v100
	v_mul_f32_e32 v101, v125, v101
	v_mul_f32_e32 v126, v125, v126
	v_mul_f32_e32 v102, v125, v102
	v_mul_f32_e32 v0, v125, v0
	v_mul_f32_e32 v103, v125, v103
	v_mul_f32_e32 v104, v125, v104
	v_mul_f32_e32 v105, v125, v105
	v_mul_f32_e32 v106, v125, v106
	v_mul_f32_e32 v107, v125, v107
	v_mul_f32_e32 v108, v125, v108
	v_mul_f32_e32 v109, v125, v109
	s_waitcnt vmcnt(1)
	v_mul_f32_e32 v101, v133, v101
	s_waitcnt vmcnt(0)
	v_mul_f32_e32 v98, v136, v98
	v_mul_f32_e32 v99, v137, v99
	v_cvt_pk_bf16_f32 v98, v98, v99
	v_mul_f32_e32 v99, v125, v128
	v_mul_f32_e32 v99, v138, v99
	v_mul_f32_e32 v100, v139, v100
	v_cvt_pk_bf16_f32 v99, v99, v100
	v_mul_f32_e32 v100, v125, v129
	v_mul_f32_e32 v100, v132, v100
	v_cvt_pk_bf16_f32 v100, v100, v101
	v_mul_f32_e32 v101, v125, v130
	v_mul_f32_e32 v101, v134, v101
	v_mul_f32_e32 v126, v135, v126
	v_cvt_pk_bf16_f32 v101, v101, v126
	global_load_dwordx4 v[126:129], v[162:163], off offset:144
	global_load_dwordx4 v[130:133], v[162:163], off offset:128
	s_waitcnt vmcnt(1)
	v_mul_f32_e32 v104, v127, v104
	s_waitcnt vmcnt(0)
	v_mul_f32_e32 v102, v130, v102
	v_mul_f32_e32 v0, v131, v0
	v_cvt_pk_bf16_f32 v102, v102, v0
	v_mul_f32_e32 v0, v125, v122
	v_mul_f32_e32 v0, v132, v0
	v_mul_f32_e32 v103, v133, v103
	v_cvt_pk_bf16_f32 v103, v0, v103
	v_mul_f32_e32 v0, v125, v123
	v_mul_f32_e32 v0, v126, v0
	v_cvt_pk_bf16_f32 v104, v0, v104
	v_mul_f32_e32 v0, v125, v124
	v_mul_f32_e32 v0, v128, v0
	v_mul_f32_e32 v105, v129, v105
	global_load_dwordx4 v[126:129], v[162:163], off offset:272
	global_load_dwordx4 v[130:133], v[162:163], off offset:256
	v_cvt_pk_bf16_f32 v105, v0, v105
	v_mul_f32_e32 v0, v125, v112
	s_waitcnt vmcnt(1)
	v_mul_f32_e32 v108, v127, v108
	s_waitcnt vmcnt(0)
	v_mul_f32_e32 v0, v130, v0
	v_mul_f32_e32 v106, v131, v106
	v_cvt_pk_bf16_f32 v106, v0, v106
	v_mul_f32_e32 v0, v125, v113
	v_mul_f32_e32 v0, v132, v0
	v_mul_f32_e32 v107, v133, v107
	v_cvt_pk_bf16_f32 v107, v0, v107
	v_mul_f32_e32 v0, v125, v110
	v_mul_f32_e32 v0, v126, v0
	v_cvt_pk_bf16_f32 v108, v0, v108
	v_mul_f32_e32 v0, v125, v111
	v_mul_f32_e32 v0, v128, v0
	v_mul_f32_e32 v109, v129, v109
	global_load_dwordx4 v[126:129], v[162:163], off offset:400
	global_load_dwordx4 v[110:113], v[162:163], off offset:384
	v_cvt_pk_bf16_f32 v109, v0, v109
	v_mul_f32_e32 v0, v125, v120
	ds_write_b128 v198, v[66:69]
	ds_write_b128 v198, v[70:73] offset:1088
	ds_write_b128 v198, v[74:77] offset:2176
	ds_write_b128 v198, v[78:81] offset:3264
	ds_write_b128 v198, v[82:85] offset:4352
	ds_write_b128 v198, v[86:89] offset:5440
	ds_write_b128 v198, v[90:93] offset:6528
	ds_write_b128 v198, v[94:97] offset:7616
	s_waitcnt vmcnt(0)
	v_mul_f32_e32 v0, v110, v0
	v_mul_f32_e32 v110, v125, v118
	v_mul_f32_e32 v110, v111, v110
	v_cvt_pk_bf16_f32 v110, v0, v110
	v_mul_f32_e32 v0, v125, v121
	v_mul_f32_e32 v111, v125, v119
	v_mul_f32_e32 v0, v112, v0
	v_mul_f32_e32 v111, v113, v111
	v_cvt_pk_bf16_f32 v111, v0, v111
	v_mul_f32_e32 v0, v125, v116
	v_mul_f32_e32 v112, v125, v114
	v_mul_f32_e32 v0, v126, v0
	v_mul_f32_e32 v112, v127, v112
	v_cvt_pk_bf16_f32 v112, v0, v112
	v_mul_f32_e32 v0, v125, v117
	v_mul_f32_e32 v113, v125, v115
	v_mul_f32_e32 v0, v128, v0
	v_mul_f32_e32 v113, v129, v113
	ds_read_b128 v[138:141], v199
	ds_read_b128 v[142:145], v199 offset:64
	ds_read_b128 v[146:149], v199 offset:128
	ds_read_b128 v[150:153], v199 offset:192
	ds_read_b128 v[134:137], v199 offset:4352
	ds_read_b128 v[130:133], v199 offset:4416
	ds_read_b128 v[122:125], v199 offset:4480
	ds_read_b128 v[118:121], v199 offset:4544
	ds_read_b128 v[126:129], v165 offset:1024
	ds_read_b128 v[114:117], v165 offset:1088
	ds_read_b128 v[76:79], v167 offset:4480
	ds_read_b128 v[92:95], v167 offset:4496
	v_cvt_pk_bf16_f32 v113, v0, v113
	s_waitcnt lgkmcnt(1)
; #define LAS __attribute__((address_space(3)))
; #define GAS __attribute__((address_space(1)))
; __device__ __forceinline__ f32x4 mfma16(bf16x8 a, bf16x8 b, f32x4 c) { return __builtin_amdgcn_mfma_f32_16x16x32_bf16(a, b, c, 0, 0, 0); }
; __device__ __forceinline__ void att_core(LAS unsigned char* Vst, const LAS float* listr, const LAS unsigned* listT, const bf16* P, const bf16* AKVb, bf16* ACAT, const float* aqg, size_t tok, int cnt, int lane) {
;     ...
;     for (int st = 0; st < 8; ++st) {
; #pragma unroll
;         for (int i = 0; i < 8; ++i) *(LAS u32x4*)(Vst + (4 * i + fq) * 272 + fr * 16) = kb[st % 3][i];
;         __builtin_amdgcn_fence(__ATOMIC_RELEASE, "wavefront"); __builtin_amdgcn_wave_barrier();
;         bf16x8 Kf[2][4];
; #pragma unroll
;         for (int gg = 0; gg < 2; ++gg)
; #pragma unroll
;             for (int kk = 0; kk < 4; ++kk) Kf[gg][kk] = *(const LAS bf16x8*)(Vst + (16 * gg + fr) * 272 + kk * 64 + fq * 16);
;         const f32x4 lr0 = *(const LAS f32x4*)(listr + 32 * st + 4 * fq), lr1 = *(const LAS f32x4*)(listr + 32 * st + 16 + 4 * fq);
;         if (st + 3 < 8) {
;             const u32x4 o0 = *(const LAS u32x4*)(lt + (st + 3) * 32), o1 = *(const LAS u32x4*)(lt + (st + 3) * 32 + 4);
; #pragma unroll
;             for (int i = 0; i < 8; ++i) kb[st % 3][i] = *(const GAS u32x4*)(kbase + (i < 4 ? o0[i & 3] : o1[i & 3]));
;         }
;         __builtin_amdgcn_sched_barrier(0);
; #pragma unroll
;         for (int gg = 0; gg < 2; ++gg) {
;             const int g = 2 * st + gg;
;             f32x4 a = (f32x4){0.f, 0.f, 0.f, 0.f};
; #pragma unroll
;             for (int kk = 0; kk < 4; ++kk) a = mfma16(Kf[gg][kk], Qf[kk], a);
;             const f32x4 lr = gg ? lr1 : lr0;
; #pragma unroll
;             for (int r = 0; r < 4; ++r) lg[g][r] = (16 * g + 4 * fq + r < cnt) ? a[r] * lr[r] : -INFINITY;
;             mx = fmaxf(mx, fmaxf(fmaxf(lg[g][0], lg[g][1]), fmaxf(lg[g][2], lg[g][3])));
;         }
	v_mov_b32_e32 v0, v76
	v_lshl_add_u64 v[66:67], v[160:161], 0, v[0:1]
	v_mov_b32_e32 v0, v77
	v_lshl_add_u64 v[70:71], v[160:161], 0, v[0:1]
	v_mov_b32_e32 v0, v78
	v_lshl_add_u64 v[74:75], v[160:161], 0, v[0:1]
	v_mov_b32_e32 v0, v79
	v_lshl_add_u64 v[78:79], v[160:161], 0, v[0:1]
	s_waitcnt lgkmcnt(0)
	v_mov_b32_e32 v0, v92
	v_lshl_add_u64 v[82:83], v[160:161], 0, v[0:1]
	v_mov_b32_e32 v0, v93
	v_lshl_add_u64 v[86:87], v[160:161], 0, v[0:1]
	v_mov_b32_e32 v0, v94
	v_lshl_add_u64 v[90:91], v[160:161], 0, v[0:1]
	v_mov_b32_e32 v0, v95
	v_lshl_add_u64 v[94:95], v[160:161], 0, v[0:1]
	global_load_dwordx4 v[66:69], v[66:67], off
	s_nop 0
	global_load_dwordx4 v[70:73], v[70:71], off
	s_nop 0
	global_load_dwordx4 v[74:77], v[74:75], off
	s_nop 0
	global_load_dwordx4 v[78:81], v[78:79], off
	s_nop 0
	global_load_dwordx4 v[82:85], v[82:83], off
	s_nop 0
	global_load_dwordx4 v[86:89], v[86:87], off
	s_nop 0
	global_load_dwordx4 v[90:93], v[90:91], off
	s_nop 0
	global_load_dwordx4 v[94:97], v[94:95], off
	v_mfma_f32_16x16x32_bf16 v[138:141], v[138:141], v[98:101], 0
	v_readlane_b32 s42, v254, 47
	v_readlane_b32 s43, v254, 48
	s_mov_b32 s33, 0xff800000
	v_mfma_f32_16x16x32_bf16 v[138:141], v[142:145], v[102:105], v[138:141]
	v_mfma_f32_16x16x32_bf16 v[138:141], v[146:149], v[106:109], v[138:141]
	v_mfma_f32_16x16x32_bf16 v[134:137], v[134:137], v[98:101], 0
	v_mfma_f32_16x16x32_bf16 v[138:141], v[150:153], v[110:113], v[138:141]
	v_mfma_f32_16x16x32_bf16 v[130:133], v[130:133], v[102:105], v[134:137]
	v_mfma_f32_16x16x32_bf16 v[130:133], v[122:125], v[106:109], v[130:133]
	s_nop 5
	v_mul_f32_e32 v0, v126, v138
	v_cndmask_b32_e64 v126, v231, v0, s[42:43]
	v_readlane_b32 s42, v254, 49
	v_mul_f32_e32 v0, v127, v139
	v_readlane_b32 s43, v254, 50
	v_mfma_f32_16x16x32_bf16 v[118:121], v[118:121], v[110:113], v[130:133]
	s_nop 0
	v_cndmask_b32_e64 v127, v231, v0, s[42:43]
	v_readlane_b32 s42, v254, 51
	v_mul_f32_e32 v0, v128, v140
	v_readlane_b32 s43, v254, 52
	s_nop 2
	v_mul_f32_e32 v114, v114, v118
	v_mul_f32_e32 v115, v115, v119
	v_cndmask_b32_e64 v128, v231, v0, s[42:43]
	v_readlane_b32 s42, v254, 53
	v_mul_f32_e32 v0, v129, v141
	v_readlane_b32 s43, v254, 54
	v_mul_f32_e32 v116, v116, v120
	v_mul_f32_e32 v117, v117, v121
	v_cndmask_b32_e64 v122, v231, v0, s[42:43]
	v_readlane_b32 s42, v254, 55
	v_readlane_b32 s43, v254, 56
	v_max_f32_e32 v0, v128, v122
	v_max3_f32 v0, v126, v127, v0
	v_cndmask_b32_e64 v114, v231, v114, s[42:43]
	v_readlane_b32 s42, v254, 57
	v_readlane_b32 s43, v254, 58
	s_nop 1
	v_cndmask_b32_e64 v115, v231, v115, s[42:43]
	v_readlane_b32 s42, v254, 59
	v_readlane_b32 s43, v254, 60
	s_nop 1
	v_cndmask_b32_e64 v116, v231, v116, s[42:43]
	v_readlane_b32 s42, v254, 61
	v_readlane_b32 s43, v254, 62
	s_nop 1
	v_cndmask_b32_e64 v117, v231, v117, s[42:43]
	v_max_f32_e32 v118, v116, v117
	v_max3_f32 v118, v114, v115, v118
	v_max3_f32 v169, v0, s33, v118
	ds_write_b128 v198, v[34:37]
	ds_write_b128 v198, v[38:41] offset:1088
	ds_write_b128 v198, v[42:45] offset:2176
	ds_write_b128 v198, v[46:49] offset:3264
	ds_write_b128 v198, v[50:53] offset:4352
	ds_write_b128 v198, v[54:57] offset:5440
	ds_write_b128 v198, v[58:61] offset:6528
	ds_write_b128 v198, v[62:65] offset:7616
	ds_read_b128 v[40:43], v167 offset:4608
	ds_read_b128 v[56:59], v167 offset:4624
	s_waitcnt lgkmcnt(1)
	v_mov_b32_e32 v0, v40
	v_lshl_add_u64 v[34:35], v[160:161], 0, v[0:1]
	v_mov_b32_e32 v0, v41
	v_lshl_add_u64 v[38:39], v[160:161], 0, v[0:1]
	v_mov_b32_e32 v0, v42
	v_lshl_add_u64 v[44:45], v[160:161], 0, v[0:1]
	v_mov_b32_e32 v0, v43
	v_lshl_add_u64 v[46:47], v[160:161], 0, v[0:1]
	s_waitcnt lgkmcnt(0)
	v_mov_b32_e32 v0, v56
	v_lshl_add_u64 v[50:51], v[160:161], 0, v[0:1]
	v_mov_b32_e32 v0, v57
	v_lshl_add_u64 v[54:55], v[160:161], 0, v[0:1]
	v_mov_b32_e32 v0, v58
	v_lshl_add_u64 v[60:61], v[160:161], 0, v[0:1]
	v_mov_b32_e32 v0, v59
	v_lshl_add_u64 v[62:63], v[160:161], 0, v[0:1]
	global_load_dwordx4 v[34:37], v[34:35], off
	s_nop 0
	global_load_dwordx4 v[38:41], v[38:39], off
	s_nop 0
	global_load_dwordx4 v[42:45], v[44:45], off
	s_nop 0
	global_load_dwordx4 v[46:49], v[46:47], off
	s_nop 0
	global_load_dwordx4 v[50:53], v[50:51], off
	s_nop 0
	global_load_dwordx4 v[54:57], v[54:55], off
	s_nop 0
	global_load_dwordx4 v[58:61], v[60:61], off
	s_nop 0
	global_load_dwordx4 v[62:65], v[62:63], off
	ds_read_b128 v[118:121], v199
	ds_read_b128 v[130:133], v199 offset:64
	ds_read_b128 v[134:137], v199 offset:128
	ds_read_b128 v[138:141], v199 offset:192
	ds_read_b128 v[142:145], v199 offset:4352
	ds_read_b128 v[146:149], v199 offset:4416
	ds_read_b128 v[150:153], v199 offset:4480
	ds_read_b128 v[210:213], v199 offset:4544
	ds_read_b128 v[214:217], v165 offset:1152
	ds_read_b128 v[232:235], v165 offset:1216
	s_waitcnt lgkmcnt(9)
	v_mfma_f32_16x16x32_bf16 v[118:121], v[118:121], v[98:101], 0
	v_readlane_b32 s42, v254, 63
	v_readlane_b32 s43, v252, 0
	s_waitcnt lgkmcnt(8)
	v_mfma_f32_16x16x32_bf16 v[118:121], v[130:133], v[102:105], v[118:121]
	s_waitcnt lgkmcnt(7)
	v_mfma_f32_16x16x32_bf16 v[118:121], v[134:137], v[106:109], v[118:121]
	s_waitcnt lgkmcnt(5)
	v_mfma_f32_16x16x32_bf16 v[130:133], v[142:145], v[98:101], 0
	v_mfma_f32_16x16x32_bf16 v[118:121], v[138:141], v[110:113], v[118:121]
	s_waitcnt lgkmcnt(4)
	v_mfma_f32_16x16x32_bf16 v[130:133], v[146:149], v[102:105], v[130:133]
	s_waitcnt lgkmcnt(3)
	v_mfma_f32_16x16x32_bf16 v[130:133], v[150:153], v[106:109], v[130:133]
	s_waitcnt lgkmcnt(1)
; #define LAS __attribute__((address_space(3)))
; #define GAS __attribute__((address_space(1)))
; __device__ __forceinline__ f32x4 mfma16(bf16x8 a, bf16x8 b, f32x4 c) { return __builtin_amdgcn_mfma_f32_16x16x32_bf16(a, b, c, 0, 0, 0); }
; __device__ __forceinline__ void att_core(LAS unsigned char* Vst, const LAS float* listr, const LAS unsigned* listT, const bf16* P, const bf16* AKVb, bf16* ACAT, const float* aqg, size_t tok, int cnt, int lane) {
;     ...
;     for (int st = 0; st < 8; ++st) {
; #pragma unroll
;         for (int i = 0; i < 8; ++i) *(LAS u32x4*)(Vst + (4 * i + fq) * 272 + fr * 16) = kb[st % 3][i];
;         __builtin_amdgcn_fence(__ATOMIC_RELEASE, "wavefront"); __builtin_amdgcn_wave_barrier();
;         bf16x8 Kf[2][4];
; #pragma unroll
;         for (int gg = 0; gg < 2; ++gg)
; #pragma unroll
;             for (int kk = 0; kk < 4; ++kk) Kf[gg][kk] = *(const LAS bf16x8*)(Vst + (16 * gg + fr) * 272 + kk * 64 + fq * 16);
;         const f32x4 lr0 = *(const LAS f32x4*)(listr + 32 * st + 4 * fq), lr1 = *(const LAS f32x4*)(listr + 32 * st + 16 + 4 * fq);
;         if (st + 3 < 8) {
;             const u32x4 o0 = *(const LAS u32x4*)(lt + (st + 3) * 32), o1 = *(const LAS u32x4*)(lt + (st + 3) * 32 + 4);
; #pragma unroll
;             for (int i = 0; i < 8; ++i) kb[st % 3][i] = *(const GAS u32x4*)(kbase + (i < 4 ? o0[i & 3] : o1[i & 3]));
;         }
;         __builtin_amdgcn_sched_barrier(0);
; #pragma unroll
;         for (int gg = 0; gg < 2; ++gg) {
;             const int g = 2 * st + gg;
;             f32x4 a = (f32x4){0.f, 0.f, 0.f, 0.f};
; #pragma unroll
;             for (int kk = 0; kk < 4; ++kk) a = mfma16(Kf[gg][kk], Qf[kk], a);
;             const f32x4 lr = gg ? lr1 : lr0;
; #pragma unroll
;             for (int r = 0; r < 4; ++r) lg[g][r] = (16 * g + 4 * fq + r < cnt) ? a[r] * lr[r] : -INFINITY;
;             mx = fmaxf(mx, fmaxf(fmaxf(lg[g][0], lg[g][1]), fmaxf(lg[g][2], lg[g][3])));
;         }
	s_nop 2
	v_mul_f32_e32 v0, v214, v118
	v_cndmask_b32_e64 v118, v231, v0, s[42:43]
	v_readlane_b32 s42, v252, 1
	v_mul_f32_e32 v0, v215, v119
	v_readlane_b32 s43, v252, 2
	v_mfma_f32_16x16x32_bf16 v[130:133], v[210:213], v[110:113], v[130:133]
	s_nop 0
	v_cndmask_b32_e64 v119, v231, v0, s[42:43]
	v_readlane_b32 s42, v252, 3
	v_mul_f32_e32 v0, v216, v120
	v_readlane_b32 s43, v252, 4
	s_waitcnt lgkmcnt(0)
	s_nop 1
	v_mul_f32_e32 v123, v232, v130
	v_mul_f32_e32 v124, v233, v131
	v_cndmask_b32_e64 v120, v231, v0, s[42:43]
	v_readlane_b32 s42, v252, 5
	v_mul_f32_e32 v0, v217, v121
	v_readlane_b32 s43, v252, 6
	v_mul_f32_e32 v125, v234, v132
	v_mul_f32_e32 v129, v235, v133
	v_cndmask_b32_e64 v121, v231, v0, s[42:43]
	v_readlane_b32 s42, v252, 7
	v_readlane_b32 s43, v252, 8
	v_max_f32_e32 v0, v120, v121
	v_max3_f32 v0, v118, v119, v0
	v_cndmask_b32_e64 v123, v231, v123, s[42:43]
	v_readlane_b32 s42, v252, 9
	v_readlane_b32 s43, v252, 10
	s_nop 1
	v_cndmask_b32_e64 v124, v231, v124, s[42:43]
	v_readlane_b32 s42, v252, 11
	v_readlane_b32 s43, v252, 12
	s_nop 1
	v_cndmask_b32_e64 v125, v231, v125, s[42:43]
	v_readlane_b32 s42, v252, 13
	v_readlane_b32 s43, v252, 14
	s_nop 1
	v_cndmask_b32_e64 v129, v231, v129, s[42:43]
	v_max_f32_e32 v130, v125, v129
	v_max3_f32 v130, v123, v124, v130
	v_max3_f32 v169, v169, v0, v130
	ds_write_b128 v198, v[2:5]
	ds_write_b128 v198, v[6:9] offset:1088
	ds_write_b128 v198, v[10:13] offset:2176
	ds_write_b128 v198, v[14:17] offset:3264
	ds_write_b128 v198, v[18:21] offset:4352
	ds_write_b128 v198, v[22:25] offset:5440
	ds_write_b128 v198, v[26:29] offset:6528
	ds_write_b128 v198, v[30:33] offset:7616
	ds_read_b128 v[8:11], v167 offset:4736
	ds_read_b128 v[24:27], v167 offset:4752
	s_waitcnt lgkmcnt(1)
	v_mov_b32_e32 v0, v8
	v_lshl_add_u64 v[2:3], v[160:161], 0, v[0:1]
	v_mov_b32_e32 v0, v9
	v_lshl_add_u64 v[6:7], v[160:161], 0, v[0:1]
	v_mov_b32_e32 v0, v10
	v_lshl_add_u64 v[12:13], v[160:161], 0, v[0:1]
	v_mov_b32_e32 v0, v11
	v_lshl_add_u64 v[14:15], v[160:161], 0, v[0:1]
	s_waitcnt lgkmcnt(0)
	v_mov_b32_e32 v0, v24
	v_lshl_add_u64 v[18:19], v[160:161], 0, v[0:1]
	v_mov_b32_e32 v0, v25
	v_lshl_add_u64 v[22:23], v[160:161], 0, v[0:1]
	v_mov_b32_e32 v0, v26
	v_lshl_add_u64 v[28:29], v[160:161], 0, v[0:1]
	v_mov_b32_e32 v0, v27
	v_lshl_add_u64 v[30:31], v[160:161], 0, v[0:1]
	global_load_dwordx4 v[2:5], v[2:3], off
	s_nop 0
	global_load_dwordx4 v[6:9], v[6:7], off
	s_nop 0
	global_load_dwordx4 v[10:13], v[12:13], off
	s_nop 0
	global_load_dwordx4 v[14:17], v[14:15], off
	s_nop 0
	global_load_dwordx4 v[18:21], v[18:19], off
	s_nop 0
	global_load_dwordx4 v[22:25], v[22:23], off
	s_nop 0
	global_load_dwordx4 v[26:29], v[28:29], off
	s_nop 0
	global_load_dwordx4 v[30:33], v[30:31], off
	ds_read_b128 v[130:133], v199
	ds_read_b128 v[134:137], v199 offset:64
	ds_read_b128 v[138:141], v199 offset:128
	ds_read_b128 v[142:145], v199 offset:192
	ds_read_b128 v[146:149], v199 offset:4352
	ds_read_b128 v[150:153], v199 offset:4416
	ds_read_b128 v[210:213], v199 offset:4480
	ds_read_b128 v[214:217], v199 offset:4544
	ds_read_b128 v[232:235], v165 offset:1280
	ds_read_b128 v[236:239], v165 offset:1344
	s_waitcnt lgkmcnt(9)
	v_mfma_f32_16x16x32_bf16 v[130:133], v[130:133], v[98:101], 0
	v_readlane_b32 s42, v252, 15
	v_readlane_b32 s43, v252, 16
	s_waitcnt lgkmcnt(8)
	v_mfma_f32_16x16x32_bf16 v[130:133], v[134:137], v[102:105], v[130:133]
	s_waitcnt lgkmcnt(7)
	v_mfma_f32_16x16x32_bf16 v[130:133], v[138:141], v[106:109], v[130:133]
	s_waitcnt lgkmcnt(5)
	v_mfma_f32_16x16x32_bf16 v[138:141], v[146:149], v[98:101], 0
	v_mfma_f32_16x16x32_bf16 v[134:137], v[142:145], v[110:113], v[130:133]
	s_waitcnt lgkmcnt(4)
	v_mfma_f32_16x16x32_bf16 v[138:141], v[150:153], v[102:105], v[138:141]
	s_waitcnt lgkmcnt(3)
	v_mfma_f32_16x16x32_bf16 v[138:141], v[210:213], v[106:109], v[138:141]
	s_waitcnt lgkmcnt(1)
	s_nop 2
	v_mul_f32_e32 v0, v232, v134
	v_cndmask_b32_e64 v132, v231, v0, s[42:43]
	v_readlane_b32 s42, v252, 17
	v_mul_f32_e32 v0, v233, v135
	v_readlane_b32 s43, v252, 18
	v_mfma_f32_16x16x32_bf16 v[138:141], v[214:217], v[110:113], v[138:141]
	s_nop 0
	v_cndmask_b32_e64 v133, v231, v0, s[42:43]
	v_readlane_b32 s42, v252, 19
	v_mul_f32_e32 v0, v234, v136
	v_readlane_b32 s43, v252, 20
	s_waitcnt lgkmcnt(0)
	s_nop 1
	v_mul_f32_e32 v130, v236, v138
	v_cndmask_b32_e64 v135, v231, v0, s[42:43]
	v_readlane_b32 s42, v252, 21
	v_mul_f32_e32 v0, v235, v137
	v_readlane_b32 s43, v252, 22
	s_nop 1
	v_cndmask_b32_e64 v136, v231, v0, s[42:43]
	v_readlane_b32 s42, v252, 23
	v_readlane_b32 s43, v252, 24
	v_max_f32_e32 v0, v135, v136
	v_max3_f32 v0, v132, v133, v0
	v_cndmask_b32_e64 v137, v231, v130, s[42:43]
	v_mul_f32_e32 v130, v237, v139
	v_cndmask_b32_e64 v134, v231, v130, s[50:51]
	v_mul_f32_e32 v130, v238, v140
	v_cndmask_b32_e64 v131, v231, v130, s[52:53]
	v_mul_f32_e32 v130, v239, v141
	v_cndmask_b32_e64 v130, v231, v130, s[54:55]
	v_max_f32_e32 v138, v131, v130
	v_max3_f32 v138, v137, v134, v138
	v_max3_f32 v175, v169, v0, v138
	s_waitcnt vmcnt(23)
	ds_write_b128 v198, v[66:69]
	s_waitcnt vmcnt(22)
	ds_write_b128 v198, v[70:73] offset:1088
	s_waitcnt vmcnt(21)
	ds_write_b128 v198, v[74:77] offset:2176
	s_waitcnt vmcnt(20)
	ds_write_b128 v198, v[78:81] offset:3264
	s_waitcnt vmcnt(19)
	ds_write_b128 v198, v[82:85] offset:4352
	s_waitcnt vmcnt(18)
	ds_write_b128 v198, v[86:89] offset:5440
	s_waitcnt vmcnt(17)
	ds_write_b128 v198, v[90:93] offset:6528
	s_waitcnt vmcnt(16)
	ds_write_b128 v198, v[94:97] offset:7616
	ds_read_b128 v[66:69], v167 offset:4864
	ds_read_b128 v[70:73], v167 offset:4880
	s_waitcnt lgkmcnt(1)
; #define LAS __attribute__((address_space(3)))
; #define GAS __attribute__((address_space(1)))
; __device__ __forceinline__ f32x4 mfma16(bf16x8 a, bf16x8 b, f32x4 c) { return __builtin_amdgcn_mfma_f32_16x16x32_bf16(a, b, c, 0, 0, 0); }
; __device__ __forceinline__ void att_core(LAS unsigned char* Vst, const LAS float* listr, const LAS unsigned* listT, const bf16* P, const bf16* AKVb, bf16* ACAT, const float* aqg, size_t tok, int cnt, int lane) {
;     ...
;     for (int st = 0; st < 8; ++st) {
; #pragma unroll
;         for (int i = 0; i < 8; ++i) *(LAS u32x4*)(Vst + (4 * i + fq) * 272 + fr * 16) = kb[st % 3][i];
;         __builtin_amdgcn_fence(__ATOMIC_RELEASE, "wavefront"); __builtin_amdgcn_wave_barrier();
;         bf16x8 Kf[2][4];
; #pragma unroll
;         for (int gg = 0; gg < 2; ++gg)
; #pragma unroll
;             for (int kk = 0; kk < 4; ++kk) Kf[gg][kk] = *(const LAS bf16x8*)(Vst + (16 * gg + fr) * 272 + kk * 64 + fq * 16);
;         const f32x4 lr0 = *(const LAS f32x4*)(listr + 32 * st + 4 * fq), lr1 = *(const LAS f32x4*)(listr + 32 * st + 16 + 4 * fq);
;         if (st + 3 < 8) {
;             const u32x4 o0 = *(const LAS u32x4*)(lt + (st + 3) * 32), o1 = *(const LAS u32x4*)(lt + (st + 3) * 32 + 4);
; #pragma unroll
;             for (int i = 0; i < 8; ++i) kb[st % 3][i] = *(const GAS u32x4*)(kbase + (i < 4 ? o0[i & 3] : o1[i & 3]));
;         }
;         __builtin_amdgcn_sched_barrier(0);
; #pragma unroll
;         for (int gg = 0; gg < 2; ++gg) {
;             const int g = 2 * st + gg;
;             f32x4 a = (f32x4){0.f, 0.f, 0.f, 0.f};
; #pragma unroll
;             for (int kk = 0; kk < 4; ++kk) a = mfma16(Kf[gg][kk], Qf[kk], a);
;             const f32x4 lr = gg ? lr1 : lr0;
; #pragma unroll
;             for (int r = 0; r < 4; ++r) lg[g][r] = (16 * g + 4 * fq + r < cnt) ? a[r] * lr[r] : -INFINITY;
;             mx = fmaxf(mx, fmaxf(fmaxf(lg[g][0], lg[g][1]), fmaxf(lg[g][2], lg[g][3])));
;         }
	v_mov_b32_e32 v0, v66
	v_lshl_add_u64 v[74:75], v[160:161], 0, v[0:1]
	v_mov_b32_e32 v0, v67
	v_lshl_add_u64 v[66:67], v[160:161], 0, v[0:1]
	v_mov_b32_e32 v0, v68
	global_load_dwordx4 v[74:77], v[74:75], off
	s_nop 0
	global_load_dwordx4 v[78:81], v[66:67], off
	v_lshl_add_u64 v[66:67], v[160:161], 0, v[0:1]
	v_mov_b32_e32 v0, v69
	v_lshl_add_u64 v[82:83], v[160:161], 0, v[0:1]
	s_waitcnt lgkmcnt(0)
	v_mov_b32_e32 v0, v70
	v_lshl_add_u64 v[86:87], v[160:161], 0, v[0:1]
	v_mov_b32_e32 v0, v71
	v_lshl_add_u64 v[70:71], v[160:161], 0, v[0:1]
	v_mov_b32_e32 v0, v72
	global_load_dwordx4 v[66:69], v[66:67], off
	s_nop 0
	global_load_dwordx4 v[82:85], v[82:83], off
	s_nop 0
	global_load_dwordx4 v[86:89], v[86:87], off
	s_nop 0
	global_load_dwordx4 v[90:93], v[70:71], off
	v_lshl_add_u64 v[70:71], v[160:161], 0, v[0:1]
	v_mov_b32_e32 v0, v73
	v_lshl_add_u64 v[94:95], v[160:161], 0, v[0:1]
	global_load_dwordx4 v[70:73], v[70:71], off
	s_nop 0
	global_load_dwordx4 v[94:97], v[94:95], off
	ds_read_b128 v[138:141], v199
	ds_read_b128 v[142:145], v199 offset:64
	ds_read_b128 v[146:149], v199 offset:128
	ds_read_b128 v[150:153], v199 offset:192
	ds_read_b128 v[210:213], v199 offset:4352
	ds_read_b128 v[214:217], v199 offset:4416
	ds_read_b128 v[232:235], v199 offset:4480
	ds_read_b128 v[236:239], v199 offset:4544
	ds_read_b128 v[240:243], v165 offset:1408
	ds_read_b128 v[244:247], v165 offset:1472
	s_waitcnt lgkmcnt(9)
	v_mfma_f32_16x16x32_bf16 v[138:141], v[138:141], v[98:101], 0
	s_waitcnt lgkmcnt(8)
	v_mfma_f32_16x16x32_bf16 v[138:141], v[142:145], v[102:105], v[138:141]
	s_waitcnt lgkmcnt(7)
	v_mfma_f32_16x16x32_bf16 v[138:141], v[146:149], v[106:109], v[138:141]
	s_waitcnt lgkmcnt(5)
	v_mfma_f32_16x16x32_bf16 v[142:145], v[210:213], v[98:101], 0
	v_mfma_f32_16x16x32_bf16 v[138:141], v[150:153], v[110:113], v[138:141]
	s_waitcnt lgkmcnt(4)
	v_mfma_f32_16x16x32_bf16 v[142:145], v[214:217], v[102:105], v[142:145]
	s_waitcnt lgkmcnt(1)
	s_nop 4
	v_mul_f32_e32 v0, v240, v138
	v_cndmask_b32_e64 v173, v231, v0, s[56:57]
	v_mul_f32_e32 v0, v241, v139
	v_cndmask_b32_e64 v171, v231, v0, s[58:59]
	v_mul_f32_e32 v0, v242, v140
	v_cndmask_b32_e64 v169, v231, v0, s[60:61]
	v_mul_f32_e32 v0, v243, v141
	v_mfma_f32_16x16x32_bf16 v[138:141], v[232:235], v[106:109], v[142:145]
	v_cndmask_b32_e64 v153, v231, v0, s[62:63]
	v_max_f32_e32 v0, v169, v153
	v_max3_f32 v0, v173, v171, v0
	v_mfma_f32_16x16x32_bf16 v[138:141], v[236:239], v[110:113], v[138:141]
	s_waitcnt lgkmcnt(0)
	s_nop 6
	v_mul_f32_e32 v138, v244, v138
	v_cndmask_b32_e64 v152, v231, v138, s[64:65]
	v_mul_f32_e32 v138, v245, v139
	v_cndmask_b32_e64 v151, v231, v138, s[66:67]
	v_mul_f32_e32 v138, v246, v140
	v_cndmask_b32_e64 v150, v231, v138, s[68:69]
	v_mul_f32_e32 v138, v247, v141
	v_cndmask_b32_e64 v149, v231, v138, s[70:71]
	v_max_f32_e32 v138, v150, v149
	v_max3_f32 v138, v152, v151, v138
	v_max3_f32 v146, v175, v0, v138
	s_waitcnt vmcnt(23)
	ds_write_b128 v198, v[34:37]
	s_waitcnt vmcnt(22)
	ds_write_b128 v198, v[38:41] offset:1088
	s_waitcnt vmcnt(21)
	ds_write_b128 v198, v[42:45] offset:2176
	s_waitcnt vmcnt(20)
	ds_write_b128 v198, v[46:49] offset:3264
	s_waitcnt vmcnt(19)
	ds_write_b128 v198, v[50:53] offset:4352
	s_waitcnt vmcnt(18)
	ds_write_b128 v198, v[54:57] offset:5440
	s_waitcnt vmcnt(17)
	ds_write_b128 v198, v[58:61] offset:6528
	s_waitcnt vmcnt(16)
	ds_write_b128 v198, v[62:65] offset:7616
	ds_read_b128 v[34:37], v167 offset:4992
	ds_read_b128 v[38:41], v167 offset:5008
	s_waitcnt lgkmcnt(1)
	v_mov_b32_e32 v0, v34
	v_lshl_add_u64 v[42:43], v[160:161], 0, v[0:1]
	v_mov_b32_e32 v0, v35
	v_lshl_add_u64 v[34:35], v[160:161], 0, v[0:1]
	v_mov_b32_e32 v0, v36
	global_load_dwordx4 v[42:45], v[42:43], off
	s_nop 0
	global_load_dwordx4 v[46:49], v[34:35], off
	v_lshl_add_u64 v[34:35], v[160:161], 0, v[0:1]
	v_mov_b32_e32 v0, v37
	v_lshl_add_u64 v[50:51], v[160:161], 0, v[0:1]
	s_waitcnt lgkmcnt(0)
	v_mov_b32_e32 v0, v38
	v_lshl_add_u64 v[54:55], v[160:161], 0, v[0:1]
	v_mov_b32_e32 v0, v39
	v_lshl_add_u64 v[38:39], v[160:161], 0, v[0:1]
	v_mov_b32_e32 v0, v40
	global_load_dwordx4 v[34:37], v[34:35], off
	s_nop 0
	global_load_dwordx4 v[50:53], v[50:51], off
	s_nop 0
	global_load_dwordx4 v[54:57], v[54:55], off
	s_nop 0
	global_load_dwordx4 v[58:61], v[38:39], off
	v_lshl_add_u64 v[38:39], v[160:161], 0, v[0:1]
	v_mov_b32_e32 v0, v41
	v_lshl_add_u64 v[62:63], v[160:161], 0, v[0:1]
	global_load_dwordx4 v[38:41], v[38:39], off
	s_nop 0
	global_load_dwordx4 v[62:65], v[62:63], off
	ds_read_b128 v[138:141], v199
	ds_read_b128 v[142:145], v199 offset:64
	ds_read_b128 v[210:213], v199 offset:128
	ds_read_b128 v[214:217], v199 offset:192
	ds_read_b128 v[232:235], v199 offset:4352
	ds_read_b128 v[236:239], v199 offset:4416
	ds_read_b128 v[240:243], v199 offset:4480
	ds_read_b128 v[244:247], v199 offset:4544
	ds_read_b128 v[248:251], v165 offset:1536
	ds_read_b128 v[190:193], v165 offset:1600
	s_waitcnt lgkmcnt(9)
	v_mfma_f32_16x16x32_bf16 v[138:141], v[138:141], v[98:101], 0
	s_waitcnt lgkmcnt(8)
	v_mfma_f32_16x16x32_bf16 v[138:141], v[142:145], v[102:105], v[138:141]
	s_waitcnt lgkmcnt(5)
	v_mfma_f32_16x16x32_bf16 v[142:145], v[232:235], v[98:101], 0
	v_mfma_f32_16x16x32_bf16 v[138:141], v[210:213], v[106:109], v[138:141]
	s_waitcnt lgkmcnt(4)
	v_mfma_f32_16x16x32_bf16 v[142:145], v[236:239], v[102:105], v[142:145]
	v_mfma_f32_16x16x32_bf16 v[138:141], v[214:217], v[110:113], v[138:141]
	s_waitcnt lgkmcnt(3)
	v_mfma_f32_16x16x32_bf16 v[142:145], v[240:243], v[106:109], v[142:145]
	s_waitcnt lgkmcnt(1)
; #define LAS __attribute__((address_space(3)))
; #define GAS __attribute__((address_space(1)))
; __device__ __forceinline__ f32x4 mfma16(bf16x8 a, bf16x8 b, f32x4 c) { return __builtin_amdgcn_mfma_f32_16x16x32_bf16(a, b, c, 0, 0, 0); }
; __device__ __forceinline__ void att_core(LAS unsigned char* Vst, const LAS float* listr, const LAS unsigned* listT, const bf16* P, const bf16* AKVb, bf16* ACAT, const float* aqg, size_t tok, int cnt, int lane) {
;     ...
;     for (int st = 0; st < 8; ++st) {
; #pragma unroll
;         for (int i = 0; i < 8; ++i) *(LAS u32x4*)(Vst + (4 * i + fq) * 272 + fr * 16) = kb[st % 3][i];
;         __builtin_amdgcn_fence(__ATOMIC_RELEASE, "wavefront"); __builtin_amdgcn_wave_barrier();
;         bf16x8 Kf[2][4];
; #pragma unroll
;         for (int gg = 0; gg < 2; ++gg)
; #pragma unroll
;             for (int kk = 0; kk < 4; ++kk) Kf[gg][kk] = *(const LAS bf16x8*)(Vst + (16 * gg + fr) * 272 + kk * 64 + fq * 16);
;         const f32x4 lr0 = *(const LAS f32x4*)(listr + 32 * st + 4 * fq), lr1 = *(const LAS f32x4*)(listr + 32 * st + 16 + 4 * fq);
;         if (st + 3 < 8) {
;             const u32x4 o0 = *(const LAS u32x4*)(lt + (st + 3) * 32), o1 = *(const LAS u32x4*)(lt + (st + 3) * 32 + 4);
; #pragma unroll
;             for (int i = 0; i < 8; ++i) kb[st % 3][i] = *(const GAS u32x4*)(kbase + (i < 4 ? o0[i & 3] : o1[i & 3]));
;         }
;         __builtin_amdgcn_sched_barrier(0);
; #pragma unroll
;         for (int gg = 0; gg < 2; ++gg) {
;             const int g = 2 * st + gg;
;             f32x4 a = (f32x4){0.f, 0.f, 0.f, 0.f};
; #pragma unroll
;             for (int kk = 0; kk < 4; ++kk) a = mfma16(Kf[gg][kk], Qf[kk], a);
;             const f32x4 lr = gg ? lr1 : lr0;
; #pragma unroll
;             for (int r = 0; r < 4; ++r) lg[g][r] = (16 * g + 4 * fq + r < cnt) ? a[r] * lr[r] : -INFINITY;
;             mx = fmaxf(mx, fmaxf(fmaxf(lg[g][0], lg[g][1]), fmaxf(lg[g][2], lg[g][3])));
;         }
;         __builtin_amdgcn_fence(__ATOMIC_RELEASE, "wavefront"); __builtin_amdgcn_wave_barrier();
;         __builtin_amdgcn_sched_barrier(0);
;     }
	s_nop 4
	v_mul_f32_e32 v0, v248, v138
	v_cndmask_b32_e64 v211, v231, v0, s[72:73]
	v_mul_f32_e32 v0, v249, v139
	v_cndmask_b32_e64 v212, v231, v0, s[74:75]
	v_mul_f32_e32 v0, v250, v140
	v_cndmask_b32_e64 v210, v231, v0, s[76:77]
	v_mul_f32_e32 v0, v251, v141
	v_mfma_f32_16x16x32_bf16 v[138:141], v[244:247], v[110:113], v[142:145]
	v_cndmask_b32_e64 v209, v231, v0, s[78:79]
	s_waitcnt lgkmcnt(0)
	s_nop 5
	v_mul_f32_e32 v0, v190, v138
	v_cndmask_b32_e64 v181, v231, v0, s[80:81]
	v_mul_f32_e32 v0, v191, v139
	v_cndmask_b32_e64 v179, v231, v0, s[82:83]
	v_mul_f32_e32 v0, v192, v140
	v_cndmask_b32_e64 v177, v231, v0, s[84:85]
	v_mul_f32_e32 v0, v193, v141
	v_cndmask_b32_e64 v175, v231, v0, s[86:87]
	s_waitcnt vmcnt(23)
	ds_write_b128 v198, v[2:5]
	s_waitcnt vmcnt(22)
	ds_write_b128 v198, v[6:9] offset:1088
	s_waitcnt vmcnt(21)
	ds_write_b128 v198, v[10:13] offset:2176
	s_waitcnt vmcnt(20)
	ds_write_b128 v198, v[14:17] offset:3264
	s_waitcnt vmcnt(19)
	ds_write_b128 v198, v[18:21] offset:4352
	s_waitcnt vmcnt(18)
	ds_write_b128 v198, v[22:25] offset:5440
	s_waitcnt vmcnt(17)
	ds_write_b128 v198, v[26:29] offset:6528
	s_waitcnt vmcnt(16)
	ds_write_b128 v198, v[30:33] offset:7616
	ds_read_b128 v[2:5], v165 offset:1728
	ds_read_b128 v[6:9], v165 offset:1664
	ds_read_b128 v[10:13], v199 offset:4544
	ds_read_b128 v[14:17], v199 offset:4480
	ds_read_b128 v[18:21], v199 offset:4416
	ds_read_b128 v[22:25], v199 offset:4352
	ds_read_b128 v[26:29], v199 offset:192
	ds_read_b128 v[30:33], v199 offset:128
	ds_read_b128 v[138:141], v199 offset:64
	ds_read_b128 v[142:145], v199
	s_waitcnt lgkmcnt(0)
	v_mfma_f32_16x16x32_bf16 v[142:145], v[142:145], v[98:101], 0
	v_mfma_f32_16x16x32_bf16 v[138:141], v[138:141], v[102:105], v[142:145]
	v_mfma_f32_16x16x32_bf16 v[22:25], v[22:25], v[98:101], 0
	v_mfma_f32_16x16x32_bf16 v[30:33], v[30:33], v[106:109], v[138:141]
	v_mfma_f32_16x16x32_bf16 v[18:21], v[18:21], v[102:105], v[22:25]
	v_mfma_f32_16x16x32_bf16 v[26:29], v[26:29], v[110:113], v[30:33]
	v_mfma_f32_16x16x32_bf16 v[14:17], v[14:17], v[106:109], v[18:21]
	s_nop 6
	v_mul_f32_e32 v0, v6, v26
	v_cndmask_b32_e64 v190, v231, v0, s[88:89]
	v_mul_f32_e32 v0, v7, v27
	v_cndmask_b32_e64 v191, v231, v0, s[90:91]
	v_mul_f32_e32 v0, v8, v28
	v_cndmask_b32_e64 v192, v231, v0, s[92:93]
	v_mul_f32_e32 v0, v9, v29
	v_mfma_f32_16x16x32_bf16 v[6:9], v[10:13], v[110:113], v[14:17]
	v_cndmask_b32_e64 v193, v231, v0, s[94:95]
	s_nop 6
	v_mul_f32_e32 v0, v2, v6
	v_cndmask_b32_e64 v213, v231, v0, s[96:97]
	v_mul_f32_e32 v0, v3, v7
	v_cndmask_b32_e64 v214, v231, v0, s[4:5]
	v_mul_f32_e32 v0, v4, v8
	v_cndmask_b32_e64 v215, v231, v0, s[0:1]
	v_mul_f32_e32 v0, v5, v9
	v_cndmask_b32_e64 v216, v231, v0, s[2:3]
	s_waitcnt vmcnt(15)
	ds_write_b128 v198, v[74:77]
	s_waitcnt vmcnt(14)
	ds_write_b128 v198, v[78:81] offset:1088
	s_waitcnt vmcnt(13)
	ds_write_b128 v198, v[66:69] offset:2176
	s_waitcnt vmcnt(12)
	ds_write_b128 v198, v[82:85] offset:3264
	s_waitcnt vmcnt(11)
	ds_write_b128 v198, v[86:89] offset:4352
	s_waitcnt vmcnt(10)
	ds_write_b128 v198, v[90:93] offset:5440
	s_waitcnt vmcnt(9)
	ds_write_b128 v198, v[70:73] offset:6528
	s_waitcnt vmcnt(8)
	ds_write_b128 v198, v[94:97] offset:7616
	ds_read_b128 v[2:5], v165 offset:1856
	ds_read_b128 v[6:9], v165 offset:1792
	ds_read_b128 v[10:13], v199 offset:4544
	ds_read_b128 v[14:17], v199 offset:4480
	ds_read_b128 v[18:21], v199 offset:4416
	ds_read_b128 v[22:25], v199 offset:4352
	ds_read_b128 v[26:29], v199 offset:192
	ds_read_b128 v[30:33], v199 offset:128
	ds_read_b128 v[66:69], v199 offset:64
	ds_read_b128 v[70:73], v199
	s_waitcnt lgkmcnt(0)
	v_mfma_f32_16x16x32_bf16 v[70:73], v[70:73], v[98:101], 0
	v_mfma_f32_16x16x32_bf16 v[66:69], v[66:69], v[102:105], v[70:73]
	v_mfma_f32_16x16x32_bf16 v[22:25], v[22:25], v[98:101], 0
	v_mfma_f32_16x16x32_bf16 v[30:33], v[30:33], v[106:109], v[66:69]
	v_mfma_f32_16x16x32_bf16 v[18:21], v[18:21], v[102:105], v[22:25]
	v_mfma_f32_16x16x32_bf16 v[26:29], v[26:29], v[110:113], v[30:33]
	v_mfma_f32_16x16x32_bf16 v[14:17], v[14:17], v[106:109], v[18:21]
	s_nop 6
	v_mul_f32_e32 v0, v6, v26
	v_cndmask_b32_e64 v217, v231, v0, s[6:7]
	v_mul_f32_e32 v0, v7, v27
	v_cndmask_b32_e64 v218, v231, v0, s[8:9]
	v_mul_f32_e32 v0, v8, v28
	v_cndmask_b32_e64 v219, v231, v0, s[10:11]
	v_mul_f32_e32 v0, v9, v29
	v_mfma_f32_16x16x32_bf16 v[6:9], v[10:13], v[110:113], v[14:17]
	v_cndmask_b32_e64 v232, v231, v0, s[12:13]
	s_nop 6
	v_mul_f32_e32 v0, v2, v6
	v_cndmask_b32_e64 v233, v231, v0, s[14:15]
	v_mul_f32_e32 v0, v3, v7
	v_cndmask_b32_e64 v140, v231, v0, s[16:17]
	v_mul_f32_e32 v0, v4, v8
	v_cndmask_b32_e64 v138, v231, v0, s[18:19]
	v_mul_f32_e32 v0, v5, v9
	v_cndmask_b32_e64 v139, v231, v0, s[20:21]
	s_waitcnt vmcnt(7)
	ds_write_b128 v198, v[42:45]
	s_waitcnt vmcnt(6)
	ds_write_b128 v198, v[46:49] offset:1088
	s_waitcnt vmcnt(5)
	ds_write_b128 v198, v[34:37] offset:2176
	s_waitcnt vmcnt(4)
	ds_write_b128 v198, v[50:53] offset:3264
	s_waitcnt vmcnt(3)
	ds_write_b128 v198, v[54:57] offset:4352
	s_waitcnt vmcnt(2)
	ds_write_b128 v198, v[58:61] offset:5440
	s_waitcnt vmcnt(1)
	ds_write_b128 v198, v[38:41] offset:6528
	s_waitcnt vmcnt(0)
	ds_write_b128 v198, v[62:65] offset:7616
	ds_read_b128 v[2:5], v165 offset:1984
	ds_read_b128 v[6:9], v165 offset:1920
	ds_read_b128 v[10:13], v199 offset:4544
	ds_read_b128 v[14:17], v199 offset:4480
	ds_read_b128 v[18:21], v199 offset:4416
	ds_read_b128 v[22:25], v199 offset:4352
	ds_read_b128 v[26:29], v199 offset:192
	ds_read_b128 v[30:33], v199 offset:128
	ds_read_b128 v[34:37], v199 offset:64
	ds_read_b128 v[38:41], v199
	v_max_f32_e32 v0, v210, v209
	v_max_f32_e32 v42, v177, v175
	v_max3_f32 v0, v211, v212, v0
	v_max3_f32 v42, v181, v179, v42
	v_max3_f32 v0, v146, v0, v42
	v_max_f32_e32 v42, v192, v193
	v_max_f32_e32 v43, v215, v216
	v_max3_f32 v42, v190, v191, v42
	v_max3_f32 v43, v213, v214, v43
	v_max3_f32 v0, v0, v42, v43
	v_max_f32_e32 v42, v219, v232
	v_max_f32_e32 v43, v138, v139
	v_max3_f32 v42, v217, v218, v42
	v_max3_f32 v43, v233, v140, v43
	v_max3_f32 v165, v0, v42, v43
	s_waitcnt lgkmcnt(0)
; #define LAS __attribute__((address_space(3)))
; #define GAS __attribute__((address_space(1)))
; __device__ __forceinline__ f32x4 mfma16(bf16x8 a, bf16x8 b, f32x4 c) { return __builtin_amdgcn_mfma_f32_16x16x32_bf16(a, b, c, 0, 0, 0); }
; __device__ __forceinline__ void att_core(LAS unsigned char* Vst, const LAS float* listr, const LAS unsigned* listT, const bf16* P, const bf16* AKVb, bf16* ACAT, const float* aqg, size_t tok, int cnt, int lane) {
;     ...
;             for (int kk = 0; kk < 4; ++kk) a = mfma16(Kf[gg][kk], Qf[kk], a);
;             const f32x4 lr = gg ? lr1 : lr0;
; #pragma unroll
;             for (int r = 0; r < 4; ++r) lg[g][r] = (16 * g + 4 * fq + r < cnt) ? a[r] * lr[r] : -INFINITY;
;             mx = fmaxf(mx, fmaxf(fmaxf(lg[g][0], lg[g][1]), fmaxf(lg[g][2], lg[g][3])));
;         }
;         __builtin_amdgcn_fence(__ATOMIC_RELEASE, "wavefront"); __builtin_amdgcn_wave_barrier();
;         __builtin_amdgcn_sched_barrier(0);
;     }
;     u32x4 vb[3][8];
; #pragma unroll
;     for (int s2 = 0; s2 < 3; ++s2) {
;         const u32x4 o0 = *(const LAS u32x4*)(lt + s2 * 32), o1 = *(const LAS u32x4*)(lt + s2 * 32 + 4);
; #pragma unroll
;         for (int i = 0; i < 8; ++i) vb[s2][i] = *(const GAS u32x4*)(kbase + 256 + (i < 4 ? o0[i & 3] : o1[i & 3]));
;     }
;     mx = fmaxf(mx, __shfl_xor(mx, 16)); mx = fmaxf(mx, __shfl_xor(mx, 32));
	v_mfma_f32_16x16x32_bf16 v[38:41], v[38:41], v[98:101], 0
	v_mfma_f32_16x16x32_bf16 v[34:37], v[34:37], v[102:105], v[38:41]
	v_mfma_f32_16x16x32_bf16 v[30:33], v[30:33], v[106:109], v[34:37]
	v_mfma_f32_16x16x32_bf16 v[22:25], v[22:25], v[98:101], 0
	v_mfma_f32_16x16x32_bf16 v[26:29], v[26:29], v[110:113], v[30:33]
	v_mfma_f32_16x16x32_bf16 v[18:21], v[18:21], v[102:105], v[22:25]
	s_nop 6
	v_mul_f32_e32 v0, v6, v26
	v_cndmask_b32_e64 v141, v231, v0, s[22:23]
	v_mul_f32_e32 v0, v7, v27
	v_cndmask_b32_e64 v142, v231, v0, s[24:25]
	v_mul_f32_e32 v0, v8, v28
	v_cndmask_b32_e64 v143, v231, v0, s[26:27]
	v_mul_f32_e32 v0, v9, v29
	v_mfma_f32_16x16x32_bf16 v[6:9], v[14:17], v[106:109], v[18:21]
	v_cndmask_b32_e64 v148, v231, v0, s[28:29]
	v_max_f32_e32 v0, v143, v148
	v_max3_f32 v28, v141, v142, v0
	v_mfma_f32_16x16x32_bf16 v[6:9], v[10:13], v[110:113], v[6:9]
	s_nop 7
	v_mul_f32_e32 v0, v2, v6
	v_cndmask_b32_e64 v144, v231, v0, s[30:31]
	v_mul_f32_e32 v0, v3, v7
	v_cndmask_b32_e64 v145, v231, v0, s[34:35]
	v_mul_f32_e32 v0, v4, v8
	v_cndmask_b32_e64 v146, v231, v0, s[36:37]
	v_mul_f32_e32 v0, v5, v9
	v_cndmask_b32_e64 v147, v231, v0, s[38:39]
	v_max_f32_e32 v0, v146, v147
	v_max3_f32 v29, v144, v145, v0
	ds_read_b128 v[8:11], v167 offset:4096
	ds_read_b128 v[12:15], v167 offset:4112
	v_max3_f32 v38, v165, v28, v29
	ds_bpermute_b32 v39, v185, v38
	s_waitcnt lgkmcnt(2)
	v_mov_b32_e32 v0, v8
	v_lshl_add_u64 v[2:3], v[160:161], 0, v[0:1]
	v_mov_b32_e32 v0, v9
	v_lshl_add_u64 v[6:7], v[160:161], 0, v[0:1]
	v_mov_b32_e32 v0, v10
	v_lshl_add_u64 v[16:17], v[160:161], 0, v[0:1]
	v_mov_b32_e32 v0, v11
	v_lshl_add_u64 v[10:11], v[160:161], 0, v[0:1]
	s_waitcnt lgkmcnt(1)
	v_mov_b32_e32 v0, v12
	global_load_dwordx4 v[2:5], v[2:3], off offset:256
	s_nop 0
	global_load_dwordx4 v[6:9], v[6:7], off offset:256
	s_nop 0
	global_load_dwordx4 v[42:45], v[16:17], off offset:256
	global_load_dwordx4 v[78:81], v[10:11], off offset:256
	v_lshl_add_u64 v[10:11], v[160:161], 0, v[0:1]
	v_mov_b32_e32 v0, v13
	v_lshl_add_u64 v[12:13], v[160:161], 0, v[0:1]
	global_load_dwordx4 v[82:85], v[10:11], off offset:256
	global_load_dwordx4 v[86:89], v[12:13], off offset:256
	ds_read_b128 v[10:13], v167 offset:4224
	v_mov_b32_e32 v0, v14
	v_lshl_add_u64 v[16:17], v[160:161], 0, v[0:1]
	v_mov_b32_e32 v0, v15
	v_lshl_add_u64 v[14:15], v[160:161], 0, v[0:1]
	global_load_dwordx4 v[90:93], v[16:17], off offset:256
	global_load_dwordx4 v[94:97], v[14:15], off offset:256
	ds_read_b128 v[14:17], v167 offset:4240
	s_waitcnt lgkmcnt(1)
	v_mov_b32_e32 v0, v10
	v_lshl_add_u64 v[18:19], v[160:161], 0, v[0:1]
	v_mov_b32_e32 v0, v11
	v_lshl_add_u64 v[10:11], v[160:161], 0, v[0:1]
	v_mov_b32_e32 v0, v12
	global_load_dwordx4 v[46:49], v[18:19], off offset:256
	global_load_dwordx4 v[50:53], v[10:11], off offset:256
	v_lshl_add_u64 v[10:11], v[160:161], 0, v[0:1]
	v_mov_b32_e32 v0, v13
	v_lshl_add_u64 v[12:13], v[160:161], 0, v[0:1]
	s_waitcnt lgkmcnt(0)
	v_mov_b32_e32 v0, v14
	global_load_dwordx4 v[54:57], v[10:11], off offset:256
	global_load_dwordx4 v[58:61], v[12:13], off offset:256
	v_lshl_add_u64 v[10:11], v[160:161], 0, v[0:1]
	v_mov_b32_e32 v0, v15
	v_lshl_add_u64 v[12:13], v[160:161], 0, v[0:1]
	v_mov_b32_e32 v0, v16
	global_load_dwordx4 v[62:65], v[10:11], off offset:256
	global_load_dwordx4 v[66:69], v[12:13], off offset:256
	v_lshl_add_u64 v[10:11], v[160:161], 0, v[0:1]
	v_mov_b32_e32 v0, v17
	ds_read_b128 v[16:19], v167 offset:4352
	v_lshl_add_u64 v[12:13], v[160:161], 0, v[0:1]
	global_load_dwordx4 v[70:73], v[10:11], off offset:256
	global_load_dwordx4 v[74:77], v[12:13], off offset:256
	ds_read_b128 v[32:35], v167 offset:4368
	s_waitcnt lgkmcnt(1)
	v_mov_b32_e32 v0, v16
	v_lshl_add_u64 v[10:11], v[160:161], 0, v[0:1]
	v_mov_b32_e32 v0, v17
	v_lshl_add_u64 v[14:15], v[160:161], 0, v[0:1]
	v_mov_b32_e32 v0, v18
	v_lshl_add_u64 v[20:21], v[160:161], 0, v[0:1]
	v_mov_b32_e32 v0, v19
	v_lshl_add_u64 v[22:23], v[160:161], 0, v[0:1]
	s_waitcnt lgkmcnt(0)
	v_mov_b32_e32 v0, v32
	v_lshl_add_u64 v[26:27], v[160:161], 0, v[0:1]
	v_mov_b32_e32 v0, v33
	v_lshl_add_u64 v[30:31], v[160:161], 0, v[0:1]
	v_mov_b32_e32 v0, v34
	v_lshl_add_u64 v[36:37], v[160:161], 0, v[0:1]
	v_max_f32_e32 v0, v39, v39
	v_max_f32_e32 v98, v38, v0
	ds_bpermute_b32 v99, v194, v98
	v_mov_b32_e32 v0, v35
	v_lshl_add_u64 v[38:39], v[160:161], 0, v[0:1]
	global_load_dwordx4 v[10:13], v[10:11], off offset:256
	s_nop 0
	global_load_dwordx4 v[14:17], v[14:15], off offset:256
	s_nop 0
	global_load_dwordx4 v[18:21], v[20:21], off offset:256
	s_nop 0
	global_load_dwordx4 v[22:25], v[22:23], off offset:256
	s_waitcnt lgkmcnt(0)
; #define LAS __attribute__((address_space(3)))
; #define GAS __attribute__((address_space(1)))
; __device__ __forceinline__ unsigned pk2(float lo, float hi) { unsigned r; asm("v_cvt_pk_bf16_f32 %0, %1, %2" : "=v"(r) : "v"(lo), "v"(hi)); return r; }
; __device__ __forceinline__ s16x4 ldtr(LAS unsigned char* p) { return __builtin_amdgcn_ds_read_tr16_b64_v4i16((LAS s16x4*)p); }
; __device__ __forceinline__ void att_core(LAS unsigned char* Vst, const LAS float* listr, const LAS unsigned* listT, const bf16* P, const bf16* AKVb, bf16* ACAT, const float* aqg, size_t tok, int cnt, int lane) {
;     ...
;     mx = fmaxf(mx, __shfl_xor(mx, 16)); mx = fmaxf(mx, __shfl_xor(mx, 32));
;     float sum = 0.f;
; #pragma unroll
;     for (int g = 0; g < 16; ++g)
; #pragma unroll
;         for (int r = 0; r < 4; ++r) { const float pz = __builtin_amdgcn_exp2f(lg[g][r] - mx); lg[g][r] = pz; sum += pz; }
;     sum += __shfl_xor(sum, 16); sum += __shfl_xor(sum, 32);
;     bf16x8 Pf[8];
; #pragma unroll
;     for (int G = 0; G < 8; ++G) { u32x4 t; t.x = pk2(lg[2 * G][0], lg[2 * G][1]); t.y = pk2(lg[2 * G][2], lg[2 * G][3]); t.z = pk2(lg[2 * G + 1][0], lg[2 * G + 1][1]); t.w = pk2(lg[2 * G + 1][2], lg[2 * G + 1][3]); Pf[G] = __builtin_bit_cast(bf16x8, t); }
;     f32x4 O[8];
; #pragma unroll
;     for (int nb = 0; nb < 8; ++nb) O[nb] = (f32x4){0.f, 0.f, 0.f, 0.f};
;     const LAS unsigned char* vbse = Vst + (4 * fq + (fr >> 2)) * 288 + (4 * (fr & 3)) * 2;
; #pragma unroll
;     for (int G = 0; G < 8; ++G) {
; #pragma unroll
;         for (int i = 0; i < 8; ++i) *(LAS u32x4*)(Vst + (4 * i + fq) * 288 + fr * 16) = vb[G % 3][i];
;         __builtin_amdgcn_fence(__ATOMIC_RELEASE, "wavefront"); __builtin_amdgcn_wave_barrier();
;         s16x4 tc[2][2], tn[2][2];
; #pragma unroll
;         for (int u = 0; u < 2; ++u) { tc[u][0] = ldtr((LAS unsigned char*)vbse + 32 * u); tc[u][1] = ldtr((LAS unsigned char*)vbse + 16 * 288 + 32 * u); }
;         if (G + 3 < 8) {
;             const u32x4 o0 = *(const LAS u32x4*)(lt + (G + 3) * 32), o1 = *(const LAS u32x4*)(lt + (G + 3) * 32 + 4);
; #pragma unroll
;             for (int i = 0; i < 8; ++i) vb[G % 3][i] = *(const GAS u32x4*)(kbase + 256 + (i < 4 ? o0[i & 3] : o1[i & 3]));
;         }
	v_max_f32_e32 v0, v99, v99
	v_max_f32_e32 v165, v98, v0
	v_sub_f32_e32 v0, v126, v165
	v_exp_f32_e32 v126, v0
	v_sub_f32_e32 v0, v127, v165
	v_exp_f32_e32 v127, v0
	v_sub_f32_e32 v0, v128, v165
	v_exp_f32_e32 v128, v0
	v_sub_f32_e32 v0, v122, v165
	v_exp_f32_e32 v234, v0
	v_sub_f32_e32 v98, v114, v165
	v_add_f32_e32 v0, 0, v126
	v_exp_f32_e32 v235, v98
	v_sub_f32_e32 v98, v115, v165
	v_add_f32_e32 v0, v127, v0
	v_exp_f32_e32 v236, v98
	v_sub_f32_e32 v98, v116, v165
	v_add_f32_e32 v0, v128, v0
	v_exp_f32_e32 v237, v98
	v_sub_f32_e32 v98, v117, v165
	v_add_f32_e32 v0, v234, v0
	v_exp_f32_e32 v238, v98
	v_sub_f32_e32 v98, v118, v165
	v_add_f32_e32 v0, v235, v0
	v_exp_f32_e32 v118, v98
	v_sub_f32_e32 v98, v119, v165
	v_add_f32_e32 v0, v236, v0
	v_exp_f32_e32 v119, v98
	v_sub_f32_e32 v98, v120, v165
	v_add_f32_e32 v0, v237, v0
	v_exp_f32_e32 v120, v98
	v_sub_f32_e32 v98, v121, v165
	v_add_f32_e32 v0, v238, v0
	v_exp_f32_e32 v121, v98
	v_sub_f32_e32 v98, v123, v165
	v_add_f32_e32 v0, v118, v0
	v_exp_f32_e32 v239, v98
	v_sub_f32_e32 v98, v124, v165
	v_add_f32_e32 v0, v119, v0
	v_exp_f32_e32 v240, v98
	v_sub_f32_e32 v98, v125, v165
	v_add_f32_e32 v0, v120, v0
	v_exp_f32_e32 v241, v98
	v_sub_f32_e32 v98, v129, v165
	v_add_f32_e32 v0, v121, v0
	v_exp_f32_e32 v242, v98
	v_sub_f32_e32 v98, v132, v165
	v_add_f32_e32 v0, v239, v0
	v_exp_f32_e32 v132, v98
	v_sub_f32_e32 v98, v133, v165
	v_add_f32_e32 v0, v240, v0
	v_exp_f32_e32 v133, v98
	v_sub_f32_e32 v98, v135, v165
	v_add_f32_e32 v0, v241, v0
	v_exp_f32_e32 v135, v98
	v_sub_f32_e32 v98, v136, v165
	v_add_f32_e32 v0, v242, v0
	v_exp_f32_e32 v136, v98
	v_sub_f32_e32 v98, v137, v165
	v_add_f32_e32 v0, v132, v0
	v_exp_f32_e32 v137, v98
	v_sub_f32_e32 v98, v134, v165
	v_add_f32_e32 v0, v133, v0
	v_exp_f32_e32 v134, v98
	v_sub_f32_e32 v98, v131, v165
	v_add_f32_e32 v0, v135, v0
	v_exp_f32_e32 v243, v98
	v_sub_f32_e32 v98, v130, v165
	v_add_f32_e32 v0, v136, v0
	v_exp_f32_e32 v244, v98
	v_sub_f32_e32 v98, v173, v165
	v_add_f32_e32 v0, v137, v0
	v_exp_f32_e32 v173, v98
	v_sub_f32_e32 v98, v171, v165
	v_add_f32_e32 v0, v134, v0
	v_exp_f32_e32 v171, v98
	v_sub_f32_e32 v98, v169, v165
	v_add_f32_e32 v0, v243, v0
	v_exp_f32_e32 v169, v98
	v_sub_f32_e32 v98, v153, v165
	v_add_f32_e32 v0, v244, v0
	v_exp_f32_e32 v153, v98
	v_sub_f32_e32 v98, v152, v165
	v_add_f32_e32 v0, v173, v0
	v_exp_f32_e32 v152, v98
	v_sub_f32_e32 v98, v151, v165
	v_add_f32_e32 v0, v171, v0
	v_exp_f32_e32 v151, v98
	v_sub_f32_e32 v98, v150, v165
	v_add_f32_e32 v0, v169, v0
	v_exp_f32_e32 v150, v98
	v_sub_f32_e32 v98, v149, v165
	v_add_f32_e32 v0, v153, v0
	v_exp_f32_e32 v149, v98
	v_sub_f32_e32 v98, v211, v165
	v_add_f32_e32 v0, v152, v0
	v_exp_f32_e32 v211, v98
	v_sub_f32_e32 v98, v212, v165
	v_add_f32_e32 v0, v151, v0
	v_exp_f32_e32 v212, v98
	v_sub_f32_e32 v98, v210, v165
	v_add_f32_e32 v0, v150, v0
	v_exp_f32_e32 v210, v98
	v_sub_f32_e32 v98, v209, v165
	v_add_f32_e32 v0, v149, v0
	v_exp_f32_e32 v209, v98
	v_sub_f32_e32 v98, v181, v165
	v_add_f32_e32 v0, v211, v0
	v_exp_f32_e32 v181, v98
	v_sub_f32_e32 v98, v179, v165
	v_add_f32_e32 v0, v212, v0
	v_exp_f32_e32 v179, v98
	v_sub_f32_e32 v98, v177, v165
	v_add_f32_e32 v0, v210, v0
	v_exp_f32_e32 v177, v98
	v_sub_f32_e32 v98, v175, v165
	v_add_f32_e32 v0, v209, v0
	v_exp_f32_e32 v175, v98
	v_sub_f32_e32 v98, v190, v165
	v_add_f32_e32 v0, v181, v0
	v_exp_f32_e32 v190, v98
	v_sub_f32_e32 v98, v191, v165
	v_add_f32_e32 v0, v179, v0
	v_exp_f32_e32 v191, v98
	v_sub_f32_e32 v98, v192, v165
	v_add_f32_e32 v0, v177, v0
	v_exp_f32_e32 v192, v98
	v_sub_f32_e32 v98, v193, v165
	v_add_f32_e32 v0, v175, v0
	v_exp_f32_e32 v193, v98
	v_sub_f32_e32 v98, v213, v165
	v_add_f32_e32 v0, v190, v0
	v_exp_f32_e32 v213, v98
	v_sub_f32_e32 v98, v214, v165
	v_add_f32_e32 v0, v191, v0
	v_exp_f32_e32 v214, v98
	v_sub_f32_e32 v98, v215, v165
	v_add_f32_e32 v0, v192, v0
	v_exp_f32_e32 v215, v98
	v_sub_f32_e32 v98, v216, v165
	v_add_f32_e32 v0, v193, v0
	v_exp_f32_e32 v216, v98
	v_sub_f32_e32 v98, v217, v165
	v_add_f32_e32 v0, v213, v0
	v_exp_f32_e32 v217, v98
	v_sub_f32_e32 v98, v218, v165
	v_add_f32_e32 v0, v214, v0
	v_exp_f32_e32 v218, v98
	v_sub_f32_e32 v98, v219, v165
	v_add_f32_e32 v0, v215, v0
	v_exp_f32_e32 v219, v98
	v_sub_f32_e32 v98, v232, v165
	v_add_f32_e32 v0, v216, v0
	v_exp_f32_e32 v232, v98
	global_load_dwordx4 v[26:29], v[26:27], off offset:256
	s_nop 0
	global_load_dwordx4 v[30:33], v[30:31], off offset:256
	s_nop 0
	global_load_dwordx4 v[34:37], v[36:37], off offset:256
	s_nop 0
	global_load_dwordx4 v[38:41], v[38:39], off offset:256
	v_add_f32_e32 v0, v217, v0
	s_waitcnt vmcnt(23)
	ds_write_b128 v200, v[2:5]
	s_waitcnt vmcnt(22)
	ds_write_b128 v200, v[6:9] offset:1152
	s_waitcnt vmcnt(21)
	ds_write_b128 v200, v[42:45] offset:2304
	s_waitcnt vmcnt(20)
	ds_write_b128 v200, v[78:81] offset:3456
	s_waitcnt vmcnt(19)
	ds_write_b128 v200, v[82:85] offset:4608
	s_waitcnt vmcnt(18)
	ds_write_b128 v200, v[86:89] offset:5760
	s_waitcnt vmcnt(17)
	ds_write_b128 v200, v[90:93] offset:6912
	s_waitcnt vmcnt(16)
	ds_write_b128 v200, v[94:97] offset:8064
	ds_read_b128 v[2:5], v167 offset:4480
	ds_read_b128 v[6:9], v167 offset:4496
	v_add_f32_e32 v0, v218, v0
	v_add_f32_e32 v0, v219, v0
	v_add_f32_e32 v122, v232, v0
	v_sub_f32_e32 v0, v233, v165
	v_exp_f32_e32 v233, v0
	v_sub_f32_e32 v0, v140, v165
	v_exp_f32_e32 v140, v0
	s_waitcnt lgkmcnt(1)
	v_mov_b32_e32 v0, v2
	v_lshl_add_u64 v[42:43], v[160:161], 0, v[0:1]
	v_mov_b32_e32 v0, v3
	v_lshl_add_u64 v[2:3], v[160:161], 0, v[0:1]
	v_mov_b32_e32 v0, v4
	global_load_dwordx4 v[86:89], v[42:43], off offset:256
	global_load_dwordx4 v[90:93], v[2:3], off offset:256
	v_lshl_add_u64 v[2:3], v[160:161], 0, v[0:1]
	v_mov_b32_e32 v0, v5
	v_lshl_add_u64 v[4:5], v[160:161], 0, v[0:1]
	s_waitcnt lgkmcnt(0)
; #define LAS __attribute__((address_space(3)))
; #define GAS __attribute__((address_space(1)))
; __device__ __forceinline__ unsigned pk2(float lo, float hi) { unsigned r; asm("v_cvt_pk_bf16_f32 %0, %1, %2" : "=v"(r) : "v"(lo), "v"(hi)); return r; }
; __device__ __forceinline__ void att_core(LAS unsigned char* Vst, const LAS float* listr, const LAS unsigned* listT, const bf16* P, const bf16* AKVb, bf16* ACAT, const float* aqg, size_t tok, int cnt, int lane) {
;     ...
;     sum += __shfl_xor(sum, 16); sum += __shfl_xor(sum, 32);
;     bf16x8 Pf[8];
; #pragma unroll
;     for (int G = 0; G < 8; ++G) { u32x4 t; t.x = pk2(lg[2 * G][0], lg[2 * G][1]); t.y = pk2(lg[2 * G][2], lg[2 * G][3]); t.z = pk2(lg[2 * G + 1][0], lg[2 * G + 1][1]); t.w = pk2(lg[2 * G + 1][2], lg[2 * G + 1][3]); Pf[G] = __builtin_bit_cast(bf16x8, t); }
;     f32x4 O[8];
; #pragma unroll
;     for (int nb = 0; nb < 8; ++nb) O[nb] = (f32x4){0.f, 0.f, 0.f, 0.f};
;     const LAS unsigned char* vbse = Vst + (4 * fq + (fr >> 2)) * 288 + (4 * (fr & 3)) * 2;
; #pragma unroll
;     for (int G = 0; G < 8; ++G) {
; #pragma unroll
;         for (int i = 0; i < 8; ++i) *(LAS u32x4*)(Vst + (4 * i + fq) * 288 + fr * 16) = vb[G % 3][i];
;         __builtin_amdgcn_fence(__ATOMIC_RELEASE, "wavefront"); __builtin_amdgcn_wave_barrier();
;         s16x4 tc[2][2], tn[2][2];
; #pragma unroll
;         for (int u = 0; u < 2; ++u) { tc[u][0] = ldtr((LAS unsigned char*)vbse + 32 * u); tc[u][1] = ldtr((LAS unsigned char*)vbse + 16 * 288 + 32 * u); }
;         if (G + 3 < 8) {
;             const u32x4 o0 = *(const LAS u32x4*)(lt + (G + 3) * 32), o1 = *(const LAS u32x4*)(lt + (G + 3) * 32 + 4);
; #pragma unroll
;             for (int i = 0; i < 8; ++i) vb[G % 3][i] = *(const GAS u32x4*)(kbase + 256 + (i < 4 ? o0[i & 3] : o1[i & 3]));
;         }
; #pragma unroll
;         for (int np = 0; np < 4; ++np) {
;             if (np + 1 < 4) {
; #pragma unroll
;                 for (int u = 0; u < 2; ++u) { tn[u][0] = ldtr((LAS unsigned char*)vbse + 32 * (2 * (np + 1) + u)); tn[u][1] = ldtr((LAS unsigned char*)vbse + 16 * 288 + 32 * (2 * (np + 1) + u)); } }
;             __builtin_amdgcn_sched_barrier(0);
; #pragma unroll
;             for (int u = 0; u < 2; ++u) O[2 * np + u] = mfma16(__builtin_shufflevector(tc[u][0], tc[u][1], 0, 1, 2, 3, 4, 5, 6, 7), Pf[G], O[2 * np + u]);
	v_mov_b32_e32 v0, v6
	global_load_dwordx4 v[94:97], v[2:3], off offset:256
	global_load_dwordx4 v[98:101], v[4:5], off offset:256
	v_lshl_add_u64 v[2:3], v[160:161], 0, v[0:1]
	v_mov_b32_e32 v0, v7
	v_lshl_add_u64 v[4:5], v[160:161], 0, v[0:1]
	v_mov_b32_e32 v0, v8
	global_load_dwordx4 v[102:105], v[2:3], off offset:256
	global_load_dwordx4 v[106:109], v[4:5], off offset:256
	v_lshl_add_u64 v[2:3], v[160:161], 0, v[0:1]
	v_mov_b32_e32 v0, v9
	v_lshl_add_u64 v[4:5], v[160:161], 0, v[0:1]
	global_load_dwordx4 v[110:113], v[2:3], off offset:256
	global_load_dwordx4 v[114:117], v[4:5], off offset:256
	v_sub_f32_e32 v0, v138, v165
	v_exp_f32_e32 v0, v0
	v_sub_f32_e32 v2, v139, v165
	v_exp_f32_e32 v2, v2
	v_sub_f32_e32 v4, v141, v165
	v_add_f32_e32 v3, v233, v122
	v_exp_f32_e32 v4, v4
	v_sub_f32_e32 v5, v142, v165
	v_add_f32_e32 v3, v140, v3
	v_exp_f32_e32 v5, v5
	v_sub_f32_e32 v6, v143, v165
	v_add_f32_e32 v3, v0, v3
	v_exp_f32_e32 v245, v6
	v_sub_f32_e32 v6, v148, v165
	v_add_f32_e32 v3, v2, v3
	v_exp_f32_e32 v148, v6
	v_sub_f32_e32 v6, v144, v165
	v_add_f32_e32 v3, v4, v3
	v_exp_f32_e32 v246, v6
	v_sub_f32_e32 v6, v145, v165
	v_add_f32_e32 v3, v5, v3
	v_exp_f32_e32 v247, v6
	v_sub_f32_e32 v6, v146, v165
	v_add_f32_e32 v3, v245, v3
	v_exp_f32_e32 v248, v6
	v_sub_f32_e32 v6, v147, v165
	v_add_f32_e32 v3, v148, v3
	v_exp_f32_e32 v165, v6
	v_cvt_pk_bf16_f32 v125, v128, v234
	v_cvt_pk_bf16_f32 v128, v118, v119
	v_cvt_pk_bf16_f32 v129, v120, v121
	v_cvt_pk_bf16_f32 v118, v132, v133
	v_cvt_pk_bf16_f32 v119, v135, v136
	v_cvt_pk_bf16_f32 v120, v137, v134
	v_cvt_pk_bf16_f32 v8, v233, v140
	ds_read_b64_tr_b16 v[132:133], v195
	ds_read_b64_tr_b16 v[136:137], v195 offset:32
	ds_read_b64_tr_b16 v[140:141], v195 offset:64
	ds_read_b64_tr_b16 v[144:145], v195 offset:96
	ds_read_b64_tr_b16 v[134:135], v195 offset:4608
	ds_read_b64_tr_b16 v[138:139], v195 offset:4640
	ds_read_b64_tr_b16 v[142:143], v195 offset:4672
	ds_read_b64_tr_b16 v[146:147], v195 offset:4704
	v_add_f32_e32 v3, v246, v3
	v_add_f32_e32 v3, v247, v3
	v_add_f32_e32 v3, v248, v3
	v_add_f32_e32 v3, v165, v3
	ds_bpermute_b32 v6, v185, v3
	v_cvt_pk_bf16_f32 v124, v126, v127
	v_cvt_pk_bf16_f32 v126, v235, v236
	v_cvt_pk_bf16_f32 v127, v237, v238
	v_cvt_pk_bf16_f32 v130, v239, v240
	s_waitcnt lgkmcnt(0)
	v_add_f32_e32 v122, v3, v6
	ds_bpermute_b32 v123, v194, v122
	v_cvt_pk_bf16_f32 v131, v241, v242
	v_cvt_pk_bf16_f32 v121, v243, v244
	v_cvt_pk_bf16_f32 v82, v173, v171
	v_cvt_pk_bf16_f32 v83, v169, v153
	v_cvt_pk_bf16_f32 v84, v152, v151
	v_cvt_pk_bf16_f32 v85, v150, v149
	v_cvt_pk_bf16_f32 v78, v211, v212
	v_cvt_pk_bf16_f32 v79, v210, v209
	v_cvt_pk_bf16_f32 v80, v181, v179
	v_cvt_pk_bf16_f32 v81, v177, v175
	v_cvt_pk_bf16_f32 v42, v190, v191
	v_cvt_pk_bf16_f32 v43, v192, v193
	v_cvt_pk_bf16_f32 v44, v213, v214
	v_cvt_pk_bf16_f32 v45, v215, v216
	v_cvt_pk_bf16_f32 v6, v217, v218
	v_cvt_pk_bf16_f32 v7, v219, v232
	v_cvt_pk_bf16_f32 v9, v0, v2
	v_cvt_pk_bf16_f32 v2, v4, v5
	v_cvt_pk_bf16_f32 v3, v245, v148
	v_cvt_pk_bf16_f32 v4, v246, v247
	v_cvt_pk_bf16_f32 v5, v248, v165
	v_mfma_f32_16x16x32_bf16 v[132:135], v[132:135], v[124:127], 0
	v_mfma_f32_16x16x32_bf16 v[136:139], v[136:139], v[124:127], 0
	ds_read_b64_tr_b16 v[150:151], v195 offset:4736
	ds_read_b64_tr_b16 v[148:149], v195 offset:128
	ds_read_b64_tr_b16 v[192:193], v195 offset:4768
	ds_read_b64_tr_b16 v[190:191], v195 offset:160
	v_mfma_f32_16x16x32_bf16 v[140:143], v[140:143], v[124:127], 0
	v_mfma_f32_16x16x32_bf16 v[144:147], v[144:147], v[124:127], 0
	ds_read_b64_tr_b16 v[212:213], v195 offset:4800
	ds_read_b64_tr_b16 v[210:211], v195 offset:192
	ds_read_b64_tr_b16 v[216:217], v195 offset:4832
	ds_read_b64_tr_b16 v[214:215], v195 offset:224
	s_waitcnt lgkmcnt(6)
	v_mfma_f32_16x16x32_bf16 v[148:151], v[148:151], v[124:127], 0
	s_waitcnt lgkmcnt(4)
	v_mfma_f32_16x16x32_bf16 v[190:193], v[190:193], v[124:127], 0
	s_waitcnt lgkmcnt(2)
	v_mfma_f32_16x16x32_bf16 v[210:213], v[210:213], v[124:127], 0
	s_waitcnt lgkmcnt(0)
	v_mfma_f32_16x16x32_bf16 v[124:127], v[214:217], v[124:127], 0
	s_waitcnt vmcnt(23)
	ds_write_b128 v200, v[46:49]
	s_waitcnt vmcnt(22)
	ds_write_b128 v200, v[50:53] offset:1152
	s_waitcnt vmcnt(21)
	ds_write_b128 v200, v[54:57] offset:2304
	s_waitcnt vmcnt(20)
	ds_write_b128 v200, v[58:61] offset:3456
	s_waitcnt vmcnt(19)
	ds_write_b128 v200, v[62:65] offset:4608
	s_waitcnt vmcnt(18)
	ds_write_b128 v200, v[66:69] offset:5760
	s_waitcnt vmcnt(17)
	ds_write_b128 v200, v[70:73] offset:6912
	s_waitcnt vmcnt(16)
	ds_write_b128 v200, v[74:77] offset:8064
	ds_read_b128 v[52:55], v167 offset:4608
	ds_read_b128 v[68:71], v167 offset:4624
	s_waitcnt lgkmcnt(1)
	v_mov_b32_e32 v0, v52
	v_lshl_add_u64 v[46:47], v[160:161], 0, v[0:1]
	v_mov_b32_e32 v0, v53
	v_lshl_add_u64 v[50:51], v[160:161], 0, v[0:1]
	v_mov_b32_e32 v0, v54
	v_lshl_add_u64 v[56:57], v[160:161], 0, v[0:1]
	v_mov_b32_e32 v0, v55
	v_lshl_add_u64 v[58:59], v[160:161], 0, v[0:1]
	s_waitcnt lgkmcnt(0)
	v_mov_b32_e32 v0, v68
	v_lshl_add_u64 v[62:63], v[160:161], 0, v[0:1]
	v_mov_b32_e32 v0, v69
	v_lshl_add_u64 v[66:67], v[160:161], 0, v[0:1]
	v_mov_b32_e32 v0, v70
	v_lshl_add_u64 v[72:73], v[160:161], 0, v[0:1]
	v_mov_b32_e32 v0, v71
	v_lshl_add_u64 v[74:75], v[160:161], 0, v[0:1]
	global_load_dwordx4 v[46:49], v[46:47], off offset:256
	s_nop 0
	global_load_dwordx4 v[50:53], v[50:51], off offset:256
	s_nop 0
	global_load_dwordx4 v[54:57], v[56:57], off offset:256
	s_nop 0
	global_load_dwordx4 v[58:61], v[58:59], off offset:256
	s_nop 0
	global_load_dwordx4 v[62:65], v[62:63], off offset:256
	s_nop 0
	global_load_dwordx4 v[66:69], v[66:67], off offset:256
	s_nop 0
	global_load_dwordx4 v[70:73], v[72:73], off offset:256
	s_nop 0
	global_load_dwordx4 v[74:77], v[74:75], off offset:256
	ds_read_b64_tr_b16 v[214:215], v195
	ds_read_b64_tr_b16 v[232:233], v195 offset:32
	ds_read_b64_tr_b16 v[236:237], v195 offset:64
	ds_read_b64_tr_b16 v[240:241], v195 offset:96
	ds_read_b64_tr_b16 v[216:217], v195 offset:4608
	ds_read_b64_tr_b16 v[234:235], v195 offset:4640
	ds_read_b64_tr_b16 v[238:239], v195 offset:4672
	ds_read_b64_tr_b16 v[242:243], v195 offset:4704
	s_waitcnt lgkmcnt(3)
; #define LAS __attribute__((address_space(3)))
; #define GAS __attribute__((address_space(1)))
; __device__ __forceinline__ f32x4 mfma16(bf16x8 a, bf16x8 b, f32x4 c) { return __builtin_amdgcn_mfma_f32_16x16x32_bf16(a, b, c, 0, 0, 0); }
; __device__ __forceinline__ s16x4 ldtr(LAS unsigned char* p) { return __builtin_amdgcn_ds_read_tr16_b64_v4i16((LAS s16x4*)p); }
; __device__ __forceinline__ void att_core(LAS unsigned char* Vst, const LAS float* listr, const LAS unsigned* listT, const bf16* P, const bf16* AKVb, bf16* ACAT, const float* aqg, size_t tok, int cnt, int lane) {
;     ...
;     for (int G = 0; G < 8; ++G) {
; #pragma unroll
;         for (int i = 0; i < 8; ++i) *(LAS u32x4*)(Vst + (4 * i + fq) * 288 + fr * 16) = vb[G % 3][i];
;         __builtin_amdgcn_fence(__ATOMIC_RELEASE, "wavefront"); __builtin_amdgcn_wave_barrier();
;         s16x4 tc[2][2], tn[2][2];
; #pragma unroll
;         for (int u = 0; u < 2; ++u) { tc[u][0] = ldtr((LAS unsigned char*)vbse + 32 * u); tc[u][1] = ldtr((LAS unsigned char*)vbse + 16 * 288 + 32 * u); }
;         if (G + 3 < 8) {
;             const u32x4 o0 = *(const LAS u32x4*)(lt + (G + 3) * 32), o1 = *(const LAS u32x4*)(lt + (G + 3) * 32 + 4);
; #pragma unroll
;             for (int i = 0; i < 8; ++i) vb[G % 3][i] = *(const GAS u32x4*)(kbase + 256 + (i < 4 ? o0[i & 3] : o1[i & 3]));
;         }
; #pragma unroll
;         for (int np = 0; np < 4; ++np) {
;             if (np + 1 < 4) {
; #pragma unroll
;                 for (int u = 0; u < 2; ++u) { tn[u][0] = ldtr((LAS unsigned char*)vbse + 32 * (2 * (np + 1) + u)); tn[u][1] = ldtr((LAS unsigned char*)vbse + 16 * 288 + 32 * (2 * (np + 1) + u)); } }
;             __builtin_amdgcn_sched_barrier(0);
; #pragma unroll
;             for (int u = 0; u < 2; ++u) O[2 * np + u] = mfma16(__builtin_shufflevector(tc[u][0], tc[u][1], 0, 1, 2, 3, 4, 5, 6, 7), Pf[G], O[2 * np + u]);
;             __builtin_amdgcn_sched_barrier(0);
;             if (np + 1 < 4) {
; #pragma unroll
;                 for (int u = 0; u < 2; ++u) { tc[u][0] = tn[u][0]; tc[u][1] = tn[u][1]; } }
	v_mfma_f32_16x16x32_bf16 v[132:135], v[214:217], v[128:131], v[132:135]
	s_waitcnt lgkmcnt(2)
	v_mfma_f32_16x16x32_bf16 v[136:139], v[232:235], v[128:131], v[136:139]
	ds_read_b64_tr_b16 v[216:217], v195 offset:4736
	ds_read_b64_tr_b16 v[214:215], v195 offset:128
	ds_read_b64_tr_b16 v[234:235], v195 offset:4768
	ds_read_b64_tr_b16 v[232:233], v195 offset:160
	s_waitcnt lgkmcnt(5)
	v_mfma_f32_16x16x32_bf16 v[140:143], v[236:239], v[128:131], v[140:143]
	s_waitcnt lgkmcnt(4)
	v_mfma_f32_16x16x32_bf16 v[144:147], v[240:243], v[128:131], v[144:147]
	ds_read_b64_tr_b16 v[238:239], v195 offset:4800
	ds_read_b64_tr_b16 v[236:237], v195 offset:192
	ds_read_b64_tr_b16 v[242:243], v195 offset:4832
	ds_read_b64_tr_b16 v[240:241], v195 offset:224
	s_waitcnt lgkmcnt(6)
	v_mfma_f32_16x16x32_bf16 v[148:151], v[214:217], v[128:131], v[148:151]
	s_waitcnt lgkmcnt(4)
	v_mfma_f32_16x16x32_bf16 v[190:193], v[232:235], v[128:131], v[190:193]
	s_waitcnt lgkmcnt(2)
	v_mfma_f32_16x16x32_bf16 v[210:213], v[236:239], v[128:131], v[210:213]
	s_waitcnt lgkmcnt(0)
	v_mfma_f32_16x16x32_bf16 v[124:127], v[240:243], v[128:131], v[124:127]
	s_waitcnt vmcnt(23)
	ds_write_b128 v200, v[10:13]
	s_waitcnt vmcnt(22)
	ds_write_b128 v200, v[14:17] offset:1152
	s_waitcnt vmcnt(21)
	ds_write_b128 v200, v[18:21] offset:2304
	s_waitcnt vmcnt(20)
	ds_write_b128 v200, v[22:25] offset:3456
	s_waitcnt vmcnt(19)
	ds_write_b128 v200, v[26:29] offset:4608
	s_waitcnt vmcnt(18)
	ds_write_b128 v200, v[30:33] offset:5760
	s_waitcnt vmcnt(17)
	ds_write_b128 v200, v[34:37] offset:6912
	s_waitcnt vmcnt(16)
	ds_write_b128 v200, v[38:41] offset:8064
	ds_read_b128 v[16:19], v167 offset:4736
	ds_read_b128 v[32:35], v167 offset:4752
	s_waitcnt lgkmcnt(1)
	v_mov_b32_e32 v0, v16
	v_lshl_add_u64 v[10:11], v[160:161], 0, v[0:1]
	v_mov_b32_e32 v0, v17
	v_lshl_add_u64 v[14:15], v[160:161], 0, v[0:1]
	v_mov_b32_e32 v0, v18
	v_lshl_add_u64 v[20:21], v[160:161], 0, v[0:1]
	v_mov_b32_e32 v0, v19
	v_lshl_add_u64 v[22:23], v[160:161], 0, v[0:1]
	s_waitcnt lgkmcnt(0)
	v_mov_b32_e32 v0, v32
	v_lshl_add_u64 v[26:27], v[160:161], 0, v[0:1]
	v_mov_b32_e32 v0, v33
	v_lshl_add_u64 v[30:31], v[160:161], 0, v[0:1]
	v_mov_b32_e32 v0, v34
	v_lshl_add_u64 v[36:37], v[160:161], 0, v[0:1]
	v_mov_b32_e32 v0, v35
	v_lshl_add_u64 v[38:39], v[160:161], 0, v[0:1]
	global_load_dwordx4 v[10:13], v[10:11], off offset:256
	s_nop 0
	global_load_dwordx4 v[14:17], v[14:15], off offset:256
	s_nop 0
	global_load_dwordx4 v[18:21], v[20:21], off offset:256
	s_nop 0
	global_load_dwordx4 v[22:25], v[22:23], off offset:256
	s_nop 0
	global_load_dwordx4 v[26:29], v[26:27], off offset:256
	s_nop 0
	global_load_dwordx4 v[30:33], v[30:31], off offset:256
	s_nop 0
	global_load_dwordx4 v[34:37], v[36:37], off offset:256
	s_nop 0
	global_load_dwordx4 v[38:41], v[38:39], off offset:256
	ds_read_b64_tr_b16 v[128:129], v195
	ds_read_b64_tr_b16 v[214:215], v195 offset:32
	ds_read_b64_tr_b16 v[232:233], v195 offset:64
	ds_read_b64_tr_b16 v[236:237], v195 offset:96
	ds_read_b64_tr_b16 v[130:131], v195 offset:4608
	ds_read_b64_tr_b16 v[216:217], v195 offset:4640
	ds_read_b64_tr_b16 v[234:235], v195 offset:4672
	ds_read_b64_tr_b16 v[238:239], v195 offset:4704
	s_waitcnt lgkmcnt(3)
	v_mfma_f32_16x16x32_bf16 v[128:131], v[128:131], v[118:121], v[132:135]
	s_waitcnt lgkmcnt(2)
	v_mfma_f32_16x16x32_bf16 v[132:135], v[214:217], v[118:121], v[136:139]
	s_nop 2
	ds_read_b64_tr_b16 v[138:139], v195 offset:4736
	ds_read_b64_tr_b16 v[136:137], v195 offset:128
	ds_read_b64_tr_b16 v[216:217], v195 offset:4768
	ds_read_b64_tr_b16 v[214:215], v195 offset:160
	s_waitcnt lgkmcnt(5)
	v_mfma_f32_16x16x32_bf16 v[140:143], v[232:235], v[118:121], v[140:143]
	s_waitcnt lgkmcnt(4)
	v_mfma_f32_16x16x32_bf16 v[144:147], v[236:239], v[118:121], v[144:147]
	ds_read_b64_tr_b16 v[234:235], v195 offset:4800
	ds_read_b64_tr_b16 v[232:233], v195 offset:192
	ds_read_b64_tr_b16 v[238:239], v195 offset:4832
	ds_read_b64_tr_b16 v[236:237], v195 offset:224
	s_waitcnt lgkmcnt(6)
	v_mfma_f32_16x16x32_bf16 v[136:139], v[136:139], v[118:121], v[148:151]
	s_waitcnt lgkmcnt(4)
	v_mfma_f32_16x16x32_bf16 v[148:151], v[214:217], v[118:121], v[190:193]
	s_waitcnt lgkmcnt(2)
	v_mfma_f32_16x16x32_bf16 v[190:193], v[232:235], v[118:121], v[210:213]
	s_waitcnt lgkmcnt(0)
	v_mfma_f32_16x16x32_bf16 v[118:121], v[236:239], v[118:121], v[124:127]
	s_waitcnt vmcnt(23)
	ds_write_b128 v200, v[86:89]
	s_waitcnt vmcnt(22)
	ds_write_b128 v200, v[90:93] offset:1152
	s_waitcnt vmcnt(21)
	ds_write_b128 v200, v[94:97] offset:2304
	s_waitcnt vmcnt(20)
	ds_write_b128 v200, v[98:101] offset:3456
	s_waitcnt vmcnt(19)
	ds_write_b128 v200, v[102:105] offset:4608
	s_waitcnt vmcnt(18)
	ds_write_b128 v200, v[106:109] offset:5760
	s_waitcnt vmcnt(17)
	ds_write_b128 v200, v[110:113] offset:6912
	s_waitcnt vmcnt(16)
	ds_write_b128 v200, v[114:117] offset:8064
	ds_read_b128 v[92:95], v167 offset:4864
	ds_read_b128 v[108:111], v167 offset:4880
	s_waitcnt lgkmcnt(1)
	v_mov_b32_e32 v0, v92
	v_lshl_add_u64 v[86:87], v[160:161], 0, v[0:1]
	v_mov_b32_e32 v0, v93
	v_lshl_add_u64 v[90:91], v[160:161], 0, v[0:1]
	v_mov_b32_e32 v0, v94
	v_lshl_add_u64 v[96:97], v[160:161], 0, v[0:1]
	v_mov_b32_e32 v0, v95
	v_lshl_add_u64 v[98:99], v[160:161], 0, v[0:1]
	s_waitcnt lgkmcnt(0)
; #define LAS __attribute__((address_space(3)))
; #define GAS __attribute__((address_space(1)))
; __device__ __forceinline__ f32x4 mfma16(bf16x8 a, bf16x8 b, f32x4 c) { return __builtin_amdgcn_mfma_f32_16x16x32_bf16(a, b, c, 0, 0, 0); }
; __device__ __forceinline__ s16x4 ldtr(LAS unsigned char* p) { return __builtin_amdgcn_ds_read_tr16_b64_v4i16((LAS s16x4*)p); }
; __device__ __forceinline__ void att_core(LAS unsigned char* Vst, const LAS float* listr, const LAS unsigned* listT, const bf16* P, const bf16* AKVb, bf16* ACAT, const float* aqg, size_t tok, int cnt, int lane) {
;     ...
;     for (int G = 0; G < 8; ++G) {
; #pragma unroll
;         for (int i = 0; i < 8; ++i) *(LAS u32x4*)(Vst + (4 * i + fq) * 288 + fr * 16) = vb[G % 3][i];
;         __builtin_amdgcn_fence(__ATOMIC_RELEASE, "wavefront"); __builtin_amdgcn_wave_barrier();
;         s16x4 tc[2][2], tn[2][2];
; #pragma unroll
;         for (int u = 0; u < 2; ++u) { tc[u][0] = ldtr((LAS unsigned char*)vbse + 32 * u); tc[u][1] = ldtr((LAS unsigned char*)vbse + 16 * 288 + 32 * u); }
;         if (G + 3 < 8) {
;             const u32x4 o0 = *(const LAS u32x4*)(lt + (G + 3) * 32), o1 = *(const LAS u32x4*)(lt + (G + 3) * 32 + 4);
; #pragma unroll
;             for (int i = 0; i < 8; ++i) vb[G % 3][i] = *(const GAS u32x4*)(kbase + 256 + (i < 4 ? o0[i & 3] : o1[i & 3]));
;         }
; #pragma unroll
;         for (int np = 0; np < 4; ++np) {
;             if (np + 1 < 4) {
; #pragma unroll
;                 for (int u = 0; u < 2; ++u) { tn[u][0] = ldtr((LAS unsigned char*)vbse + 32 * (2 * (np + 1) + u)); tn[u][1] = ldtr((LAS unsigned char*)vbse + 16 * 288 + 32 * (2 * (np + 1) + u)); } }
;             __builtin_amdgcn_sched_barrier(0);
; #pragma unroll
;             for (int u = 0; u < 2; ++u) O[2 * np + u] = mfma16(__builtin_shufflevector(tc[u][0], tc[u][1], 0, 1, 2, 3, 4, 5, 6, 7), Pf[G], O[2 * np + u]);
;             __builtin_amdgcn_sched_barrier(0);
;             if (np + 1 < 4) {
; #pragma unroll
;                 for (int u = 0; u < 2; ++u) { tc[u][0] = tn[u][0]; tc[u][1] = tn[u][1]; } }
	v_mov_b32_e32 v0, v108
	v_lshl_add_u64 v[102:103], v[160:161], 0, v[0:1]
	v_mov_b32_e32 v0, v109
	v_lshl_add_u64 v[106:107], v[160:161], 0, v[0:1]
	v_mov_b32_e32 v0, v110
	v_lshl_add_u64 v[112:113], v[160:161], 0, v[0:1]
	v_mov_b32_e32 v0, v111
	v_lshl_add_u64 v[114:115], v[160:161], 0, v[0:1]
	global_load_dwordx4 v[86:89], v[86:87], off offset:256
	s_nop 0
	global_load_dwordx4 v[90:93], v[90:91], off offset:256
	s_nop 0
	global_load_dwordx4 v[94:97], v[96:97], off offset:256
	s_nop 0
	global_load_dwordx4 v[98:101], v[98:99], off offset:256
	s_nop 0
	global_load_dwordx4 v[102:105], v[102:103], off offset:256
	s_nop 0
	global_load_dwordx4 v[106:109], v[106:107], off offset:256
	s_nop 0
	global_load_dwordx4 v[110:113], v[112:113], off offset:256
	s_nop 0
	global_load_dwordx4 v[114:117], v[114:115], off offset:256
	ds_read_b64_tr_b16 v[124:125], v195
	ds_read_b64_tr_b16 v[210:211], v195 offset:32
	ds_read_b64_tr_b16 v[214:215], v195 offset:64
	ds_read_b64_tr_b16 v[232:233], v195 offset:96
	ds_read_b64_tr_b16 v[126:127], v195 offset:4608
	ds_read_b64_tr_b16 v[212:213], v195 offset:4640
	ds_read_b64_tr_b16 v[216:217], v195 offset:4672
	ds_read_b64_tr_b16 v[234:235], v195 offset:4704
	s_waitcnt lgkmcnt(3)
	v_mfma_f32_16x16x32_bf16 v[124:127], v[124:127], v[82:85], v[128:131]
	s_waitcnt lgkmcnt(2)
	v_mfma_f32_16x16x32_bf16 v[128:131], v[210:213], v[82:85], v[132:135]
	s_nop 2
	ds_read_b64_tr_b16 v[134:135], v195 offset:4736
	ds_read_b64_tr_b16 v[132:133], v195 offset:128
	ds_read_b64_tr_b16 v[212:213], v195 offset:4768
	ds_read_b64_tr_b16 v[210:211], v195 offset:160
	s_waitcnt lgkmcnt(5)
	v_mfma_f32_16x16x32_bf16 v[140:143], v[214:217], v[82:85], v[140:143]
	s_waitcnt lgkmcnt(4)
	v_mfma_f32_16x16x32_bf16 v[144:147], v[232:235], v[82:85], v[144:147]
	ds_read_b64_tr_b16 v[216:217], v195 offset:4800
	ds_read_b64_tr_b16 v[214:215], v195 offset:192
	ds_read_b64_tr_b16 v[234:235], v195 offset:4832
	ds_read_b64_tr_b16 v[232:233], v195 offset:224
	s_waitcnt lgkmcnt(6)
	v_mfma_f32_16x16x32_bf16 v[132:135], v[132:135], v[82:85], v[136:139]
	s_waitcnt lgkmcnt(4)
	v_mfma_f32_16x16x32_bf16 v[136:139], v[210:213], v[82:85], v[148:151]
	s_waitcnt lgkmcnt(2)
	v_mfma_f32_16x16x32_bf16 v[148:151], v[214:217], v[82:85], v[190:193]
	s_waitcnt lgkmcnt(0)
	v_mfma_f32_16x16x32_bf16 v[82:85], v[232:235], v[82:85], v[118:121]
	s_waitcnt vmcnt(23)
	ds_write_b128 v200, v[46:49]
	s_waitcnt vmcnt(22)
	ds_write_b128 v200, v[50:53] offset:1152
	s_waitcnt vmcnt(21)
	ds_write_b128 v200, v[54:57] offset:2304
	s_waitcnt vmcnt(20)
	ds_write_b128 v200, v[58:61] offset:3456
	s_waitcnt vmcnt(19)
	ds_write_b128 v200, v[62:65] offset:4608
	s_waitcnt vmcnt(18)
	ds_write_b128 v200, v[66:69] offset:5760
	s_waitcnt vmcnt(17)
	ds_write_b128 v200, v[70:73] offset:6912
	s_waitcnt vmcnt(16)
	ds_write_b128 v200, v[74:77] offset:8064
	ds_read_b128 v[52:55], v167 offset:4992
	ds_read_b128 v[62:65], v167 offset:5008
	s_waitcnt lgkmcnt(1)
	v_mov_b32_e32 v0, v52
	v_lshl_add_u64 v[46:47], v[160:161], 0, v[0:1]
	v_mov_b32_e32 v0, v53
	v_lshl_add_u64 v[50:51], v[160:161], 0, v[0:1]
	v_mov_b32_e32 v0, v54
	v_lshl_add_u64 v[56:57], v[160:161], 0, v[0:1]
	v_mov_b32_e32 v0, v55
	v_lshl_add_u64 v[58:59], v[160:161], 0, v[0:1]
	s_waitcnt lgkmcnt(0)
	v_mov_b32_e32 v0, v62
	v_lshl_add_u64 v[66:67], v[160:161], 0, v[0:1]
	v_mov_b32_e32 v0, v63
	v_lshl_add_u64 v[62:63], v[160:161], 0, v[0:1]
	v_mov_b32_e32 v0, v64
	global_load_dwordx4 v[46:49], v[46:47], off offset:256
	s_nop 0
	global_load_dwordx4 v[50:53], v[50:51], off offset:256
	s_nop 0
	global_load_dwordx4 v[54:57], v[56:57], off offset:256
	s_nop 0
	global_load_dwordx4 v[58:61], v[58:59], off offset:256
	s_nop 0
	global_load_dwordx4 v[66:69], v[66:67], off offset:256
	s_nop 0
	global_load_dwordx4 v[70:73], v[62:63], off offset:256
	v_lshl_add_u64 v[62:63], v[160:161], 0, v[0:1]
	v_mov_b32_e32 v0, v65
	v_lshl_add_u64 v[74:75], v[160:161], 0, v[0:1]
	global_load_dwordx4 v[62:65], v[62:63], off offset:256
	s_nop 0
	global_load_dwordx4 v[74:77], v[74:75], off offset:256
	ds_read_b64_tr_b16 v[118:119], v195
	ds_read_b64_tr_b16 v[190:191], v195 offset:32
	ds_read_b64_tr_b16 v[210:211], v195 offset:64
	ds_read_b64_tr_b16 v[214:215], v195 offset:96
	ds_read_b64_tr_b16 v[120:121], v195 offset:4608
	ds_read_b64_tr_b16 v[192:193], v195 offset:4640
	ds_read_b64_tr_b16 v[212:213], v195 offset:4672
	ds_read_b64_tr_b16 v[216:217], v195 offset:4704
	s_waitcnt lgkmcnt(3)
	v_mfma_f32_16x16x32_bf16 v[118:121], v[118:121], v[78:81], v[124:127]
	s_waitcnt lgkmcnt(2)
	v_mfma_f32_16x16x32_bf16 v[124:127], v[190:193], v[78:81], v[128:131]
	s_nop 2
	ds_read_b64_tr_b16 v[130:131], v195 offset:4736
	ds_read_b64_tr_b16 v[128:129], v195 offset:128
	ds_read_b64_tr_b16 v[192:193], v195 offset:4768
	ds_read_b64_tr_b16 v[190:191], v195 offset:160
	s_waitcnt lgkmcnt(5)
	v_mfma_f32_16x16x32_bf16 v[140:143], v[210:213], v[78:81], v[140:143]
	s_waitcnt lgkmcnt(4)
	v_mfma_f32_16x16x32_bf16 v[144:147], v[214:217], v[78:81], v[144:147]
	ds_read_b64_tr_b16 v[212:213], v195 offset:4800
	ds_read_b64_tr_b16 v[210:211], v195 offset:192
	ds_read_b64_tr_b16 v[216:217], v195 offset:4832
	ds_read_b64_tr_b16 v[214:215], v195 offset:224
	s_waitcnt lgkmcnt(6)
	v_mfma_f32_16x16x32_bf16 v[128:131], v[128:131], v[78:81], v[132:135]
	s_waitcnt lgkmcnt(4)
	v_mfma_f32_16x16x32_bf16 v[132:135], v[190:193], v[78:81], v[136:139]
	s_waitcnt lgkmcnt(2)
	v_mfma_f32_16x16x32_bf16 v[136:139], v[210:213], v[78:81], v[148:151]
	s_waitcnt lgkmcnt(0)
	v_mfma_f32_16x16x32_bf16 v[78:81], v[214:217], v[78:81], v[82:85]
	s_waitcnt vmcnt(23)
	ds_write_b128 v200, v[10:13]
	s_waitcnt vmcnt(22)
	ds_write_b128 v200, v[14:17] offset:1152
	s_waitcnt vmcnt(21)
; #define LAS __attribute__((address_space(3)))
; #define GAS __attribute__((address_space(1)))
; __device__ __forceinline__ f32x4 mfma16(bf16x8 a, bf16x8 b, f32x4 c) { return __builtin_amdgcn_mfma_f32_16x16x32_bf16(a, b, c, 0, 0, 0); }
; __device__ __forceinline__ s16x4 ldtr(LAS unsigned char* p) { return __builtin_amdgcn_ds_read_tr16_b64_v4i16((LAS s16x4*)p); }
; __device__ __forceinline__ void att_core(LAS unsigned char* Vst, const LAS float* listr, const LAS unsigned* listT, const bf16* P, const bf16* AKVb, bf16* ACAT, const float* aqg, size_t tok, int cnt, int lane) {
;     ...
;     for (int G = 0; G < 8; ++G) {
; #pragma unroll
;         for (int i = 0; i < 8; ++i) *(LAS u32x4*)(Vst + (4 * i + fq) * 288 + fr * 16) = vb[G % 3][i];
;         __builtin_amdgcn_fence(__ATOMIC_RELEASE, "wavefront"); __builtin_amdgcn_wave_barrier();
;         s16x4 tc[2][2], tn[2][2];
; #pragma unroll
;         for (int u = 0; u < 2; ++u) { tc[u][0] = ldtr((LAS unsigned char*)vbse + 32 * u); tc[u][1] = ldtr((LAS unsigned char*)vbse + 16 * 288 + 32 * u); }
;         if (G + 3 < 8) {
;             const u32x4 o0 = *(const LAS u32x4*)(lt + (G + 3) * 32), o1 = *(const LAS u32x4*)(lt + (G + 3) * 32 + 4);
; #pragma unroll
;             for (int i = 0; i < 8; ++i) vb[G % 3][i] = *(const GAS u32x4*)(kbase + 256 + (i < 4 ? o0[i & 3] : o1[i & 3]));
;         }
; #pragma unroll
;         for (int np = 0; np < 4; ++np) {
;             if (np + 1 < 4) {
; #pragma unroll
;                 for (int u = 0; u < 2; ++u) { tn[u][0] = ldtr((LAS unsigned char*)vbse + 32 * (2 * (np + 1) + u)); tn[u][1] = ldtr((LAS unsigned char*)vbse + 16 * 288 + 32 * (2 * (np + 1) + u)); } }
;             __builtin_amdgcn_sched_barrier(0);
; #pragma unroll
;             for (int u = 0; u < 2; ++u) O[2 * np + u] = mfma16(__builtin_shufflevector(tc[u][0], tc[u][1], 0, 1, 2, 3, 4, 5, 6, 7), Pf[G], O[2 * np + u]);
;             __builtin_amdgcn_sched_barrier(0);
;             if (np + 1 < 4) {
; #pragma unroll
;                 for (int u = 0; u < 2; ++u) { tc[u][0] = tn[u][0]; tc[u][1] = tn[u][1]; } }
;         }
	ds_write_b128 v200, v[18:21] offset:2304
	s_waitcnt vmcnt(20)
	ds_write_b128 v200, v[22:25] offset:3456
	s_waitcnt vmcnt(19)
	ds_write_b128 v200, v[26:29] offset:4608
	s_waitcnt vmcnt(18)
	ds_write_b128 v200, v[30:33] offset:5760
	s_waitcnt vmcnt(17)
	ds_write_b128 v200, v[34:37] offset:6912
	s_waitcnt vmcnt(16)
	ds_write_b128 v200, v[38:41] offset:8064
	ds_read_b64_tr_b16 v[10:11], v195
	ds_read_b64_tr_b16 v[14:15], v195 offset:32
	ds_read_b64_tr_b16 v[18:19], v195 offset:64
	ds_read_b64_tr_b16 v[22:23], v195 offset:96
	ds_read_b64_tr_b16 v[12:13], v195 offset:4608
	ds_read_b64_tr_b16 v[16:17], v195 offset:4640
	ds_read_b64_tr_b16 v[20:21], v195 offset:4672
	ds_read_b64_tr_b16 v[24:25], v195 offset:4704
	s_waitcnt lgkmcnt(3)
	v_mfma_f32_16x16x32_bf16 v[10:13], v[10:13], v[42:45], v[118:121]
	s_waitcnt lgkmcnt(2)
	v_mfma_f32_16x16x32_bf16 v[14:17], v[14:17], v[42:45], v[124:127]
	ds_read_b64_tr_b16 v[28:29], v195 offset:4736
	ds_read_b64_tr_b16 v[26:27], v195 offset:128
	ds_read_b64_tr_b16 v[32:33], v195 offset:4768
	ds_read_b64_tr_b16 v[30:31], v195 offset:160
	s_waitcnt lgkmcnt(5)
	v_mfma_f32_16x16x32_bf16 v[18:21], v[18:21], v[42:45], v[140:143]
	s_waitcnt lgkmcnt(4)
	v_mfma_f32_16x16x32_bf16 v[22:25], v[22:25], v[42:45], v[144:147]
	ds_read_b64_tr_b16 v[36:37], v195 offset:4800
	ds_read_b64_tr_b16 v[34:35], v195 offset:192
	ds_read_b64_tr_b16 v[40:41], v195 offset:4832
	ds_read_b64_tr_b16 v[38:39], v195 offset:224
	s_waitcnt lgkmcnt(6)
	v_mfma_f32_16x16x32_bf16 v[26:29], v[26:29], v[42:45], v[128:131]
	s_waitcnt lgkmcnt(4)
	v_mfma_f32_16x16x32_bf16 v[30:33], v[30:33], v[42:45], v[132:135]
	s_waitcnt lgkmcnt(2)
	v_mfma_f32_16x16x32_bf16 v[34:37], v[34:37], v[42:45], v[136:139]
	s_waitcnt lgkmcnt(0)
	v_mfma_f32_16x16x32_bf16 v[38:41], v[38:41], v[42:45], v[78:81]
	s_waitcnt vmcnt(15)
	ds_write_b128 v200, v[86:89]
	s_waitcnt vmcnt(14)
	ds_write_b128 v200, v[90:93] offset:1152
	s_waitcnt vmcnt(13)
	ds_write_b128 v200, v[94:97] offset:2304
	s_waitcnt vmcnt(12)
	ds_write_b128 v200, v[98:101] offset:3456
	s_waitcnt vmcnt(11)
	ds_write_b128 v200, v[102:105] offset:4608
	s_waitcnt vmcnt(10)
	ds_write_b128 v200, v[106:109] offset:5760
	s_waitcnt vmcnt(9)
	ds_write_b128 v200, v[110:113] offset:6912
	s_waitcnt vmcnt(8)
	ds_write_b128 v200, v[114:117] offset:8064
	ds_read_b64_tr_b16 v[42:43], v195
	ds_read_b64_tr_b16 v[78:79], v195 offset:32
	ds_read_b64_tr_b16 v[82:83], v195 offset:64
	ds_read_b64_tr_b16 v[86:87], v195 offset:96
	ds_read_b64_tr_b16 v[44:45], v195 offset:4608
	ds_read_b64_tr_b16 v[80:81], v195 offset:4640
	ds_read_b64_tr_b16 v[84:85], v195 offset:4672
	ds_read_b64_tr_b16 v[88:89], v195 offset:4704
	s_waitcnt lgkmcnt(3)
	v_mfma_f32_16x16x32_bf16 v[10:13], v[42:45], v[6:9], v[10:13]
	s_waitcnt lgkmcnt(2)
	v_mfma_f32_16x16x32_bf16 v[14:17], v[78:81], v[6:9], v[14:17]
	ds_read_b64_tr_b16 v[44:45], v195 offset:4736
	ds_read_b64_tr_b16 v[42:43], v195 offset:128
	ds_read_b64_tr_b16 v[80:81], v195 offset:4768
	ds_read_b64_tr_b16 v[78:79], v195 offset:160
	s_waitcnt lgkmcnt(5)
	v_mfma_f32_16x16x32_bf16 v[18:21], v[82:85], v[6:9], v[18:21]
	s_waitcnt lgkmcnt(4)
	v_mfma_f32_16x16x32_bf16 v[22:25], v[86:89], v[6:9], v[22:25]
	ds_read_b64_tr_b16 v[84:85], v195 offset:4800
	ds_read_b64_tr_b16 v[82:83], v195 offset:192
	ds_read_b64_tr_b16 v[88:89], v195 offset:4832
	ds_read_b64_tr_b16 v[86:87], v195 offset:224
	s_waitcnt lgkmcnt(6)
	v_mfma_f32_16x16x32_bf16 v[26:29], v[42:45], v[6:9], v[26:29]
	s_waitcnt lgkmcnt(4)
	v_mfma_f32_16x16x32_bf16 v[30:33], v[78:81], v[6:9], v[30:33]
	s_waitcnt lgkmcnt(2)
	v_mfma_f32_16x16x32_bf16 v[34:37], v[82:85], v[6:9], v[34:37]
	s_waitcnt lgkmcnt(0)
	v_mfma_f32_16x16x32_bf16 v[6:9], v[86:89], v[6:9], v[38:41]
	s_waitcnt vmcnt(7)
	ds_write_b128 v200, v[46:49]
	s_waitcnt vmcnt(6)
	ds_write_b128 v200, v[50:53] offset:1152
	s_waitcnt vmcnt(5)
	ds_write_b128 v200, v[54:57] offset:2304
	s_waitcnt vmcnt(4)
	ds_write_b128 v200, v[58:61] offset:3456
	s_waitcnt vmcnt(3)
	ds_write_b128 v200, v[66:69] offset:4608
	s_waitcnt vmcnt(2)
	ds_write_b128 v200, v[70:73] offset:5760
	s_waitcnt vmcnt(1)
	ds_write_b128 v200, v[62:65] offset:6912
	s_waitcnt vmcnt(0)
	ds_write_b128 v200, v[74:77] offset:8064
	ds_read_b64_tr_b16 v[38:39], v195
	ds_read_b64_tr_b16 v[42:43], v195 offset:32
	ds_read_b64_tr_b16 v[46:47], v195 offset:64
	ds_read_b64_tr_b16 v[50:51], v195 offset:96
	ds_read_b64_tr_b16 v[40:41], v195 offset:4608
	ds_read_b64_tr_b16 v[44:45], v195 offset:4640
	ds_read_b64_tr_b16 v[48:49], v195 offset:4672
	ds_read_b64_tr_b16 v[52:53], v195 offset:4704
	s_waitcnt lgkmcnt(3)
	v_mfma_f32_16x16x32_bf16 v[10:13], v[38:41], v[2:5], v[10:13]
	s_waitcnt lgkmcnt(2)
	v_mfma_f32_16x16x32_bf16 v[14:17], v[42:45], v[2:5], v[14:17]
	ds_read_b64_tr_b16 v[40:41], v195 offset:4736
	ds_read_b64_tr_b16 v[38:39], v195 offset:128
	ds_read_b64_tr_b16 v[44:45], v195 offset:4768
	ds_read_b64_tr_b16 v[42:43], v195 offset:160
	s_waitcnt lgkmcnt(5)
	v_mfma_f32_16x16x32_bf16 v[18:21], v[46:49], v[2:5], v[18:21]
	s_waitcnt lgkmcnt(4)
	v_mfma_f32_16x16x32_bf16 v[22:25], v[50:53], v[2:5], v[22:25]
	ds_read_b64_tr_b16 v[48:49], v195 offset:4800
	ds_read_b64_tr_b16 v[46:47], v195 offset:192
	ds_read_b64_tr_b16 v[52:53], v195 offset:4832
	ds_read_b64_tr_b16 v[50:51], v195 offset:224
	s_waitcnt lgkmcnt(6)
	v_mfma_f32_16x16x32_bf16 v[26:29], v[38:41], v[2:5], v[26:29]
	s_waitcnt lgkmcnt(4)
	v_mfma_f32_16x16x32_bf16 v[30:33], v[42:45], v[2:5], v[30:33]
	s_waitcnt lgkmcnt(2)
	v_mfma_f32_16x16x32_bf16 v[34:37], v[46:49], v[2:5], v[34:37]
	s_waitcnt lgkmcnt(0)
; #define LAS __attribute__((address_space(3)))
; #define GAS __attribute__((address_space(1)))
; __device__ __forceinline__ float bflo(unsigned w) { return __uint_as_float(w << 16); }
; __device__ __forceinline__ float bfhi(unsigned w) { return __uint_as_float(w & 0xffff0000u); }
; __device__ __forceinline__ unsigned pk2(float lo, float hi) { unsigned r; asm("v_cvt_pk_bf16_f32 %0, %1, %2" : "=v"(r) : "v"(lo), "v"(hi)); return r; }
; __device__ __forceinline__ void att_core(LAS unsigned char* Vst, const LAS float* listr, const LAS unsigned* listT, const bf16* P, const bf16* AKVb, bf16* ACAT, const float* aqg, size_t tok, int cnt, int lane) {
;     ...
;     const float rs = __builtin_amdgcn_rcpf(sum);
;     LAS float* Ot = (LAS float*)Vst;
; #pragma unroll
;     for (int nb = 0; nb < 8; ++nb) *(LAS f32x4*)(Ot + fr * 132 + 16 * nb + 4 * fq) = O[nb] * rs;
;     __builtin_amdgcn_fence(__ATOMIC_RELEASE, "wavefront"); __builtin_amdgcn_wave_barrier();
;     {
;         u32x2 sg[8];
; #pragma unroll
;         for (int j = 0; j < 8; ++j) sg[j] = *(const GAS u32x2*)(P + tok * NP + C_AG + 256 * j + 4 * lane);
; #pragma unroll
;         for (int j = 0; j < 8; ++j) {
;             const int c = 256 * j + 4 * lane;
;             const f32x4 o4 = *(const LAS f32x4*)(Ot + (c >> 7) * 132 + (c & 127));
;             u32x2 o; o.x = pk2(o4.x * bflo(sg[j].x), o4.y * bfhi(sg[j].x)); o.y = pk2(o4.z * bflo(sg[j].y), o4.w * bfhi(sg[j].y));
;             *(GAS u32x2*)(ACAT + ((size_t)NTOK + tok) * DM + c) = o;
;         }
; __device__ __forceinline__ void att_unit(LAS unsigned char* lds, const bf16* P, const bf16* AKV, const bf16* IKC, bf16* ACAT, const float* aqg, const float* ssq_ak, const float* ssq_ik, int b, int qg, int tid) {
;     ...
;     for (int q = 0; q < 2 * REP_ATTB; ++q)
;         att_core(Vst, (const LAS float*)list0 + 512 * (q & 1) + 256, (const LAS unsigned*)list0 + 1024 + 256 * (q & 1), P, AKVb, ACAT, aqg, tok0 + (q & 1), cnt, lane);
	v_mfma_f32_16x16x32_bf16 v[2:5], v[50:53], v[2:5], v[6:9]
	v_add_f32_e32 v0, v122, v123
	v_rcp_f32_e32 v0, v0
	v_mov_b32_e32 v167, v1
	s_mov_b64 s[42:43], 0x5200
	s_movk_i32 s33, 0x5000
	v_pk_mul_f32 v[8:9], v[0:1], v[12:13] op_sel_hi:[0,1]
	v_pk_mul_f32 v[6:7], v[0:1], v[10:11] op_sel_hi:[0,1]
	ds_write_b128 v196, v[6:9]
	v_pk_mul_f32 v[8:9], v[0:1], v[16:17] op_sel_hi:[0,1]
	v_pk_mul_f32 v[6:7], v[0:1], v[14:15] op_sel_hi:[0,1]
	ds_write_b128 v196, v[6:9] offset:64
	v_pk_mul_f32 v[8:9], v[0:1], v[20:21] op_sel_hi:[0,1]
	v_pk_mul_f32 v[6:7], v[0:1], v[18:19] op_sel_hi:[0,1]
	ds_write_b128 v196, v[6:9] offset:128
	v_pk_mul_f32 v[8:9], v[0:1], v[24:25] op_sel_hi:[0,1]
	v_pk_mul_f32 v[6:7], v[0:1], v[22:23] op_sel_hi:[0,1]
	v_pk_mul_f32 v[4:5], v[0:1], v[4:5] op_sel_hi:[0,1]
	v_pk_mul_f32 v[2:3], v[0:1], v[2:3] op_sel_hi:[0,1]
	ds_write_b128 v196, v[6:9] offset:192
	v_pk_mul_f32 v[8:9], v[0:1], v[28:29] op_sel_hi:[0,1]
	v_pk_mul_f32 v[6:7], v[0:1], v[26:27] op_sel_hi:[0,1]
	ds_write_b128 v196, v[2:5] offset:448
	v_lshl_add_u64 v[2:3], v[182:183], 0, v[166:167]
	ds_write_b128 v196, v[6:9] offset:256
	v_pk_mul_f32 v[8:9], v[0:1], v[32:33] op_sel_hi:[0,1]
	v_pk_mul_f32 v[6:7], v[0:1], v[30:31] op_sel_hi:[0,1]
	v_lshl_add_u64 v[4:5], v[2:3], 0, s[42:43]
	v_add_co_u32_e32 v2, vcc, s33, v2
	ds_write_b128 v196, v[6:9] offset:320
	v_pk_mul_f32 v[8:9], v[0:1], v[36:37] op_sel_hi:[0,1]
	v_pk_mul_f32 v[6:7], v[0:1], v[34:35] op_sel_hi:[0,1]
	v_addc_co_u32_e32 v3, vcc, 0, v3, vcc
	ds_write_b128 v196, v[6:9] offset:384
	global_load_dwordx2 v[18:19], v[2:3], off offset:512
	global_load_dwordx2 v[20:21], v[4:5], off offset:512
	global_load_dwordx2 v[22:23], v[4:5], off offset:1024
	global_load_dwordx2 v[12:13], v[4:5], off offset:1536
	global_load_dwordx2 v[10:11], v[4:5], off offset:2048
	global_load_dwordx2 v[8:9], v[4:5], off offset:2560
	global_load_dwordx2 v[6:7], v[4:5], off offset:3072
	global_load_dwordx2 v[2:3], v[4:5], off offset:3584
	ds_read_b128 v[14:17], v201
	v_lshlrev_b64 v[4:5], 12, v[156:157]
	v_lshl_add_u64 v[4:5], s[46:47], 0, v[4:5]
	s_mov_b64 s[42:43], 0x2000000
	v_lshl_add_u64 v[4:5], v[4:5], 0, s[42:43]
	v_mov_b32_e32 v169, v1
	v_mov_b32_e32 v171, v1
	v_mov_b32_e32 v173, v1
	v_mov_b32_e32 v175, v1
	v_mov_b32_e32 v177, v1
	v_mov_b32_e32 v179, v1
	v_mov_b32_e32 v181, v1
	s_mov_b64 s[42:43], 0
	s_and_b64 vcc, exec, s[40:41]
	s_mov_b32 s33, 1
	s_waitcnt vmcnt(7)
	v_lshlrev_b32_e32 v0, 16, v18
	s_waitcnt lgkmcnt(0)
	v_mul_f32_e32 v0, v14, v0
	v_and_b32_e32 v14, 0xffff0000, v18
	v_mul_f32_e32 v14, v15, v14
	v_and_b32_e32 v15, 0xffff0000, v19
	v_cvt_pk_bf16_f32 v14, v0, v14
	v_lshlrev_b32_e32 v0, 16, v19
	v_mul_f32_e32 v15, v17, v15
	v_mul_f32_e32 v0, v16, v0
	v_cvt_pk_bf16_f32 v15, v0, v15
	v_lshl_add_u64 v[16:17], v[4:5], 0, v[166:167]
	global_store_dwordx2 v[16:17], v[14:15], off
	ds_read_b128 v[14:17], v202
	s_waitcnt vmcnt(7)
	v_lshlrev_b32_e32 v0, 16, v20
	s_waitcnt lgkmcnt(0)
	v_mul_f32_e32 v0, v14, v0
	v_and_b32_e32 v14, 0xffff0000, v20
	v_mul_f32_e32 v14, v15, v14
	v_and_b32_e32 v15, 0xffff0000, v21
	v_cvt_pk_bf16_f32 v14, v0, v14
	v_lshlrev_b32_e32 v0, 16, v21
	v_mul_f32_e32 v15, v17, v15
	v_mul_f32_e32 v0, v16, v0
	v_cvt_pk_bf16_f32 v15, v0, v15
	v_lshl_add_u64 v[16:17], v[4:5], 0, v[168:169]
	global_store_dwordx2 v[16:17], v[14:15], off
	ds_read_b128 v[14:17], v203
	s_waitcnt vmcnt(7)
	v_lshlrev_b32_e32 v0, 16, v22
	s_waitcnt lgkmcnt(0)
	v_mul_f32_e32 v0, v14, v0
	v_and_b32_e32 v14, 0xffff0000, v22
	v_mul_f32_e32 v14, v15, v14
	v_and_b32_e32 v15, 0xffff0000, v23
	v_cvt_pk_bf16_f32 v14, v0, v14
	v_lshlrev_b32_e32 v0, 16, v23
	v_mul_f32_e32 v15, v17, v15
	v_mul_f32_e32 v0, v16, v0
	v_cvt_pk_bf16_f32 v15, v0, v15
	v_lshl_add_u64 v[16:17], v[4:5], 0, v[170:171]
	global_store_dwordx2 v[16:17], v[14:15], off
	ds_read_b128 v[14:17], v204
	s_waitcnt vmcnt(7)
	v_lshlrev_b32_e32 v0, 16, v12
	v_and_b32_e32 v12, 0xffff0000, v12
	s_waitcnt lgkmcnt(0)
	v_mul_f32_e32 v0, v14, v0
	v_mul_f32_e32 v12, v15, v12
	v_cvt_pk_bf16_f32 v12, v0, v12
	v_lshlrev_b32_e32 v0, 16, v13
	v_and_b32_e32 v13, 0xffff0000, v13
	v_mul_f32_e32 v13, v17, v13
	v_mul_f32_e32 v0, v16, v0
	v_cvt_pk_bf16_f32 v13, v0, v13
	v_lshl_add_u64 v[14:15], v[4:5], 0, v[172:173]
	global_store_dwordx2 v[14:15], v[12:13], off
	ds_read_b128 v[12:15], v205
	s_waitcnt vmcnt(7)
	v_lshlrev_b32_e32 v0, 16, v10
	v_and_b32_e32 v10, 0xffff0000, v10
	s_waitcnt lgkmcnt(0)
	v_mul_f32_e32 v0, v12, v0
	v_mul_f32_e32 v10, v13, v10
	v_cvt_pk_bf16_f32 v10, v0, v10
	v_lshlrev_b32_e32 v0, 16, v11
	v_and_b32_e32 v11, 0xffff0000, v11
	v_mul_f32_e32 v11, v15, v11
	v_mul_f32_e32 v0, v14, v0
	v_cvt_pk_bf16_f32 v11, v0, v11
	v_lshl_add_u64 v[12:13], v[4:5], 0, v[174:175]
	global_store_dwordx2 v[12:13], v[10:11], off
	ds_read_b128 v[10:13], v206
	s_waitcnt vmcnt(7)
	v_lshlrev_b32_e32 v0, 16, v8
	v_and_b32_e32 v8, 0xffff0000, v8
	s_waitcnt lgkmcnt(0)
	v_mul_f32_e32 v0, v10, v0
	v_mul_f32_e32 v8, v11, v8
	v_cvt_pk_bf16_f32 v8, v0, v8
	v_lshlrev_b32_e32 v0, 16, v9
	v_and_b32_e32 v9, 0xffff0000, v9
	v_mul_f32_e32 v9, v13, v9
	v_mul_f32_e32 v0, v12, v0
	v_cvt_pk_bf16_f32 v9, v0, v9
	v_lshl_add_u64 v[10:11], v[4:5], 0, v[176:177]
	global_store_dwordx2 v[10:11], v[8:9], off
	ds_read_b128 v[8:11], v207
	s_waitcnt vmcnt(7)
	v_lshlrev_b32_e32 v0, 16, v6
	v_and_b32_e32 v6, 0xffff0000, v6
	s_waitcnt lgkmcnt(0)
	v_mul_f32_e32 v0, v8, v0
	v_mul_f32_e32 v6, v9, v6
	v_cvt_pk_bf16_f32 v6, v0, v6
	v_lshlrev_b32_e32 v0, 16, v7
	v_and_b32_e32 v7, 0xffff0000, v7
	v_mul_f32_e32 v7, v11, v7
	v_mul_f32_e32 v0, v10, v0
	v_cvt_pk_bf16_f32 v7, v0, v7
	v_lshl_add_u64 v[8:9], v[4:5], 0, v[178:179]
	global_store_dwordx2 v[8:9], v[6:7], off
	ds_read_b128 v[6:9], v208
	s_waitcnt vmcnt(7)
	v_lshlrev_b32_e32 v0, 16, v2
	v_and_b32_e32 v2, 0xffff0000, v2
	v_lshl_add_u64 v[4:5], v[4:5], 0, v[180:181]
	s_waitcnt lgkmcnt(0)
	v_mul_f32_e32 v0, v6, v0
	v_mul_f32_e32 v2, v7, v2
	v_cvt_pk_bf16_f32 v2, v0, v2
	v_lshlrev_b32_e32 v0, 16, v3
	v_and_b32_e32 v3, 0xffff0000, v3
	v_mul_f32_e32 v3, v9, v3
	v_mul_f32_e32 v0, v8, v0
	v_cvt_pk_bf16_f32 v3, v0, v3
	global_store_dwordx2 v[4:5], v[2:3], off
	s_cbranch_vccz .LBB0_1010
	s_setprio 0
	s_branch .LBB0_580
